# SwiGLU and sigmoid-gate epilogues: -log2e and -ln2 folded into gate/up/w_ple_gate weights at conversion, one multiply less per element
# baseline (speedup 1.0000x reference)
.LBB0_27:
	s_lshl_b32 s17, s8, 1
	s_lshl_b32 s18, s9, 1
	v_or_b32_e32 v83, s18, v2
	s_add_i32 s19, s17, 4
	s_add_i32 s20, s18, 4
	s_add_i32 s23, s18, 8
	v_add_u32_e32 v4, s7, v83
	v_or_b32_e32 v84, s19, v1
	v_or_b32_e32 v85, s20, v2
	v_mov_b32_e32 v63, v5
	v_or_b32_e32 v82, s17, v1
	s_add_i32 s31, s18, 12
	v_or_b32_e32 v87, s23, v2
	v_lshlrev_b64 v[76:77], 12, v[4:5]
	v_add_u32_e32 v62, s4, v84
	v_add_u32_e32 v4, s7, v85
	v_mov_b32_e32 v61, v5
	s_add_i32 s21, s17, 8
	s_add_i32 s30, s17, 12
	s_add_i32 s34, s18, 16
	v_add_u32_e32 v60, s4, v82
	v_or_b32_e32 v89, s31, v2
	v_lshlrev_b64 v[62:63], 12, v[62:63]
	v_lshlrev_b64 v[78:79], 12, v[4:5]
	v_add_u32_e32 v4, s7, v87
	s_add_i32 s36, s18, 20
	v_or_b32_e32 v86, s21, v1
	v_or_b32_e32 v88, s30, v1
	v_or_b32_e32 v91, s34, v2
	v_lshlrev_b64 v[60:61], 12, v[60:61]
	v_lshl_add_u64 v[76:77], v[54:55], 0, v[76:77]
	v_lshl_add_u64 v[62:63], v[54:55], 0, v[62:63]
	v_lshlrev_b64 v[80:81], 12, v[4:5]
	v_add_u32_e32 v4, s7, v89
	v_mov_b32_e32 v65, v5
	v_mov_b32_e32 v67, v5
	s_add_i32 s33, s17, 16
	s_add_i32 s35, s17, 20
	s_add_i32 s38, s18, 24
	v_or_b32_e32 v93, s36, v2
	v_add_u32_e32 v64, s4, v86
	v_add_u32_e32 v66, s4, v88
	v_lshl_add_u64 v[60:61], v[54:55], 0, v[60:61]
	v_lshl_add_u64 v[78:79], v[54:55], 0, v[78:79]
	global_load_dword v98, v[76:77], off
	global_load_dword v99, v[60:61], off
	global_load_dword v100, v[78:79], off
	global_load_dword v101, v[62:63], off
	v_lshlrev_b64 v[62:63], 12, v[4:5]
	v_add_u32_e32 v4, s7, v91
	s_add_i32 s37, s17, 24
	s_add_i32 s17, s17, 28
	s_add_i32 s18, s18, 28
	v_or_b32_e32 v90, s33, v1
	v_or_b32_e32 v92, s35, v1
	v_or_b32_e32 v95, s38, v2
	v_lshlrev_b64 v[64:65], 12, v[64:65]
	v_lshlrev_b64 v[66:67], 12, v[66:67]
	v_lshl_add_u64 v[60:61], v[54:55], 0, v[80:81]
	v_lshl_add_u64 v[62:63], v[54:55], 0, v[62:63]
	v_lshlrev_b64 v[76:77], 12, v[4:5]
	v_add_u32_e32 v4, s7, v93
	v_mov_b32_e32 v69, v5
	v_mov_b32_e32 v71, v5
	v_or_b32_e32 v94, s37, v1
	v_or_b32_e32 v96, s17, v1
	v_or_b32_e32 v97, s18, v2
	v_add_u32_e32 v68, s4, v90
	v_add_u32_e32 v70, s4, v92
	v_lshl_add_u64 v[64:65], v[54:55], 0, v[64:65]
	v_lshl_add_u64 v[66:67], v[54:55], 0, v[66:67]
	global_load_dword v102, v[60:61], off
	global_load_dword v103, v[64:65], off
	global_load_dword v104, v[62:63], off
	global_load_dword v105, v[66:67], off
	v_lshlrev_b64 v[62:63], 12, v[4:5]
	v_add_u32_e32 v4, s7, v95
	v_mov_b32_e32 v73, v5
	v_mov_b32_e32 v75, v5
	v_add_u32_e32 v72, s4, v94
	v_add_u32_e32 v74, s4, v96
	v_lshlrev_b64 v[68:69], 12, v[68:69]
	v_lshlrev_b64 v[70:71], 12, v[70:71]
	v_lshl_add_u64 v[60:61], v[54:55], 0, v[76:77]
	v_lshl_add_u64 v[62:63], v[54:55], 0, v[62:63]
	v_lshlrev_b64 v[64:65], 12, v[4:5]
	v_add_u32_e32 v4, s7, v97
	v_lshlrev_b64 v[72:73], 12, v[72:73]
	v_lshlrev_b64 v[74:75], 12, v[74:75]
	v_lshl_add_u64 v[68:69], v[54:55], 0, v[68:69]
	v_lshl_add_u64 v[70:71], v[54:55], 0, v[70:71]
	global_load_dword v106, v[60:61], off
	global_load_dword v107, v[68:69], off
	global_load_dword v108, v[62:63], off
	global_load_dword v109, v[70:71], off
	v_lshl_add_u64 v[60:61], v[54:55], 0, v[64:65]
	v_lshlrev_b64 v[62:63], 12, v[4:5]
	v_lshl_add_u64 v[72:73], v[54:55], 0, v[72:73]
	v_lshl_add_u64 v[74:75], v[54:55], 0, v[74:75]
	v_lshl_add_u64 v[62:63], v[54:55], 0, v[62:63]
	global_load_dword v4, v[60:61], off
	global_load_dword v110, v[72:73], off
	global_load_dword v111, v[62:63], off
	global_load_dword v112, v[74:75], off
	s_add_i32 s9, s9, 16
	s_add_i32 s8, s8, 16
	s_add_i32 s16, s16, -16
	v_mad_u64_u32 v[60:61], s[18:19], v83, s10, v[10:11]
	s_cmp_lg_u32 s16, 0
	v_mad_u64_u32 v[62:63], s[18:19], v82, s10, v[10:11]
	v_mad_u64_u32 v[64:65], s[18:19], v85, s10, v[10:11]
	v_mad_u64_u32 v[66:67], s[18:19], v84, s10, v[10:11]
	v_mad_u64_u32 v[68:69], s[18:19], v87, s10, v[10:11]
	v_mad_u64_u32 v[70:71], s[18:19], v86, s10, v[10:11]
	v_mad_u64_u32 v[72:73], s[18:19], v89, s10, v[10:11]
	v_mad_u64_u32 v[74:75], s[18:19], v88, s10, v[10:11]
	v_mad_u64_u32 v[76:77], s[18:19], v91, s10, v[10:11]
	v_mad_u64_u32 v[78:79], s[18:19], v90, s10, v[10:11]
	v_mad_u64_u32 v[80:81], s[18:19], v93, s10, v[10:11]
	v_mad_u64_u32 v[82:83], s[18:19], v92, s10, v[10:11]
	v_mad_u64_u32 v[84:85], s[18:19], v95, s10, v[10:11]
	v_mad_u64_u32 v[86:87], s[18:19], v94, s10, v[10:11]
	v_mad_u64_u32 v[88:89], s[18:19], v97, s10, v[10:11]
	v_mad_u64_u32 v[90:91], s[18:19], v96, s10, v[10:11]
	s_waitcnt vmcnt(15)
	ds_write_b32 v60, v98
	s_waitcnt vmcnt(14)
	ds_write_b32 v62, v99
	s_waitcnt vmcnt(13)
	ds_write_b32 v64, v100
	s_waitcnt vmcnt(12)
	ds_write_b32 v66, v101
	s_waitcnt vmcnt(11)
	ds_write_b32 v68, v102
	s_waitcnt vmcnt(10)
	ds_write_b32 v70, v103
	s_waitcnt vmcnt(9)
	ds_write_b32 v72, v104
	s_waitcnt vmcnt(8)
	ds_write_b32 v74, v105
	s_waitcnt vmcnt(7)
	ds_write_b32 v76, v106
	s_waitcnt vmcnt(6)
	ds_write_b32 v78, v107
	s_waitcnt vmcnt(5)
	ds_write_b32 v80, v108
	s_waitcnt vmcnt(4)
	ds_write_b32 v82, v109
	s_waitcnt vmcnt(3)
	ds_write_b32 v84, v4
	s_waitcnt vmcnt(2)
	ds_write_b32 v86, v110
	s_waitcnt vmcnt(1)
	ds_write_b32 v88, v111
	s_waitcnt vmcnt(0)
	ds_write_b32 v90, v112
	s_cbranch_scc1 .LBB0_27
	s_waitcnt lgkmcnt(0)
	ds_read2_b32 v[54:55], v56 offset0:33 offset1:41
	ds_read2_b32 v[64:65], v56 offset1:8
	ds_read2_b32 v[66:67], v56 offset0:66 offset1:74
	ds_read2_b32 v[68:69], v56 offset0:99 offset1:107
	ds_read2_b32 v[70:71], v56 offset0:132 offset1:140
	ds_read2_b32 v[72:73], v56 offset0:165 offset1:173
	ds_read2_b32 v[74:75], v56 offset0:198 offset1:206
	ds_read2_b32 v[76:77], v56 offset0:231 offset1:239
	s_lshl_b32 s4, s7, 1
	v_or_b32_e32 v4, s6, v3
	v_lshl_add_u64 v[78:79], v[14:15], 0, s[4:5]
	v_lshlrev_b32_e32 v4, 11, v4
	s_waitcnt lgkmcnt(6)
	v_mul_f32_e32 v64, 0xbfb8aa3b, v64
	v_mul_f32_e32 v54, 0xbfb8aa3b, v54
	v_cvt_pk_bf16_f32 v60, v64, v54
	s_waitcnt lgkmcnt(4)
	v_mul_f32_e32 v66, 0xbfb8aa3b, v66
	v_mul_f32_e32 v68, 0xbfb8aa3b, v68
	v_cvt_pk_bf16_f32 v61, v66, v68
	s_waitcnt lgkmcnt(2)
	v_mul_f32_e32 v70, 0xbfb8aa3b, v70
	v_mul_f32_e32 v72, 0xbfb8aa3b, v72
	v_cvt_pk_bf16_f32 v62, v70, v72
	s_waitcnt lgkmcnt(0)
	v_mul_f32_e32 v74, 0xbfb8aa3b, v74
	v_mul_f32_e32 v76, 0xbfb8aa3b, v76
	v_cvt_pk_bf16_f32 v63, v74, v76
	v_lshl_add_u64 v[80:81], v[78:79], 0, v[4:5]
	global_store_dwordx4 v[80:81], v[60:63], off
	v_or_b32_e32 v4, s6, v57
	v_lshlrev_b32_e32 v4, 11, v4
	v_mul_f32_e32 v65, 0xbfb8aa3b, v65
	v_mul_f32_e32 v55, 0xbfb8aa3b, v55
	v_cvt_pk_bf16_f32 v60, v65, v55
	v_mul_f32_e32 v67, 0xbfb8aa3b, v67
	v_mul_f32_e32 v69, 0xbfb8aa3b, v69
	v_cvt_pk_bf16_f32 v61, v67, v69
	v_mul_f32_e32 v71, 0xbfb8aa3b, v71
	v_mul_f32_e32 v73, 0xbfb8aa3b, v73
	v_cvt_pk_bf16_f32 v62, v71, v73
	v_mul_f32_e32 v75, 0xbfb8aa3b, v75
	v_mul_f32_e32 v77, 0xbfb8aa3b, v77
	v_cvt_pk_bf16_f32 v63, v75, v77
	ds_read2_b32 v[64:65], v56 offset0:49 offset1:57
	ds_read2_b32 v[66:67], v56 offset0:16 offset1:24
	ds_read2_b32 v[68:69], v56 offset0:82 offset1:90
	ds_read2_b32 v[70:71], v56 offset0:115 offset1:123
	ds_read2_b32 v[72:73], v56 offset0:148 offset1:156
	ds_read2_b32 v[74:75], v56 offset0:181 offset1:189
	ds_read2_b32 v[76:77], v56 offset0:214 offset1:222
	ds_read2_b32 v[80:81], v56 offset0:247 offset1:255
	v_lshl_add_u64 v[54:55], v[78:79], 0, v[4:5]
	v_or_b32_e32 v4, s6, v58
	v_lshlrev_b32_e32 v4, 11, v4
	global_store_dwordx4 v[54:55], v[60:63], off
	v_lshl_add_u64 v[54:55], v[78:79], 0, v[4:5]
	v_or_b32_e32 v4, s6, v59
	s_waitcnt lgkmcnt(6)
	v_mul_f32_e32 v66, 0xbfb8aa3b, v66
	v_mul_f32_e32 v64, 0xbfb8aa3b, v64
	v_cvt_pk_bf16_f32 v60, v66, v64
	s_waitcnt lgkmcnt(4)
	v_mul_f32_e32 v68, 0xbfb8aa3b, v68
	v_mul_f32_e32 v70, 0xbfb8aa3b, v70
	v_cvt_pk_bf16_f32 v61, v68, v70
	s_waitcnt lgkmcnt(2)
	v_mul_f32_e32 v72, 0xbfb8aa3b, v72
	v_mul_f32_e32 v74, 0xbfb8aa3b, v74
	v_cvt_pk_bf16_f32 v62, v72, v74
	s_waitcnt lgkmcnt(0)
	v_mul_f32_e32 v76, 0xbfb8aa3b, v76
	v_mul_f32_e32 v80, 0xbfb8aa3b, v80
	v_cvt_pk_bf16_f32 v63, v76, v80
	v_lshlrev_b32_e32 v4, 11, v4
	global_store_dwordx4 v[54:55], v[60:63], off
	v_lshl_add_u64 v[54:55], v[78:79], 0, v[4:5]
	s_mov_b64 s[6:7], 0
	v_mul_f32_e32 v67, 0xbfb8aa3b, v67
	v_mul_f32_e32 v65, 0xbfb8aa3b, v65
	v_cvt_pk_bf16_f32 v60, v67, v65
	v_mul_f32_e32 v69, 0xbfb8aa3b, v69
	v_mul_f32_e32 v71, 0xbfb8aa3b, v71
	v_cvt_pk_bf16_f32 v61, v69, v71
	v_mul_f32_e32 v73, 0xbfb8aa3b, v73
	v_mul_f32_e32 v75, 0xbfb8aa3b, v75
	v_cvt_pk_bf16_f32 v62, v73, v75
	v_mul_f32_e32 v77, 0xbfb8aa3b, v77
	v_mul_f32_e32 v81, 0xbfb8aa3b, v81
	v_cvt_pk_bf16_f32 v63, v77, v81
	global_store_dwordx4 v[54:55], v[60:63], off
	s_waitcnt lgkmcnt(0)

.LBB0_66:
	s_lshl_b32 s18, s9, 1
	s_lshl_b32 s19, s16, 1
	v_or_b32_e32 v4, s18, v1
	v_or_b32_e32 v92, s19, v2
	s_add_i32 s20, s18, 4
	s_add_i32 s21, s19, 4
	s_add_i32 s23, s18, 8
	s_add_i32 s30, s19, 8
	s_add_i32 s31, s18, 12
	s_add_i32 s33, s19, 12
	s_add_i32 s34, s18, 16
	s_add_i32 s35, s19, 16
	s_add_i32 s36, s18, 20
	s_add_i32 s37, s19, 20
	s_add_i32 s38, s18, 24
	s_add_i32 s39, s19, 24
	s_add_i32 s18, s18, 28
	s_add_i32 s19, s19, 28
	v_add_u32_e32 v60, s6, v92
	v_or_b32_e32 v93, s20, v1
	v_or_b32_e32 v94, s21, v2
	v_or_b32_e32 v95, s23, v1
	v_or_b32_e32 v96, s30, v2
	v_or_b32_e32 v97, s31, v1
	v_or_b32_e32 v98, s33, v2
	v_or_b32_e32 v99, s34, v1
	v_or_b32_e32 v100, s35, v2
	v_or_b32_e32 v101, s36, v1
	v_or_b32_e32 v102, s37, v2
	v_or_b32_e32 v103, s38, v1
	v_or_b32_e32 v104, s39, v2
	v_or_b32_e32 v105, s18, v1
	v_or_b32_e32 v106, s19, v2
	v_add_u32_e32 v62, s4, v4
	v_mad_u64_u32 v[60:61], s[18:19], v60, s14, v[54:55]
	v_add_u32_e32 v66, s4, v93
	v_add_u32_e32 v64, s6, v94
	v_add_u32_e32 v70, s4, v95
	v_add_u32_e32 v68, s6, v96
	v_add_u32_e32 v74, s4, v97
	v_add_u32_e32 v72, s6, v98
	v_add_u32_e32 v78, s4, v99
	v_add_u32_e32 v76, s6, v100
	v_add_u32_e32 v82, s4, v101
	v_add_u32_e32 v80, s6, v102
	v_add_u32_e32 v86, s4, v103
	v_add_u32_e32 v84, s6, v104
	v_add_u32_e32 v90, s4, v105
	v_add_u32_e32 v88, s6, v106
	v_mad_u64_u32 v[62:63], s[18:19], v62, s14, v[54:55]
	v_mad_u64_u32 v[64:65], s[18:19], v64, s14, v[54:55]
	v_mad_u64_u32 v[66:67], s[18:19], v66, s14, v[54:55]
	v_mad_u64_u32 v[68:69], s[18:19], v68, s14, v[54:55]
	v_mad_u64_u32 v[70:71], s[18:19], v70, s14, v[54:55]
	v_mad_u64_u32 v[72:73], s[18:19], v72, s14, v[54:55]
	v_mad_u64_u32 v[74:75], s[18:19], v74, s14, v[54:55]
	v_mad_u64_u32 v[76:77], s[18:19], v76, s14, v[54:55]
	v_mad_u64_u32 v[78:79], s[18:19], v78, s14, v[54:55]
	v_mad_u64_u32 v[80:81], s[18:19], v80, s14, v[54:55]
	v_mad_u64_u32 v[82:83], s[18:19], v82, s14, v[54:55]
	v_mad_u64_u32 v[84:85], s[18:19], v84, s14, v[54:55]
	v_mad_u64_u32 v[86:87], s[18:19], v86, s14, v[54:55]
	v_mad_u64_u32 v[88:89], s[18:19], v88, s14, v[54:55]
	v_mad_u64_u32 v[90:91], s[18:19], v90, s14, v[54:55]
	global_load_dword v107, v[60:61], off
	global_load_dword v108, v[62:63], off
	global_load_dword v109, v[64:65], off
	global_load_dword v110, v[66:67], off
	global_load_dword v111, v[68:69], off
	global_load_dword v112, v[70:71], off
	global_load_dword v113, v[72:73], off
	global_load_dword v114, v[74:75], off
	global_load_dword v115, v[76:77], off
	global_load_dword v116, v[78:79], off
	global_load_dword v117, v[80:81], off
	global_load_dword v118, v[82:83], off
	global_load_dword v119, v[84:85], off
	global_load_dword v120, v[86:87], off
	global_load_dword v121, v[88:89], off
	global_load_dword v122, v[90:91], off
	s_add_i32 s16, s16, 16
	s_add_i32 s9, s9, 16
	s_add_i32 s17, s17, -16
	v_mad_u64_u32 v[60:61], s[18:19], v92, s10, v[10:11]
	s_cmp_lg_u32 s17, 0
	v_mad_u64_u32 v[62:63], s[18:19], v4, s10, v[10:11]
	v_mad_u64_u32 v[64:65], s[18:19], v94, s10, v[10:11]
	v_mad_u64_u32 v[66:67], s[18:19], v93, s10, v[10:11]
	v_mad_u64_u32 v[68:69], s[18:19], v96, s10, v[10:11]
	v_mad_u64_u32 v[70:71], s[18:19], v95, s10, v[10:11]
	v_mad_u64_u32 v[72:73], s[18:19], v98, s10, v[10:11]
	v_mad_u64_u32 v[74:75], s[18:19], v97, s10, v[10:11]
	v_mad_u64_u32 v[76:77], s[18:19], v100, s10, v[10:11]
	v_mad_u64_u32 v[78:79], s[18:19], v99, s10, v[10:11]
	v_mad_u64_u32 v[80:81], s[18:19], v102, s10, v[10:11]
	v_mad_u64_u32 v[82:83], s[18:19], v101, s10, v[10:11]
	v_mad_u64_u32 v[84:85], s[18:19], v104, s10, v[10:11]
	v_mad_u64_u32 v[86:87], s[18:19], v103, s10, v[10:11]
	v_mad_u64_u32 v[88:89], s[18:19], v106, s10, v[10:11]
	v_mad_u64_u32 v[90:91], s[18:19], v105, s10, v[10:11]
	s_waitcnt vmcnt(15)
	ds_write_b32 v60, v107
	s_waitcnt vmcnt(14)
	ds_write_b32 v62, v108
	s_waitcnt vmcnt(13)
	ds_write_b32 v64, v109
	s_waitcnt vmcnt(12)
	ds_write_b32 v66, v110
	s_waitcnt vmcnt(11)
	ds_write_b32 v68, v111
	s_waitcnt vmcnt(10)
	ds_write_b32 v70, v112
	s_waitcnt vmcnt(9)
	ds_write_b32 v72, v113
	s_waitcnt vmcnt(8)
	ds_write_b32 v74, v114
	s_waitcnt vmcnt(7)
	ds_write_b32 v76, v115
	s_waitcnt vmcnt(6)
	ds_write_b32 v78, v116
	s_waitcnt vmcnt(5)
	ds_write_b32 v80, v117
	s_waitcnt vmcnt(4)
	ds_write_b32 v82, v118
	s_waitcnt vmcnt(3)
	ds_write_b32 v84, v119
	s_waitcnt vmcnt(2)
	ds_write_b32 v86, v120
	s_waitcnt vmcnt(1)
	ds_write_b32 v88, v121
	s_waitcnt vmcnt(0)
	ds_write_b32 v90, v122
	s_cbranch_scc1 .LBB0_66
	s_lshl_b32 s4, s8, 6
	s_waitcnt lgkmcnt(0)
	s_and_b32 s4, s4, 0x1f00
	s_and_b32 s7, s7, 0x60
	ds_read2_b32 v[54:55], v56 offset0:33 offset1:41
	ds_read2_b32 v[64:65], v56 offset1:8
	ds_read2_b32 v[66:67], v56 offset0:66 offset1:74
	ds_read2_b32 v[68:69], v56 offset0:99 offset1:107
	ds_read2_b32 v[70:71], v56 offset0:132 offset1:140
	ds_read2_b32 v[72:73], v56 offset0:165 offset1:173
	ds_read2_b32 v[74:75], v56 offset0:198 offset1:206
	ds_read2_b32 v[76:77], v56 offset0:231 offset1:239
	s_or_b32 s4, s7, s4
	s_or_b32 s7, s4, 0x80
	s_and_b32 s4, 0xffff, s6
	s_lshl_b32 s4, s4, 1
	v_or_b32_e32 v4, s7, v3
	v_lshl_add_u64 v[78:79], v[48:49], 0, s[4:5]
	v_lshlrev_b32_e32 v4, 11, v4
	s_waitcnt lgkmcnt(6)
	v_mul_f32_e32 v64, 0xbf317218, v64
	v_mul_f32_e32 v54, 0xbf317218, v54
	v_cvt_pk_bf16_f32 v60, v64, v54
	s_waitcnt lgkmcnt(4)
	v_mul_f32_e32 v66, 0xbf317218, v66
	v_mul_f32_e32 v68, 0xbf317218, v68
	v_cvt_pk_bf16_f32 v61, v66, v68
	s_waitcnt lgkmcnt(2)
	v_mul_f32_e32 v70, 0xbf317218, v70
	v_mul_f32_e32 v72, 0xbf317218, v72
	v_cvt_pk_bf16_f32 v62, v70, v72
	s_waitcnt lgkmcnt(0)
	v_mul_f32_e32 v74, 0xbf317218, v74
	v_mul_f32_e32 v76, 0xbf317218, v76
	v_cvt_pk_bf16_f32 v63, v74, v76
	v_lshl_add_u64 v[80:81], v[78:79], 0, v[4:5]
	global_store_dwordx4 v[80:81], v[60:63], off
	v_or_b32_e32 v4, s7, v57
	v_lshlrev_b32_e32 v4, 11, v4
	v_mul_f32_e32 v65, 0xbf317218, v65
	v_mul_f32_e32 v55, 0xbf317218, v55
	v_cvt_pk_bf16_f32 v60, v65, v55
	v_mul_f32_e32 v67, 0xbf317218, v67
	v_mul_f32_e32 v69, 0xbf317218, v69
	v_cvt_pk_bf16_f32 v61, v67, v69
	v_mul_f32_e32 v71, 0xbf317218, v71
	v_mul_f32_e32 v73, 0xbf317218, v73
	v_cvt_pk_bf16_f32 v62, v71, v73
	v_mul_f32_e32 v75, 0xbf317218, v75
	v_mul_f32_e32 v77, 0xbf317218, v77
	v_cvt_pk_bf16_f32 v63, v75, v77
	ds_read2_b32 v[64:65], v56 offset0:49 offset1:57
	ds_read2_b32 v[66:67], v56 offset0:16 offset1:24
	ds_read2_b32 v[68:69], v56 offset0:82 offset1:90
	ds_read2_b32 v[70:71], v56 offset0:115 offset1:123
	ds_read2_b32 v[72:73], v56 offset0:148 offset1:156
	ds_read2_b32 v[74:75], v56 offset0:181 offset1:189
	ds_read2_b32 v[76:77], v56 offset0:214 offset1:222
	ds_read2_b32 v[80:81], v56 offset0:247 offset1:255
	v_lshl_add_u64 v[54:55], v[78:79], 0, v[4:5]
	v_or_b32_e32 v4, s7, v58
	v_lshlrev_b32_e32 v4, 11, v4
	global_store_dwordx4 v[54:55], v[60:63], off
	v_lshl_add_u64 v[54:55], v[78:79], 0, v[4:5]
	v_or_b32_e32 v4, s7, v59
	s_waitcnt lgkmcnt(6)
	v_mul_f32_e32 v66, 0xbf317218, v66
	v_mul_f32_e32 v64, 0xbf317218, v64
	v_cvt_pk_bf16_f32 v60, v66, v64
	s_waitcnt lgkmcnt(4)
	v_mul_f32_e32 v68, 0xbf317218, v68
	v_mul_f32_e32 v70, 0xbf317218, v70
	v_cvt_pk_bf16_f32 v61, v68, v70
	s_waitcnt lgkmcnt(2)
	v_mul_f32_e32 v72, 0xbf317218, v72
	v_mul_f32_e32 v74, 0xbf317218, v74
	v_cvt_pk_bf16_f32 v62, v72, v74
	s_waitcnt lgkmcnt(0)
	v_mul_f32_e32 v76, 0xbf317218, v76
	v_mul_f32_e32 v80, 0xbf317218, v80
	v_cvt_pk_bf16_f32 v63, v76, v80
	v_lshlrev_b32_e32 v4, 11, v4
	global_store_dwordx4 v[54:55], v[60:63], off
	v_lshl_add_u64 v[54:55], v[78:79], 0, v[4:5]
	s_nop 0
	v_mul_f32_e32 v67, 0xbf317218, v67
	v_mul_f32_e32 v65, 0xbf317218, v65
	v_cvt_pk_bf16_f32 v60, v67, v65
	v_mul_f32_e32 v69, 0xbf317218, v69
	v_mul_f32_e32 v71, 0xbf317218, v71
	v_cvt_pk_bf16_f32 v61, v69, v71
	v_mul_f32_e32 v73, 0xbf317218, v73
	v_mul_f32_e32 v75, 0xbf317218, v75
	v_cvt_pk_bf16_f32 v62, v73, v75
	v_mul_f32_e32 v77, 0xbf317218, v77
	v_mul_f32_e32 v81, 0xbf317218, v81
	v_cvt_pk_bf16_f32 v63, v77, v81
	global_store_dwordx4 v[54:55], v[60:63], off
	s_waitcnt lgkmcnt(0)

.LBB0_71:
	s_lshl_b32 s18, s9, 1
	s_lshl_b32 s19, s16, 1
	v_or_b32_e32 v4, s18, v1
	v_or_b32_e32 v92, s19, v2
	s_add_i32 s20, s18, 4
	s_add_i32 s21, s19, 4
	s_add_i32 s23, s18, 8
	s_add_i32 s30, s19, 8
	s_add_i32 s31, s18, 12
	s_add_i32 s33, s19, 12
	s_add_i32 s34, s18, 16
	s_add_i32 s35, s19, 16
	s_add_i32 s36, s18, 20
	s_add_i32 s37, s19, 20
	s_add_i32 s38, s18, 24
	s_add_i32 s39, s19, 24
	s_add_i32 s18, s18, 28
	s_add_i32 s19, s19, 28
	v_add_u32_e32 v60, s6, v92
	v_or_b32_e32 v93, s20, v1
	v_or_b32_e32 v94, s21, v2
	v_or_b32_e32 v95, s23, v1
	v_or_b32_e32 v96, s30, v2
	v_or_b32_e32 v97, s31, v1
	v_or_b32_e32 v98, s33, v2
	v_or_b32_e32 v99, s34, v1
	v_or_b32_e32 v100, s35, v2
	v_or_b32_e32 v101, s36, v1
	v_or_b32_e32 v102, s37, v2
	v_or_b32_e32 v103, s38, v1
	v_or_b32_e32 v104, s39, v2
	v_or_b32_e32 v105, s18, v1
	v_or_b32_e32 v106, s19, v2
	v_add_u32_e32 v62, s4, v4
	v_mad_u64_u32 v[60:61], s[18:19], v60, s14, v[54:55]
	v_add_u32_e32 v66, s4, v93
	v_add_u32_e32 v64, s6, v94
	v_add_u32_e32 v70, s4, v95
	v_add_u32_e32 v68, s6, v96
	v_add_u32_e32 v74, s4, v97
	v_add_u32_e32 v72, s6, v98
	v_add_u32_e32 v78, s4, v99
	v_add_u32_e32 v76, s6, v100
	v_add_u32_e32 v82, s4, v101
	v_add_u32_e32 v80, s6, v102
	v_add_u32_e32 v86, s4, v103
	v_add_u32_e32 v84, s6, v104
	v_add_u32_e32 v90, s4, v105
	v_add_u32_e32 v88, s6, v106
	v_mad_u64_u32 v[62:63], s[18:19], v62, s14, v[54:55]
	v_mad_u64_u32 v[64:65], s[18:19], v64, s14, v[54:55]
	v_mad_u64_u32 v[66:67], s[18:19], v66, s14, v[54:55]
	v_mad_u64_u32 v[68:69], s[18:19], v68, s14, v[54:55]
	v_mad_u64_u32 v[70:71], s[18:19], v70, s14, v[54:55]
	v_mad_u64_u32 v[72:73], s[18:19], v72, s14, v[54:55]
	v_mad_u64_u32 v[74:75], s[18:19], v74, s14, v[54:55]
	v_mad_u64_u32 v[76:77], s[18:19], v76, s14, v[54:55]
	v_mad_u64_u32 v[78:79], s[18:19], v78, s14, v[54:55]
	v_mad_u64_u32 v[80:81], s[18:19], v80, s14, v[54:55]
	v_mad_u64_u32 v[82:83], s[18:19], v82, s14, v[54:55]
	v_mad_u64_u32 v[84:85], s[18:19], v84, s14, v[54:55]
	v_mad_u64_u32 v[86:87], s[18:19], v86, s14, v[54:55]
	v_mad_u64_u32 v[88:89], s[18:19], v88, s14, v[54:55]
	v_mad_u64_u32 v[90:91], s[18:19], v90, s14, v[54:55]
	global_load_dword v107, v[60:61], off
	global_load_dword v108, v[62:63], off
	global_load_dword v109, v[64:65], off
	global_load_dword v110, v[66:67], off
	global_load_dword v111, v[68:69], off
	global_load_dword v112, v[70:71], off
	global_load_dword v113, v[72:73], off
	global_load_dword v114, v[74:75], off
	global_load_dword v115, v[76:77], off
	global_load_dword v116, v[78:79], off
	global_load_dword v117, v[80:81], off
	global_load_dword v118, v[82:83], off
	global_load_dword v119, v[84:85], off
	global_load_dword v120, v[86:87], off
	global_load_dword v121, v[88:89], off
	global_load_dword v122, v[90:91], off
	s_add_i32 s16, s16, 16
	s_add_i32 s9, s9, 16
	s_add_i32 s17, s17, -16
	v_mad_u64_u32 v[60:61], s[18:19], v92, s10, v[10:11]
	s_cmp_lg_u32 s17, 0
	v_mad_u64_u32 v[62:63], s[18:19], v4, s10, v[10:11]
	v_mad_u64_u32 v[64:65], s[18:19], v94, s10, v[10:11]
	v_mad_u64_u32 v[66:67], s[18:19], v93, s10, v[10:11]
	v_mad_u64_u32 v[68:69], s[18:19], v96, s10, v[10:11]
	v_mad_u64_u32 v[70:71], s[18:19], v95, s10, v[10:11]
	v_mad_u64_u32 v[72:73], s[18:19], v98, s10, v[10:11]
	v_mad_u64_u32 v[74:75], s[18:19], v97, s10, v[10:11]
	v_mad_u64_u32 v[76:77], s[18:19], v100, s10, v[10:11]
	v_mad_u64_u32 v[78:79], s[18:19], v99, s10, v[10:11]
	v_mad_u64_u32 v[80:81], s[18:19], v102, s10, v[10:11]
	v_mad_u64_u32 v[82:83], s[18:19], v101, s10, v[10:11]
	v_mad_u64_u32 v[84:85], s[18:19], v104, s10, v[10:11]
	v_mad_u64_u32 v[86:87], s[18:19], v103, s10, v[10:11]
	v_mad_u64_u32 v[88:89], s[18:19], v106, s10, v[10:11]
	v_mad_u64_u32 v[90:91], s[18:19], v105, s10, v[10:11]
	s_waitcnt vmcnt(15)
	ds_write_b32 v60, v107
	s_waitcnt vmcnt(14)
	ds_write_b32 v62, v108
	s_waitcnt vmcnt(13)
	ds_write_b32 v64, v109
	s_waitcnt vmcnt(12)
	ds_write_b32 v66, v110
	s_waitcnt vmcnt(11)
	ds_write_b32 v68, v111
	s_waitcnt vmcnt(10)
	ds_write_b32 v70, v112
	s_waitcnt vmcnt(9)
	ds_write_b32 v72, v113
	s_waitcnt vmcnt(8)
	ds_write_b32 v74, v114
	s_waitcnt vmcnt(7)
	ds_write_b32 v76, v115
	s_waitcnt vmcnt(6)
	ds_write_b32 v78, v116
	s_waitcnt vmcnt(5)
	ds_write_b32 v80, v117
	s_waitcnt vmcnt(4)
	ds_write_b32 v82, v118
	s_waitcnt vmcnt(3)
	ds_write_b32 v84, v119
	s_waitcnt vmcnt(2)
	ds_write_b32 v86, v120
	s_waitcnt vmcnt(1)
	ds_write_b32 v88, v121
	s_waitcnt vmcnt(0)
	ds_write_b32 v90, v122
	s_cbranch_scc1 .LBB0_71
	s_waitcnt lgkmcnt(0)
	s_lshl_b32 s4, s8, 6
	ds_read2_b32 v[54:55], v56 offset0:33 offset1:41
	ds_read2_b32 v[64:65], v56 offset1:8
	ds_read2_b32 v[66:67], v56 offset0:66 offset1:74
	ds_read2_b32 v[68:69], v56 offset0:99 offset1:107
	ds_read2_b32 v[70:71], v56 offset0:132 offset1:140
	ds_read2_b32 v[72:73], v56 offset0:165 offset1:173
	ds_read2_b32 v[74:75], v56 offset0:198 offset1:206
	ds_read2_b32 v[76:77], v56 offset0:231 offset1:239
	s_and_b32 s4, s4, 0x1f00
	s_and_b32 s7, s7, 0x60
	s_or_b32 s7, s7, s4
	s_and_b32 s4, 0xffff, s6
	s_lshl_b32 s4, s4, 1
	v_or_b32_e32 v4, s7, v3
	v_lshl_add_u64 v[78:79], v[48:49], 0, s[4:5]
	v_lshlrev_b32_e32 v4, 11, v4
	s_waitcnt lgkmcnt(6)
	v_mul_f32_e32 v64, 0xbfb8aa3b, v64
	v_mul_f32_e32 v54, 0xbfb8aa3b, v54
	v_cvt_pk_bf16_f32 v60, v64, v54
	s_waitcnt lgkmcnt(4)
	v_mul_f32_e32 v66, 0xbfb8aa3b, v66
	v_mul_f32_e32 v68, 0xbfb8aa3b, v68
	v_cvt_pk_bf16_f32 v61, v66, v68
	s_waitcnt lgkmcnt(2)
	v_mul_f32_e32 v70, 0xbfb8aa3b, v70
	v_mul_f32_e32 v72, 0xbfb8aa3b, v72
	v_cvt_pk_bf16_f32 v62, v70, v72
	s_waitcnt lgkmcnt(0)
	v_mul_f32_e32 v74, 0xbfb8aa3b, v74
	v_mul_f32_e32 v76, 0xbfb8aa3b, v76
	v_cvt_pk_bf16_f32 v63, v74, v76
	v_lshl_add_u64 v[80:81], v[78:79], 0, v[4:5]
	global_store_dwordx4 v[80:81], v[60:63], off
	v_or_b32_e32 v4, s7, v57
	v_lshlrev_b32_e32 v4, 11, v4
	v_mul_f32_e32 v65, 0xbfb8aa3b, v65
	v_mul_f32_e32 v55, 0xbfb8aa3b, v55
	v_cvt_pk_bf16_f32 v60, v65, v55
	v_mul_f32_e32 v67, 0xbfb8aa3b, v67
	v_mul_f32_e32 v69, 0xbfb8aa3b, v69
	v_cvt_pk_bf16_f32 v61, v67, v69
	v_mul_f32_e32 v71, 0xbfb8aa3b, v71
	v_mul_f32_e32 v73, 0xbfb8aa3b, v73
	v_cvt_pk_bf16_f32 v62, v71, v73
	v_mul_f32_e32 v75, 0xbfb8aa3b, v75
	v_mul_f32_e32 v77, 0xbfb8aa3b, v77
	v_cvt_pk_bf16_f32 v63, v75, v77
	ds_read2_b32 v[64:65], v56 offset0:49 offset1:57
	ds_read2_b32 v[66:67], v56 offset0:16 offset1:24
	ds_read2_b32 v[68:69], v56 offset0:82 offset1:90
	ds_read2_b32 v[70:71], v56 offset0:115 offset1:123
	ds_read2_b32 v[72:73], v56 offset0:148 offset1:156
	ds_read2_b32 v[74:75], v56 offset0:181 offset1:189
	ds_read2_b32 v[76:77], v56 offset0:214 offset1:222
	ds_read2_b32 v[80:81], v56 offset0:247 offset1:255
	v_lshl_add_u64 v[54:55], v[78:79], 0, v[4:5]
	v_or_b32_e32 v4, s7, v58
	v_lshlrev_b32_e32 v4, 11, v4
	global_store_dwordx4 v[54:55], v[60:63], off
	v_lshl_add_u64 v[54:55], v[78:79], 0, v[4:5]
	v_or_b32_e32 v4, s7, v59
	s_waitcnt lgkmcnt(6)
	v_mul_f32_e32 v66, 0xbfb8aa3b, v66
	v_mul_f32_e32 v64, 0xbfb8aa3b, v64
	v_cvt_pk_bf16_f32 v60, v66, v64
	s_waitcnt lgkmcnt(4)
	v_mul_f32_e32 v68, 0xbfb8aa3b, v68
	v_mul_f32_e32 v70, 0xbfb8aa3b, v70
	v_cvt_pk_bf16_f32 v61, v68, v70
	s_waitcnt lgkmcnt(2)
	v_mul_f32_e32 v72, 0xbfb8aa3b, v72
	v_mul_f32_e32 v74, 0xbfb8aa3b, v74
	v_cvt_pk_bf16_f32 v62, v72, v74
	s_waitcnt lgkmcnt(0)
	v_mul_f32_e32 v76, 0xbfb8aa3b, v76
	v_mul_f32_e32 v80, 0xbfb8aa3b, v80
	v_cvt_pk_bf16_f32 v63, v76, v80
	v_lshlrev_b32_e32 v4, 11, v4
	global_store_dwordx4 v[54:55], v[60:63], off
	v_lshl_add_u64 v[54:55], v[78:79], 0, v[4:5]
	s_nop 0
	v_mul_f32_e32 v67, 0xbfb8aa3b, v67
	v_mul_f32_e32 v65, 0xbfb8aa3b, v65
	v_cvt_pk_bf16_f32 v60, v67, v65
	v_mul_f32_e32 v69, 0xbfb8aa3b, v69
	v_mul_f32_e32 v71, 0xbfb8aa3b, v71
	v_cvt_pk_bf16_f32 v61, v69, v71
	v_mul_f32_e32 v73, 0xbfb8aa3b, v73
	v_mul_f32_e32 v75, 0xbfb8aa3b, v75
	v_cvt_pk_bf16_f32 v62, v73, v75
	v_mul_f32_e32 v77, 0xbfb8aa3b, v77
	v_mul_f32_e32 v81, 0xbfb8aa3b, v81
	v_cvt_pk_bf16_f32 v63, v77, v81
	global_store_dwordx4 v[54:55], v[60:63], off
	s_waitcnt lgkmcnt(0)

.LBB0_76:
	s_lshl_b32 s18, s9, 1
	s_lshl_b32 s19, s16, 1
	v_or_b32_e32 v4, s18, v1
	v_or_b32_e32 v92, s19, v2
	s_add_i32 s20, s18, 4
	s_add_i32 s21, s19, 4
	s_add_i32 s23, s18, 8
	s_add_i32 s30, s19, 8
	s_add_i32 s31, s18, 12
	s_add_i32 s33, s19, 12
	s_add_i32 s34, s18, 16
	s_add_i32 s35, s19, 16
	s_add_i32 s36, s18, 20
	s_add_i32 s37, s19, 20
	s_add_i32 s38, s18, 24
	s_add_i32 s39, s19, 24
	s_add_i32 s18, s18, 28
	s_add_i32 s19, s19, 28
	v_add_u32_e32 v60, s6, v92
	v_or_b32_e32 v93, s20, v1
	v_or_b32_e32 v94, s21, v2
	v_or_b32_e32 v95, s23, v1
	v_or_b32_e32 v96, s30, v2
	v_or_b32_e32 v97, s31, v1
	v_or_b32_e32 v98, s33, v2
	v_or_b32_e32 v99, s34, v1
	v_or_b32_e32 v100, s35, v2
	v_or_b32_e32 v101, s36, v1
	v_or_b32_e32 v102, s37, v2
	v_or_b32_e32 v103, s38, v1
	v_or_b32_e32 v104, s39, v2
	v_or_b32_e32 v105, s18, v1
	v_or_b32_e32 v106, s19, v2
	v_add_u32_e32 v62, s4, v4
	v_mad_u64_u32 v[60:61], s[18:19], v60, s14, v[54:55]
	v_add_u32_e32 v66, s4, v93
	v_add_u32_e32 v64, s6, v94
	v_add_u32_e32 v70, s4, v95
	v_add_u32_e32 v68, s6, v96
	v_add_u32_e32 v74, s4, v97
	v_add_u32_e32 v72, s6, v98
	v_add_u32_e32 v78, s4, v99
	v_add_u32_e32 v76, s6, v100
	v_add_u32_e32 v82, s4, v101
	v_add_u32_e32 v80, s6, v102
	v_add_u32_e32 v86, s4, v103
	v_add_u32_e32 v84, s6, v104
	v_add_u32_e32 v90, s4, v105
	v_add_u32_e32 v88, s6, v106
	v_mad_u64_u32 v[62:63], s[18:19], v62, s14, v[54:55]
	v_mad_u64_u32 v[64:65], s[18:19], v64, s14, v[54:55]
	v_mad_u64_u32 v[66:67], s[18:19], v66, s14, v[54:55]
	v_mad_u64_u32 v[68:69], s[18:19], v68, s14, v[54:55]
	v_mad_u64_u32 v[70:71], s[18:19], v70, s14, v[54:55]
	v_mad_u64_u32 v[72:73], s[18:19], v72, s14, v[54:55]
	v_mad_u64_u32 v[74:75], s[18:19], v74, s14, v[54:55]
	v_mad_u64_u32 v[76:77], s[18:19], v76, s14, v[54:55]
	v_mad_u64_u32 v[78:79], s[18:19], v78, s14, v[54:55]
	v_mad_u64_u32 v[80:81], s[18:19], v80, s14, v[54:55]
	v_mad_u64_u32 v[82:83], s[18:19], v82, s14, v[54:55]
	v_mad_u64_u32 v[84:85], s[18:19], v84, s14, v[54:55]
	v_mad_u64_u32 v[86:87], s[18:19], v86, s14, v[54:55]
	v_mad_u64_u32 v[88:89], s[18:19], v88, s14, v[54:55]
	v_mad_u64_u32 v[90:91], s[18:19], v90, s14, v[54:55]
	global_load_dword v107, v[60:61], off
	global_load_dword v108, v[62:63], off
	global_load_dword v109, v[64:65], off
	global_load_dword v110, v[66:67], off
	global_load_dword v111, v[68:69], off
	global_load_dword v112, v[70:71], off
	global_load_dword v113, v[72:73], off
	global_load_dword v114, v[74:75], off
	global_load_dword v115, v[76:77], off
	global_load_dword v116, v[78:79], off
	global_load_dword v117, v[80:81], off
	global_load_dword v118, v[82:83], off
	global_load_dword v119, v[84:85], off
	global_load_dword v120, v[86:87], off
	global_load_dword v121, v[88:89], off
	global_load_dword v122, v[90:91], off
	s_add_i32 s16, s16, 16
	s_add_i32 s9, s9, 16
	s_add_i32 s17, s17, -16
	v_mad_u64_u32 v[60:61], s[18:19], v92, s10, v[10:11]
	s_cmp_lg_u32 s17, 0
	v_mad_u64_u32 v[62:63], s[18:19], v4, s10, v[10:11]
	v_mad_u64_u32 v[64:65], s[18:19], v94, s10, v[10:11]
	v_mad_u64_u32 v[66:67], s[18:19], v93, s10, v[10:11]
	v_mad_u64_u32 v[68:69], s[18:19], v96, s10, v[10:11]
	v_mad_u64_u32 v[70:71], s[18:19], v95, s10, v[10:11]
	v_mad_u64_u32 v[72:73], s[18:19], v98, s10, v[10:11]
	v_mad_u64_u32 v[74:75], s[18:19], v97, s10, v[10:11]
	v_mad_u64_u32 v[76:77], s[18:19], v100, s10, v[10:11]
	v_mad_u64_u32 v[78:79], s[18:19], v99, s10, v[10:11]
	v_mad_u64_u32 v[80:81], s[18:19], v102, s10, v[10:11]
	v_mad_u64_u32 v[82:83], s[18:19], v101, s10, v[10:11]
	v_mad_u64_u32 v[84:85], s[18:19], v104, s10, v[10:11]
	v_mad_u64_u32 v[86:87], s[18:19], v103, s10, v[10:11]
	v_mad_u64_u32 v[88:89], s[18:19], v106, s10, v[10:11]
	v_mad_u64_u32 v[90:91], s[18:19], v105, s10, v[10:11]
	s_waitcnt vmcnt(15)
	ds_write_b32 v60, v107
	s_waitcnt vmcnt(14)
	ds_write_b32 v62, v108
	s_waitcnt vmcnt(13)
	ds_write_b32 v64, v109
	s_waitcnt vmcnt(12)
	ds_write_b32 v66, v110
	s_waitcnt vmcnt(11)
	ds_write_b32 v68, v111
	s_waitcnt vmcnt(10)
	ds_write_b32 v70, v112
	s_waitcnt vmcnt(9)
	ds_write_b32 v72, v113
	s_waitcnt vmcnt(8)
	ds_write_b32 v74, v114
	s_waitcnt vmcnt(7)
	ds_write_b32 v76, v115
	s_waitcnt vmcnt(6)
	ds_write_b32 v78, v116
	s_waitcnt vmcnt(5)
	ds_write_b32 v80, v117
	s_waitcnt vmcnt(4)
	ds_write_b32 v82, v118
	s_waitcnt vmcnt(3)
	ds_write_b32 v84, v119
	s_waitcnt vmcnt(2)
	ds_write_b32 v86, v120
	s_waitcnt vmcnt(1)
	ds_write_b32 v88, v121
	s_waitcnt vmcnt(0)
	ds_write_b32 v90, v122
	s_cbranch_scc1 .LBB0_76
	s_lshl_b32 s4, s8, 6
	s_waitcnt lgkmcnt(0)
	s_and_b32 s4, s4, 0x1f00
	s_and_b32 s7, s7, 0x60
	ds_read2_b32 v[54:55], v56 offset0:33 offset1:41
	ds_read2_b32 v[64:65], v56 offset1:8
	ds_read2_b32 v[66:67], v56 offset0:66 offset1:74
	ds_read2_b32 v[68:69], v56 offset0:99 offset1:107
	ds_read2_b32 v[70:71], v56 offset0:132 offset1:140
	ds_read2_b32 v[72:73], v56 offset0:165 offset1:173
	ds_read2_b32 v[74:75], v56 offset0:198 offset1:206
	ds_read2_b32 v[76:77], v56 offset0:231 offset1:239
	s_or_b32 s4, s7, s4
	s_or_b32 s7, s4, 0x80
	s_and_b32 s4, 0xffff, s6
	s_lshl_b32 s4, s4, 1
	v_or_b32_e32 v4, s7, v3
	v_lshl_add_u64 v[78:79], v[12:13], 0, s[4:5]
	v_lshlrev_b32_e32 v4, 11, v4
	s_waitcnt lgkmcnt(6)
	v_mul_f32_e32 v64, 0xbf317218, v64
	v_mul_f32_e32 v54, 0xbf317218, v54
	v_cvt_pk_bf16_f32 v60, v64, v54
	s_waitcnt lgkmcnt(4)
	v_mul_f32_e32 v66, 0xbf317218, v66
	v_mul_f32_e32 v68, 0xbf317218, v68
	v_cvt_pk_bf16_f32 v61, v66, v68
	s_waitcnt lgkmcnt(2)
	v_mul_f32_e32 v70, 0xbf317218, v70
	v_mul_f32_e32 v72, 0xbf317218, v72
	v_cvt_pk_bf16_f32 v62, v70, v72
	s_waitcnt lgkmcnt(0)
	v_mul_f32_e32 v74, 0xbf317218, v74
	v_mul_f32_e32 v76, 0xbf317218, v76
	v_cvt_pk_bf16_f32 v63, v74, v76
	v_lshl_add_u64 v[80:81], v[78:79], 0, v[4:5]
	global_store_dwordx4 v[80:81], v[60:63], off
	v_or_b32_e32 v4, s7, v57
	v_lshlrev_b32_e32 v4, 11, v4
	v_mul_f32_e32 v65, 0xbf317218, v65
	v_mul_f32_e32 v55, 0xbf317218, v55
	v_cvt_pk_bf16_f32 v60, v65, v55
	v_mul_f32_e32 v67, 0xbf317218, v67
	v_mul_f32_e32 v69, 0xbf317218, v69
	v_cvt_pk_bf16_f32 v61, v67, v69
	v_mul_f32_e32 v71, 0xbf317218, v71
	v_mul_f32_e32 v73, 0xbf317218, v73
	v_cvt_pk_bf16_f32 v62, v71, v73
	v_mul_f32_e32 v75, 0xbf317218, v75
	v_mul_f32_e32 v77, 0xbf317218, v77
	v_cvt_pk_bf16_f32 v63, v75, v77
	ds_read2_b32 v[64:65], v56 offset0:49 offset1:57
	ds_read2_b32 v[66:67], v56 offset0:16 offset1:24
	ds_read2_b32 v[68:69], v56 offset0:82 offset1:90
	ds_read2_b32 v[70:71], v56 offset0:115 offset1:123
	ds_read2_b32 v[72:73], v56 offset0:148 offset1:156
	ds_read2_b32 v[74:75], v56 offset0:181 offset1:189
	ds_read2_b32 v[76:77], v56 offset0:214 offset1:222
	ds_read2_b32 v[80:81], v56 offset0:247 offset1:255
	v_lshl_add_u64 v[54:55], v[78:79], 0, v[4:5]
	v_or_b32_e32 v4, s7, v58
	v_lshlrev_b32_e32 v4, 11, v4
	global_store_dwordx4 v[54:55], v[60:63], off
	v_lshl_add_u64 v[54:55], v[78:79], 0, v[4:5]
	v_or_b32_e32 v4, s7, v59
	s_waitcnt lgkmcnt(6)
	v_mul_f32_e32 v66, 0xbf317218, v66
	v_mul_f32_e32 v64, 0xbf317218, v64
	v_cvt_pk_bf16_f32 v60, v66, v64
	s_waitcnt lgkmcnt(4)
	v_mul_f32_e32 v68, 0xbf317218, v68
	v_mul_f32_e32 v70, 0xbf317218, v70
	v_cvt_pk_bf16_f32 v61, v68, v70
	s_waitcnt lgkmcnt(2)
	v_mul_f32_e32 v72, 0xbf317218, v72
	v_mul_f32_e32 v74, 0xbf317218, v74
	v_cvt_pk_bf16_f32 v62, v72, v74
	s_waitcnt lgkmcnt(0)
	v_mul_f32_e32 v76, 0xbf317218, v76
	v_mul_f32_e32 v80, 0xbf317218, v80
	v_cvt_pk_bf16_f32 v63, v76, v80
	v_lshlrev_b32_e32 v4, 11, v4
	global_store_dwordx4 v[54:55], v[60:63], off
	v_lshl_add_u64 v[54:55], v[78:79], 0, v[4:5]
	s_nop 0
	v_mul_f32_e32 v67, 0xbf317218, v67
	v_mul_f32_e32 v65, 0xbf317218, v65
	v_cvt_pk_bf16_f32 v60, v67, v65
	v_mul_f32_e32 v69, 0xbf317218, v69
	v_mul_f32_e32 v71, 0xbf317218, v71
	v_cvt_pk_bf16_f32 v61, v69, v71
	v_mul_f32_e32 v73, 0xbf317218, v73
	v_mul_f32_e32 v75, 0xbf317218, v75
	v_cvt_pk_bf16_f32 v62, v73, v75
	v_mul_f32_e32 v77, 0xbf317218, v77
	v_mul_f32_e32 v81, 0xbf317218, v81
	v_cvt_pk_bf16_f32 v63, v77, v81
	global_store_dwordx4 v[54:55], v[60:63], off
	s_waitcnt lgkmcnt(0)

.LBB0_81:
	s_lshl_b32 s18, s9, 1
	s_lshl_b32 s19, s16, 1
	v_or_b32_e32 v4, s18, v1
	v_or_b32_e32 v92, s19, v2
	s_add_i32 s20, s18, 4
	s_add_i32 s21, s19, 4
	s_add_i32 s23, s18, 8
	s_add_i32 s30, s19, 8
	s_add_i32 s31, s18, 12
	s_add_i32 s33, s19, 12
	s_add_i32 s34, s18, 16
	s_add_i32 s35, s19, 16
	s_add_i32 s36, s18, 20
	s_add_i32 s37, s19, 20
	s_add_i32 s38, s18, 24
	s_add_i32 s39, s19, 24
	s_add_i32 s18, s18, 28
	s_add_i32 s19, s19, 28
	v_add_u32_e32 v60, s6, v92
	v_or_b32_e32 v93, s20, v1
	v_or_b32_e32 v94, s21, v2
	v_or_b32_e32 v95, s23, v1
	v_or_b32_e32 v96, s30, v2
	v_or_b32_e32 v97, s31, v1
	v_or_b32_e32 v98, s33, v2
	v_or_b32_e32 v99, s34, v1
	v_or_b32_e32 v100, s35, v2
	v_or_b32_e32 v101, s36, v1
	v_or_b32_e32 v102, s37, v2
	v_or_b32_e32 v103, s38, v1
	v_or_b32_e32 v104, s39, v2
	v_or_b32_e32 v105, s18, v1
	v_or_b32_e32 v106, s19, v2
	v_add_u32_e32 v62, s7, v4
	v_mad_i64_i32 v[60:61], s[18:19], v60, s14, v[54:55]
	v_add_u32_e32 v66, s7, v93
	v_add_u32_e32 v64, s6, v94
	v_add_u32_e32 v70, s7, v95
	v_add_u32_e32 v68, s6, v96
	v_add_u32_e32 v74, s7, v97
	v_add_u32_e32 v72, s6, v98
	v_add_u32_e32 v78, s7, v99
	v_add_u32_e32 v76, s6, v100
	v_add_u32_e32 v82, s7, v101
	v_add_u32_e32 v80, s6, v102
	v_add_u32_e32 v86, s7, v103
	v_add_u32_e32 v84, s6, v104
	v_add_u32_e32 v90, s7, v105
	v_add_u32_e32 v88, s6, v106
	v_mad_i64_i32 v[62:63], s[18:19], v62, s14, v[54:55]
	v_mad_i64_i32 v[64:65], s[18:19], v64, s14, v[54:55]
	v_mad_i64_i32 v[66:67], s[18:19], v66, s14, v[54:55]
	v_mad_i64_i32 v[68:69], s[18:19], v68, s14, v[54:55]
	v_mad_i64_i32 v[70:71], s[18:19], v70, s14, v[54:55]
	v_mad_i64_i32 v[72:73], s[18:19], v72, s14, v[54:55]
	v_mad_i64_i32 v[74:75], s[18:19], v74, s14, v[54:55]
	v_mad_i64_i32 v[76:77], s[18:19], v76, s14, v[54:55]
	v_mad_i64_i32 v[78:79], s[18:19], v78, s14, v[54:55]
	v_mad_i64_i32 v[80:81], s[18:19], v80, s14, v[54:55]
	v_mad_i64_i32 v[82:83], s[18:19], v82, s14, v[54:55]
	v_mad_i64_i32 v[84:85], s[18:19], v84, s14, v[54:55]
	v_mad_i64_i32 v[86:87], s[18:19], v86, s14, v[54:55]
	v_mad_i64_i32 v[88:89], s[18:19], v88, s14, v[54:55]
	v_mad_i64_i32 v[90:91], s[18:19], v90, s14, v[54:55]
	global_load_dword v107, v[60:61], off
	global_load_dword v108, v[62:63], off
	global_load_dword v109, v[64:65], off
	global_load_dword v110, v[66:67], off
	global_load_dword v111, v[68:69], off
	global_load_dword v112, v[70:71], off
	global_load_dword v113, v[72:73], off
	global_load_dword v114, v[74:75], off
	global_load_dword v115, v[76:77], off
	global_load_dword v116, v[78:79], off
	global_load_dword v117, v[80:81], off
	global_load_dword v118, v[82:83], off
	global_load_dword v119, v[84:85], off
	global_load_dword v120, v[86:87], off
	global_load_dword v121, v[88:89], off
	global_load_dword v122, v[90:91], off
	s_add_i32 s16, s16, 16
	s_add_i32 s9, s9, 16
	s_add_i32 s17, s17, -16
	v_mad_u64_u32 v[60:61], s[18:19], v92, s10, v[10:11]
	s_cmp_lg_u32 s17, 0
	v_mad_u64_u32 v[62:63], s[18:19], v4, s10, v[10:11]
	v_mad_u64_u32 v[64:65], s[18:19], v94, s10, v[10:11]
	v_mad_u64_u32 v[66:67], s[18:19], v93, s10, v[10:11]
	v_mad_u64_u32 v[68:69], s[18:19], v96, s10, v[10:11]
	v_mad_u64_u32 v[70:71], s[18:19], v95, s10, v[10:11]
	v_mad_u64_u32 v[72:73], s[18:19], v98, s10, v[10:11]
	v_mad_u64_u32 v[74:75], s[18:19], v97, s10, v[10:11]
	v_mad_u64_u32 v[76:77], s[18:19], v100, s10, v[10:11]
	v_mad_u64_u32 v[78:79], s[18:19], v99, s10, v[10:11]
	v_mad_u64_u32 v[80:81], s[18:19], v102, s10, v[10:11]
	v_mad_u64_u32 v[82:83], s[18:19], v101, s10, v[10:11]
	v_mad_u64_u32 v[84:85], s[18:19], v104, s10, v[10:11]
	v_mad_u64_u32 v[86:87], s[18:19], v103, s10, v[10:11]
	v_mad_u64_u32 v[88:89], s[18:19], v106, s10, v[10:11]
	v_mad_u64_u32 v[90:91], s[18:19], v105, s10, v[10:11]
	s_waitcnt vmcnt(15)
	ds_write_b32 v60, v107
	s_waitcnt vmcnt(14)
	ds_write_b32 v62, v108
	s_waitcnt vmcnt(13)
	ds_write_b32 v64, v109
	s_waitcnt vmcnt(12)
	ds_write_b32 v66, v110
	s_waitcnt vmcnt(11)
	ds_write_b32 v68, v111
	s_waitcnt vmcnt(10)
	ds_write_b32 v70, v112
	s_waitcnt vmcnt(9)
	ds_write_b32 v72, v113
	s_waitcnt vmcnt(8)
	ds_write_b32 v74, v114
	s_waitcnt vmcnt(7)
	ds_write_b32 v76, v115
	s_waitcnt vmcnt(6)
	ds_write_b32 v78, v116
	s_waitcnt vmcnt(5)
	ds_write_b32 v80, v117
	s_waitcnt vmcnt(4)
	ds_write_b32 v82, v118
	s_waitcnt vmcnt(3)
	ds_write_b32 v84, v119
	s_waitcnt vmcnt(2)
	ds_write_b32 v86, v120
	s_waitcnt vmcnt(1)
	ds_write_b32 v88, v121
	s_waitcnt vmcnt(0)
	ds_write_b32 v90, v122
	s_cbranch_scc1 .LBB0_81
	s_lshl_b32 s4, s4, 6
	s_waitcnt lgkmcnt(0)
	s_and_b32 s4, s4, 0xffffff00
	s_and_b32 s7, s8, 0x60
	ds_read2_b32 v[54:55], v56 offset0:33 offset1:41
	ds_read2_b32 v[64:65], v56 offset1:8
	ds_read2_b32 v[66:67], v56 offset0:66 offset1:74
	ds_read2_b32 v[68:69], v56 offset0:99 offset1:107
	ds_read2_b32 v[70:71], v56 offset0:132 offset1:140
	ds_read2_b32 v[72:73], v56 offset0:165 offset1:173
	ds_read2_b32 v[74:75], v56 offset0:198 offset1:206
	ds_read2_b32 v[76:77], v56 offset0:231 offset1:239
	s_or_b32 s4, s7, s4
	v_or_b32_e32 v80, s4, v3
	s_ashr_i32 s7, s6, 31
	v_ashrrev_i32_e32 v81, 31, v80
	v_lshl_add_u64 v[78:79], s[6:7], 1, v[12:13]
	v_lshlrev_b64 v[80:81], 11, v[80:81]
	s_waitcnt lgkmcnt(6)
	v_mul_f32_e32 v64, 0xbfb8aa3b, v64
	v_mul_f32_e32 v54, 0xbfb8aa3b, v54
	v_cvt_pk_bf16_f32 v60, v64, v54
	s_waitcnt lgkmcnt(4)
	v_mul_f32_e32 v66, 0xbfb8aa3b, v66
	v_mul_f32_e32 v68, 0xbfb8aa3b, v68
	v_cvt_pk_bf16_f32 v61, v66, v68
	s_waitcnt lgkmcnt(2)
	v_mul_f32_e32 v70, 0xbfb8aa3b, v70
	v_mul_f32_e32 v72, 0xbfb8aa3b, v72
	v_cvt_pk_bf16_f32 v62, v70, v72
	s_waitcnt lgkmcnt(0)
	v_mul_f32_e32 v74, 0xbfb8aa3b, v74
	v_mul_f32_e32 v76, 0xbfb8aa3b, v76
	v_cvt_pk_bf16_f32 v63, v74, v76
	v_lshl_add_u64 v[80:81], v[78:79], 0, v[80:81]
	v_or_b32_e32 v54, s4, v57
	global_store_dwordx4 v[80:81], v[60:63], off
	s_nop 1
	v_mul_f32_e32 v65, 0xbfb8aa3b, v65
	v_mul_f32_e32 v55, 0xbfb8aa3b, v55
	v_cvt_pk_bf16_f32 v60, v65, v55
	v_ashrrev_i32_e32 v55, 31, v54
	v_mul_f32_e32 v67, 0xbfb8aa3b, v67
	v_mul_f32_e32 v69, 0xbfb8aa3b, v69
	v_cvt_pk_bf16_f32 v61, v67, v69
	v_mul_f32_e32 v71, 0xbfb8aa3b, v71
	v_mul_f32_e32 v73, 0xbfb8aa3b, v73
	v_cvt_pk_bf16_f32 v62, v71, v73
	v_mul_f32_e32 v75, 0xbfb8aa3b, v75
	v_mul_f32_e32 v77, 0xbfb8aa3b, v77
	v_cvt_pk_bf16_f32 v63, v75, v77
	v_lshlrev_b64 v[54:55], 11, v[54:55]
	ds_read2_b32 v[64:65], v56 offset0:49 offset1:57
	ds_read2_b32 v[66:67], v56 offset0:16 offset1:24
	ds_read2_b32 v[68:69], v56 offset0:82 offset1:90
	ds_read2_b32 v[70:71], v56 offset0:115 offset1:123
	ds_read2_b32 v[72:73], v56 offset0:148 offset1:156
	ds_read2_b32 v[74:75], v56 offset0:181 offset1:189
	ds_read2_b32 v[76:77], v56 offset0:214 offset1:222
	ds_read2_b32 v[80:81], v56 offset0:247 offset1:255
	v_lshl_add_u64 v[54:55], v[78:79], 0, v[54:55]
	global_store_dwordx4 v[54:55], v[60:63], off
	v_or_b32_e32 v54, s4, v58
	v_ashrrev_i32_e32 v55, 31, v54
	v_lshlrev_b64 v[54:55], 11, v[54:55]
	s_waitcnt lgkmcnt(6)
	v_mul_f32_e32 v66, 0xbfb8aa3b, v66
	v_mul_f32_e32 v64, 0xbfb8aa3b, v64
	v_cvt_pk_bf16_f32 v60, v66, v64
	s_waitcnt lgkmcnt(4)
	v_mul_f32_e32 v68, 0xbfb8aa3b, v68
	v_mul_f32_e32 v70, 0xbfb8aa3b, v70
	v_cvt_pk_bf16_f32 v61, v68, v70
	s_waitcnt lgkmcnt(2)
	v_mul_f32_e32 v72, 0xbfb8aa3b, v72
	v_mul_f32_e32 v74, 0xbfb8aa3b, v74
	v_cvt_pk_bf16_f32 v62, v72, v74
	s_waitcnt lgkmcnt(0)
	v_mul_f32_e32 v76, 0xbfb8aa3b, v76
	v_mul_f32_e32 v80, 0xbfb8aa3b, v80
	v_cvt_pk_bf16_f32 v63, v76, v80
	v_lshl_add_u64 v[54:55], v[78:79], 0, v[54:55]
	global_store_dwordx4 v[54:55], v[60:63], off
	v_or_b32_e32 v54, s4, v59
	v_ashrrev_i32_e32 v55, 31, v54
	v_lshlrev_b64 v[54:55], 11, v[54:55]
	v_mul_f32_e32 v67, 0xbfb8aa3b, v67
	v_mul_f32_e32 v65, 0xbfb8aa3b, v65
	v_cvt_pk_bf16_f32 v60, v67, v65
	v_mul_f32_e32 v69, 0xbfb8aa3b, v69
	v_mul_f32_e32 v71, 0xbfb8aa3b, v71
	v_cvt_pk_bf16_f32 v61, v69, v71
	v_mul_f32_e32 v73, 0xbfb8aa3b, v73
	v_mul_f32_e32 v75, 0xbfb8aa3b, v75
	v_cvt_pk_bf16_f32 v62, v73, v75
	v_mul_f32_e32 v77, 0xbfb8aa3b, v77
	v_mul_f32_e32 v81, 0xbfb8aa3b, v81
	v_cvt_pk_bf16_f32 v63, v77, v81
	v_lshl_add_u64 v[54:55], v[78:79], 0, v[54:55]
	global_store_dwordx4 v[54:55], v[60:63], off
	s_waitcnt lgkmcnt(0)
	s_branch .LBB0_14

.LBB0_124:
	v_exp_f32_e32 v144, v124
	v_exp_f32_e32 v145, v125
	v_lshl_or_b32 v154, s50, 7, v149
	v_add_f32_e32 v144, 1.0, v144
	v_rcp_f32_e32 v156, v144
	v_add_f32_e32 v144, 1.0, v145
	v_rcp_f32_e32 v157, v144
	v_lshl_add_u32 v153, s18, 8, v147
	v_ashrrev_i32_e32 v155, 31, v154
	v_mov_b64_e32 v[144:145], s[36:37]
	v_pk_mul_f32 v[124:125], v[124:125], v[156:157]
	v_exp_f32_e32 v156, v126
	v_exp_f32_e32 v157, v127
	v_pk_mul_f32 v[116:117], v[124:125], v[116:117]
	v_mad_i64_i32 v[158:159], s[0:1], v153, s49, v[144:145]
	v_add_f32_e32 v124, 1.0, v156
	v_add_f32_e32 v125, 1.0, v157
	v_rcp_f32_e32 v124, v124
	v_rcp_f32_e32 v125, v125
	v_exp_f32_e32 v156, v120
	v_exp_f32_e32 v157, v121
	s_andn2_b64 vcc, exec, s[2:3]
	v_pk_mul_f32 v[124:125], v[126:127], v[124:125]
	v_add_f32_e32 v126, 1.0, v156
	v_add_f32_e32 v127, 1.0, v157
	v_exp_f32_e32 v156, v122
	v_exp_f32_e32 v157, v123
	v_rcp_f32_e32 v126, v126
	v_rcp_f32_e32 v127, v127
	v_add_f32_e32 v156, 1.0, v156
	v_add_f32_e32 v157, 1.0, v157
	v_rcp_f32_e32 v156, v156
	v_rcp_f32_e32 v157, v157
	v_pk_mul_f32 v[120:121], v[120:121], v[126:127]
	v_pk_mul_f32 v[118:119], v[124:125], v[118:119]
	v_pk_mul_f32 v[120:121], v[120:121], v[112:113]
	v_pk_mul_f32 v[112:113], v[122:123], v[156:157]
	s_nop 0
	v_pk_mul_f32 v[122:123], v[112:113], v[114:115]
	v_cvt_pk_bf16_f32 v115, v118, v119
	v_exp_f32_e32 v118, v108
	v_exp_f32_e32 v119, v109
	v_lshlrev_b64 v[112:113], 1, v[154:155]
	v_lshl_add_u64 v[124:125], v[158:159], 0, v[112:113]
	v_cvt_pk_bf16_f32 v114, v116, v117
	v_cvt_pk_bf16_f32 v116, v120, v121
	v_cvt_pk_bf16_f32 v117, v122, v123
	global_store_dwordx4 v[124:125], v[114:117], off
	s_nop 1
	v_add_f32_e32 v114, 1.0, v118
	v_add_f32_e32 v115, 1.0, v119
	v_rcp_f32_e32 v114, v114
	v_rcp_f32_e32 v115, v115
	v_or_b32_e32 v116, 16, v153
	v_mad_i64_i32 v[116:117], s[0:1], v116, s49, v[144:145]
	v_pk_mul_f32 v[108:109], v[108:109], v[114:115]
	v_exp_f32_e32 v114, v110
	v_exp_f32_e32 v115, v111
	v_pk_mul_f32 v[100:101], v[108:109], v[100:101]
	v_add_f32_e32 v108, 1.0, v114
	v_add_f32_e32 v109, 1.0, v115
	v_rcp_f32_e32 v108, v108
	v_rcp_f32_e32 v109, v109
	v_exp_f32_e32 v114, v104
	v_exp_f32_e32 v115, v105
	v_pk_mul_f32 v[108:109], v[110:111], v[108:109]
	v_add_f32_e32 v110, 1.0, v114
	v_add_f32_e32 v111, 1.0, v115
	v_exp_f32_e32 v114, v106
	v_exp_f32_e32 v115, v107
	v_rcp_f32_e32 v110, v110
	v_rcp_f32_e32 v111, v111
	v_add_f32_e32 v114, 1.0, v114
	v_add_f32_e32 v115, 1.0, v115
	v_rcp_f32_e32 v114, v114
	v_rcp_f32_e32 v115, v115
	v_pk_mul_f32 v[104:105], v[104:105], v[110:111]
	v_pk_mul_f32 v[102:103], v[108:109], v[102:103]
	v_pk_mul_f32 v[104:105], v[104:105], v[96:97]
	v_pk_mul_f32 v[96:97], v[106:107], v[114:115]
	v_lshl_add_u64 v[108:109], v[116:117], 0, v[112:113]
	v_pk_mul_f32 v[106:107], v[96:97], v[98:99]
	v_cvt_pk_bf16_f32 v96, v100, v101
	v_exp_f32_e32 v100, v92
	v_exp_f32_e32 v101, v93
	v_cvt_pk_bf16_f32 v97, v102, v103
	v_cvt_pk_bf16_f32 v98, v104, v105
	v_cvt_pk_bf16_f32 v99, v106, v107
	global_store_dwordx4 v[108:109], v[96:99], off
	s_nop 1
	v_add_f32_e32 v96, 1.0, v100
	v_add_f32_e32 v97, 1.0, v101
	v_rcp_f32_e32 v96, v96
	v_rcp_f32_e32 v97, v97
	v_or_b32_e32 v98, 32, v153
	v_mad_i64_i32 v[98:99], s[0:1], v98, s49, v[144:145]
	v_pk_mul_f32 v[92:93], v[92:93], v[96:97]
	v_exp_f32_e32 v96, v94
	v_exp_f32_e32 v97, v95
	v_pk_mul_f32 v[84:85], v[92:93], v[84:85]
	v_add_f32_e32 v92, 1.0, v96
	v_add_f32_e32 v93, 1.0, v97
	v_rcp_f32_e32 v92, v92
	v_rcp_f32_e32 v93, v93
	v_exp_f32_e32 v96, v88
	v_exp_f32_e32 v97, v89
	v_pk_mul_f32 v[92:93], v[94:95], v[92:93]
	v_add_f32_e32 v94, 1.0, v96
	v_add_f32_e32 v95, 1.0, v97
	v_exp_f32_e32 v96, v90
	v_exp_f32_e32 v97, v91
	v_rcp_f32_e32 v94, v94
	v_rcp_f32_e32 v95, v95
	v_add_f32_e32 v96, 1.0, v96
	v_add_f32_e32 v97, 1.0, v97
	v_rcp_f32_e32 v96, v96
	v_rcp_f32_e32 v97, v97
	v_pk_mul_f32 v[88:89], v[88:89], v[94:95]
	v_pk_mul_f32 v[86:87], v[92:93], v[86:87]
	v_pk_mul_f32 v[88:89], v[88:89], v[80:81]
	v_pk_mul_f32 v[80:81], v[90:91], v[96:97]
	v_lshl_add_u64 v[92:93], v[98:99], 0, v[112:113]
	v_pk_mul_f32 v[90:91], v[80:81], v[82:83]
	v_cvt_pk_bf16_f32 v80, v84, v85
	v_exp_f32_e32 v84, v76
	v_exp_f32_e32 v85, v77
	v_cvt_pk_bf16_f32 v81, v86, v87
	v_cvt_pk_bf16_f32 v82, v88, v89
	v_cvt_pk_bf16_f32 v83, v90, v91
	global_store_dwordx4 v[92:93], v[80:83], off
	s_nop 1
	v_add_f32_e32 v80, 1.0, v84
	v_add_f32_e32 v81, 1.0, v85
	v_rcp_f32_e32 v80, v80
	v_rcp_f32_e32 v81, v81
	v_or_b32_e32 v82, 48, v153
	v_mad_i64_i32 v[82:83], s[0:1], v82, s49, v[144:145]
	v_pk_mul_f32 v[76:77], v[76:77], v[80:81]
	v_exp_f32_e32 v80, v78
	v_exp_f32_e32 v81, v79
	v_pk_mul_f32 v[68:69], v[76:77], v[68:69]
	v_add_f32_e32 v76, 1.0, v80
	v_add_f32_e32 v77, 1.0, v81
	v_rcp_f32_e32 v76, v76
	v_rcp_f32_e32 v77, v77
	v_exp_f32_e32 v80, v72
	v_exp_f32_e32 v81, v73
	v_pk_mul_f32 v[76:77], v[78:79], v[76:77]
	v_add_f32_e32 v78, 1.0, v80
	v_add_f32_e32 v79, 1.0, v81
	v_exp_f32_e32 v80, v74
	v_exp_f32_e32 v81, v75
	v_rcp_f32_e32 v78, v78
	v_rcp_f32_e32 v79, v79
	v_add_f32_e32 v80, 1.0, v80
	v_add_f32_e32 v81, 1.0, v81
	v_rcp_f32_e32 v80, v80
	v_rcp_f32_e32 v81, v81
	v_pk_mul_f32 v[72:73], v[72:73], v[78:79]
	v_pk_mul_f32 v[70:71], v[76:77], v[70:71]
	v_pk_mul_f32 v[72:73], v[72:73], v[64:65]
	v_pk_mul_f32 v[64:65], v[74:75], v[80:81]
	v_lshl_add_u64 v[76:77], v[82:83], 0, v[112:113]
	v_pk_mul_f32 v[74:75], v[64:65], v[66:67]
	v_cvt_pk_bf16_f32 v64, v68, v69
	v_exp_f32_e32 v68, v60
	v_exp_f32_e32 v69, v61
	v_cvt_pk_bf16_f32 v65, v70, v71
	v_cvt_pk_bf16_f32 v66, v72, v73
	v_cvt_pk_bf16_f32 v67, v74, v75
	global_store_dwordx4 v[76:77], v[64:67], off
	s_nop 1
	v_add_f32_e32 v64, 1.0, v68
	v_add_f32_e32 v65, 1.0, v69
	v_rcp_f32_e32 v64, v64
	v_rcp_f32_e32 v65, v65
	v_add_u32_e32 v66, 0x80, v153
	v_mad_i64_i32 v[66:67], s[0:1], v66, s49, v[144:145]
	v_pk_mul_f32 v[60:61], v[60:61], v[64:65]
	v_exp_f32_e32 v64, v62
	v_exp_f32_e32 v65, v63
	v_pk_mul_f32 v[52:53], v[60:61], v[52:53]
	v_add_f32_e32 v60, 1.0, v64
	v_add_f32_e32 v61, 1.0, v65
	v_rcp_f32_e32 v60, v60
	v_rcp_f32_e32 v61, v61
	v_exp_f32_e32 v64, v56
	v_exp_f32_e32 v65, v57
	v_pk_mul_f32 v[60:61], v[62:63], v[60:61]
	v_add_f32_e32 v62, 1.0, v64
	v_add_f32_e32 v63, 1.0, v65
	v_exp_f32_e32 v64, v58
	v_exp_f32_e32 v65, v59
	v_rcp_f32_e32 v62, v62
	v_rcp_f32_e32 v63, v63
	v_add_f32_e32 v64, 1.0, v64
	v_add_f32_e32 v65, 1.0, v65
	v_rcp_f32_e32 v64, v64
	v_rcp_f32_e32 v65, v65
	v_pk_mul_f32 v[56:57], v[56:57], v[62:63]
	v_pk_mul_f32 v[54:55], v[60:61], v[54:55]
	v_pk_mul_f32 v[56:57], v[56:57], v[48:49]
	v_pk_mul_f32 v[48:49], v[58:59], v[64:65]
	v_lshl_add_u64 v[60:61], v[66:67], 0, v[112:113]
	v_pk_mul_f32 v[58:59], v[48:49], v[50:51]
	v_cvt_pk_bf16_f32 v48, v52, v53
	v_exp_f32_e32 v52, v44
	v_exp_f32_e32 v53, v45
	v_cvt_pk_bf16_f32 v49, v54, v55
	v_cvt_pk_bf16_f32 v50, v56, v57
	v_cvt_pk_bf16_f32 v51, v58, v59
	global_store_dwordx4 v[60:61], v[48:51], off
	s_nop 1
	v_add_f32_e32 v48, 1.0, v52
	v_add_f32_e32 v49, 1.0, v53
	v_rcp_f32_e32 v48, v48
	v_rcp_f32_e32 v49, v49
	v_add_u32_e32 v50, 0x90, v153
	v_mad_i64_i32 v[50:51], s[0:1], v50, s49, v[144:145]
	v_pk_mul_f32 v[44:45], v[44:45], v[48:49]
	v_exp_f32_e32 v48, v46
	v_exp_f32_e32 v49, v47
	v_pk_mul_f32 v[36:37], v[44:45], v[36:37]
	v_add_f32_e32 v44, 1.0, v48
	v_add_f32_e32 v45, 1.0, v49
	v_rcp_f32_e32 v44, v44
	v_rcp_f32_e32 v45, v45
	v_exp_f32_e32 v48, v40
	v_exp_f32_e32 v49, v41
	v_pk_mul_f32 v[44:45], v[46:47], v[44:45]
	v_add_f32_e32 v46, 1.0, v48
	v_add_f32_e32 v47, 1.0, v49
	v_exp_f32_e32 v48, v42
	v_exp_f32_e32 v49, v43
	v_rcp_f32_e32 v46, v46
	v_rcp_f32_e32 v47, v47
	v_add_f32_e32 v48, 1.0, v48
	v_add_f32_e32 v49, 1.0, v49
	v_rcp_f32_e32 v48, v48
	v_rcp_f32_e32 v49, v49
	v_pk_mul_f32 v[40:41], v[40:41], v[46:47]
	v_pk_mul_f32 v[38:39], v[44:45], v[38:39]
	v_pk_mul_f32 v[40:41], v[40:41], v[32:33]
	v_pk_mul_f32 v[32:33], v[42:43], v[48:49]
	v_lshl_add_u64 v[44:45], v[50:51], 0, v[112:113]
	v_pk_mul_f32 v[42:43], v[32:33], v[34:35]
	v_cvt_pk_bf16_f32 v32, v36, v37
	v_exp_f32_e32 v36, v28
	v_exp_f32_e32 v37, v29
	v_cvt_pk_bf16_f32 v33, v38, v39
	v_cvt_pk_bf16_f32 v34, v40, v41
	v_cvt_pk_bf16_f32 v35, v42, v43
	global_store_dwordx4 v[44:45], v[32:35], off
	s_nop 1
	v_add_f32_e32 v32, 1.0, v36
	v_add_f32_e32 v33, 1.0, v37
	v_rcp_f32_e32 v32, v32
	v_rcp_f32_e32 v33, v33
	v_add_u32_e32 v34, 0xa0, v153
	v_mad_i64_i32 v[34:35], s[0:1], v34, s49, v[144:145]
	v_pk_mul_f32 v[28:29], v[28:29], v[32:33]
	v_exp_f32_e32 v32, v30
	v_exp_f32_e32 v33, v31
	v_pk_mul_f32 v[20:21], v[28:29], v[20:21]
	v_add_f32_e32 v28, 1.0, v32
	v_add_f32_e32 v29, 1.0, v33
	v_rcp_f32_e32 v28, v28
	v_rcp_f32_e32 v29, v29
	v_exp_f32_e32 v32, v24
	v_exp_f32_e32 v33, v25
	v_pk_mul_f32 v[28:29], v[30:31], v[28:29]
	v_add_f32_e32 v30, 1.0, v32
	v_add_f32_e32 v31, 1.0, v33
	v_exp_f32_e32 v32, v26
	v_exp_f32_e32 v33, v27
	v_rcp_f32_e32 v30, v30
	v_rcp_f32_e32 v31, v31
	v_add_f32_e32 v32, 1.0, v32
	v_add_f32_e32 v33, 1.0, v33
	v_rcp_f32_e32 v32, v32
	v_rcp_f32_e32 v33, v33
	v_pk_mul_f32 v[24:25], v[24:25], v[30:31]
	v_pk_mul_f32 v[22:23], v[28:29], v[22:23]
	v_pk_mul_f32 v[24:25], v[24:25], v[16:17]
	v_pk_mul_f32 v[16:17], v[26:27], v[32:33]
	v_lshl_add_u64 v[28:29], v[34:35], 0, v[112:113]
	v_pk_mul_f32 v[26:27], v[16:17], v[18:19]
	v_cvt_pk_bf16_f32 v16, v20, v21
	v_exp_f32_e32 v20, v12
	v_exp_f32_e32 v21, v13
	v_cvt_pk_bf16_f32 v17, v22, v23
	v_cvt_pk_bf16_f32 v18, v24, v25
	v_cvt_pk_bf16_f32 v19, v26, v27
	global_store_dwordx4 v[28:29], v[16:19], off
	s_nop 1
	v_add_f32_e32 v16, 1.0, v20
	v_add_f32_e32 v17, 1.0, v21
	v_rcp_f32_e32 v16, v16
	v_rcp_f32_e32 v17, v17
	v_add_u32_e32 v18, 0xb0, v153
	v_mad_i64_i32 v[18:19], s[0:1], v18, s49, v[144:145]
	v_pk_mul_f32 v[12:13], v[12:13], v[16:17]
	v_exp_f32_e32 v16, v14
	v_exp_f32_e32 v17, v15
	v_pk_mul_f32 v[4:5], v[12:13], v[4:5]
	s_mov_b64 s[0:1], -1
	v_add_f32_e32 v12, 1.0, v16
	v_add_f32_e32 v13, 1.0, v17
	v_rcp_f32_e32 v12, v12
	v_rcp_f32_e32 v13, v13
	v_exp_f32_e32 v16, v8
	v_exp_f32_e32 v17, v9
	v_pk_mul_f32 v[12:13], v[14:15], v[12:13]
	v_add_f32_e32 v14, 1.0, v16
	v_add_f32_e32 v15, 1.0, v17
	v_exp_f32_e32 v16, v10
	v_exp_f32_e32 v17, v11
	v_rcp_f32_e32 v14, v14
	v_rcp_f32_e32 v15, v15
	v_add_f32_e32 v16, 1.0, v16
	v_add_f32_e32 v17, 1.0, v17
	v_rcp_f32_e32 v16, v16
	v_rcp_f32_e32 v17, v17
	v_pk_mul_f32 v[8:9], v[8:9], v[14:15]
	v_pk_mul_f32 v[6:7], v[12:13], v[6:7]
	v_pk_mul_f32 v[8:9], v[8:9], v[0:1]
	v_pk_mul_f32 v[0:1], v[10:11], v[16:17]
	v_lshl_add_u64 v[12:13], v[18:19], 0, v[112:113]
	v_pk_mul_f32 v[10:11], v[0:1], v[2:3]
	v_cvt_pk_bf16_f32 v0, v4, v5
	v_cvt_pk_bf16_f32 v1, v6, v7
	v_cvt_pk_bf16_f32 v2, v8, v9
	v_cvt_pk_bf16_f32 v3, v10, v11
	global_store_dwordx4 v[12:13], v[0:3], off
	s_cbranch_vccnz .LBB0_117
	s_andn2_b64 vcc, exec, s[4:5]
	s_cbranch_vccnz .LBB0_116
	s_barrier
	s_branch .LBB0_116

.LBB0_971:
	v_exp_f32_e32 v144, v124
	v_exp_f32_e32 v145, v125
	v_lshl_or_b32 v154, s64, 7, v149
	v_add_f32_e32 v144, 1.0, v144
	v_rcp_f32_e32 v156, v144
	v_add_f32_e32 v144, 1.0, v145
	v_rcp_f32_e32 v157, v144
	v_lshl_add_u32 v153, s18, 8, v147
	v_ashrrev_i32_e32 v155, 31, v154
	v_mov_b64_e32 v[144:145], s[36:37]
	v_pk_mul_f32 v[124:125], v[124:125], v[156:157]
	v_exp_f32_e32 v156, v126
	v_exp_f32_e32 v157, v127
	v_pk_mul_f32 v[116:117], v[124:125], v[116:117]
	v_mad_i64_i32 v[158:159], s[0:1], v153, s63, v[144:145]
	v_add_f32_e32 v124, 1.0, v156
	v_add_f32_e32 v125, 1.0, v157
	v_rcp_f32_e32 v124, v124
	v_rcp_f32_e32 v125, v125
	v_exp_f32_e32 v156, v120
	v_exp_f32_e32 v157, v121
	s_andn2_b64 vcc, exec, s[2:3]
	v_pk_mul_f32 v[124:125], v[126:127], v[124:125]
	v_add_f32_e32 v126, 1.0, v156
	v_add_f32_e32 v127, 1.0, v157
	v_exp_f32_e32 v156, v122
	v_exp_f32_e32 v157, v123
	v_rcp_f32_e32 v126, v126
	v_rcp_f32_e32 v127, v127
	v_add_f32_e32 v156, 1.0, v156
	v_add_f32_e32 v157, 1.0, v157
	v_rcp_f32_e32 v156, v156
	v_rcp_f32_e32 v157, v157
	v_pk_mul_f32 v[120:121], v[120:121], v[126:127]
	v_pk_mul_f32 v[118:119], v[124:125], v[118:119]
	v_pk_mul_f32 v[120:121], v[120:121], v[112:113]
	v_pk_mul_f32 v[112:113], v[122:123], v[156:157]
	s_nop 0
	v_pk_mul_f32 v[122:123], v[112:113], v[114:115]
	v_cvt_pk_bf16_f32 v115, v118, v119
	v_exp_f32_e32 v118, v108
	v_exp_f32_e32 v119, v109
	v_lshlrev_b64 v[112:113], 1, v[154:155]
	v_lshl_add_u64 v[124:125], v[158:159], 0, v[112:113]
	v_cvt_pk_bf16_f32 v114, v116, v117
	v_cvt_pk_bf16_f32 v116, v120, v121
	v_cvt_pk_bf16_f32 v117, v122, v123
	global_store_dwordx4 v[124:125], v[114:117], off
	s_nop 1
	v_add_f32_e32 v114, 1.0, v118
	v_add_f32_e32 v115, 1.0, v119
	v_rcp_f32_e32 v114, v114
	v_rcp_f32_e32 v115, v115
	v_or_b32_e32 v116, 16, v153
	v_mad_i64_i32 v[116:117], s[0:1], v116, s63, v[144:145]
	v_pk_mul_f32 v[108:109], v[108:109], v[114:115]
	v_exp_f32_e32 v114, v110
	v_exp_f32_e32 v115, v111
	v_pk_mul_f32 v[100:101], v[108:109], v[100:101]
	v_add_f32_e32 v108, 1.0, v114
	v_add_f32_e32 v109, 1.0, v115
	v_rcp_f32_e32 v108, v108
	v_rcp_f32_e32 v109, v109
	v_exp_f32_e32 v114, v104
	v_exp_f32_e32 v115, v105
	v_pk_mul_f32 v[108:109], v[110:111], v[108:109]
	v_add_f32_e32 v110, 1.0, v114
	v_add_f32_e32 v111, 1.0, v115
	v_exp_f32_e32 v114, v106
	v_exp_f32_e32 v115, v107
	v_rcp_f32_e32 v110, v110
	v_rcp_f32_e32 v111, v111
	v_add_f32_e32 v114, 1.0, v114
	v_add_f32_e32 v115, 1.0, v115
	v_rcp_f32_e32 v114, v114
	v_rcp_f32_e32 v115, v115
	v_pk_mul_f32 v[104:105], v[104:105], v[110:111]
	v_pk_mul_f32 v[102:103], v[108:109], v[102:103]
	v_pk_mul_f32 v[104:105], v[104:105], v[96:97]
	v_pk_mul_f32 v[96:97], v[106:107], v[114:115]
	v_lshl_add_u64 v[108:109], v[116:117], 0, v[112:113]
	v_pk_mul_f32 v[106:107], v[96:97], v[98:99]
	v_cvt_pk_bf16_f32 v96, v100, v101
	v_exp_f32_e32 v100, v92
	v_exp_f32_e32 v101, v93
	v_cvt_pk_bf16_f32 v97, v102, v103
	v_cvt_pk_bf16_f32 v98, v104, v105
	v_cvt_pk_bf16_f32 v99, v106, v107
	global_store_dwordx4 v[108:109], v[96:99], off
	s_nop 1
	v_add_f32_e32 v96, 1.0, v100
	v_add_f32_e32 v97, 1.0, v101
	v_rcp_f32_e32 v96, v96
	v_rcp_f32_e32 v97, v97
	v_or_b32_e32 v98, 32, v153
	v_mad_i64_i32 v[98:99], s[0:1], v98, s63, v[144:145]
	v_pk_mul_f32 v[92:93], v[92:93], v[96:97]
	v_exp_f32_e32 v96, v94
	v_exp_f32_e32 v97, v95
	v_pk_mul_f32 v[84:85], v[92:93], v[84:85]
	v_add_f32_e32 v92, 1.0, v96
	v_add_f32_e32 v93, 1.0, v97
	v_rcp_f32_e32 v92, v92
	v_rcp_f32_e32 v93, v93
	v_exp_f32_e32 v96, v88
	v_exp_f32_e32 v97, v89
	v_pk_mul_f32 v[92:93], v[94:95], v[92:93]
	v_add_f32_e32 v94, 1.0, v96
	v_add_f32_e32 v95, 1.0, v97
	v_exp_f32_e32 v96, v90
	v_exp_f32_e32 v97, v91
	v_rcp_f32_e32 v94, v94
	v_rcp_f32_e32 v95, v95
	v_add_f32_e32 v96, 1.0, v96
	v_add_f32_e32 v97, 1.0, v97
	v_rcp_f32_e32 v96, v96
	v_rcp_f32_e32 v97, v97
	v_pk_mul_f32 v[88:89], v[88:89], v[94:95]
	v_pk_mul_f32 v[86:87], v[92:93], v[86:87]
	v_pk_mul_f32 v[88:89], v[88:89], v[80:81]
	v_pk_mul_f32 v[80:81], v[90:91], v[96:97]
	v_lshl_add_u64 v[92:93], v[98:99], 0, v[112:113]
	v_pk_mul_f32 v[90:91], v[80:81], v[82:83]
	v_cvt_pk_bf16_f32 v80, v84, v85
	v_exp_f32_e32 v84, v76
	v_exp_f32_e32 v85, v77
	v_cvt_pk_bf16_f32 v81, v86, v87
	v_cvt_pk_bf16_f32 v82, v88, v89
	v_cvt_pk_bf16_f32 v83, v90, v91
	global_store_dwordx4 v[92:93], v[80:83], off
	s_nop 1
	v_add_f32_e32 v80, 1.0, v84
	v_add_f32_e32 v81, 1.0, v85
	v_rcp_f32_e32 v80, v80
	v_rcp_f32_e32 v81, v81
	v_or_b32_e32 v82, 48, v153
	v_mad_i64_i32 v[82:83], s[0:1], v82, s63, v[144:145]
	v_pk_mul_f32 v[76:77], v[76:77], v[80:81]
	v_exp_f32_e32 v80, v78
	v_exp_f32_e32 v81, v79
	v_pk_mul_f32 v[68:69], v[76:77], v[68:69]
	v_add_f32_e32 v76, 1.0, v80
	v_add_f32_e32 v77, 1.0, v81
	v_rcp_f32_e32 v76, v76
	v_rcp_f32_e32 v77, v77
	v_exp_f32_e32 v80, v72
	v_exp_f32_e32 v81, v73
	v_pk_mul_f32 v[76:77], v[78:79], v[76:77]
	v_add_f32_e32 v78, 1.0, v80
	v_add_f32_e32 v79, 1.0, v81
	v_exp_f32_e32 v80, v74
	v_exp_f32_e32 v81, v75
	v_rcp_f32_e32 v78, v78
	v_rcp_f32_e32 v79, v79
	v_add_f32_e32 v80, 1.0, v80
	v_add_f32_e32 v81, 1.0, v81
	v_rcp_f32_e32 v80, v80
	v_rcp_f32_e32 v81, v81
	v_pk_mul_f32 v[72:73], v[72:73], v[78:79]
	v_pk_mul_f32 v[70:71], v[76:77], v[70:71]
	v_pk_mul_f32 v[72:73], v[72:73], v[64:65]
	v_pk_mul_f32 v[64:65], v[74:75], v[80:81]
	v_lshl_add_u64 v[76:77], v[82:83], 0, v[112:113]
	v_pk_mul_f32 v[74:75], v[64:65], v[66:67]
	v_cvt_pk_bf16_f32 v64, v68, v69
	v_exp_f32_e32 v68, v60
	v_exp_f32_e32 v69, v61
	v_cvt_pk_bf16_f32 v65, v70, v71
	v_cvt_pk_bf16_f32 v66, v72, v73
	v_cvt_pk_bf16_f32 v67, v74, v75
	global_store_dwordx4 v[76:77], v[64:67], off
	s_nop 1
	v_add_f32_e32 v64, 1.0, v68
	v_add_f32_e32 v65, 1.0, v69
	v_rcp_f32_e32 v64, v64
	v_rcp_f32_e32 v65, v65
	v_add_u32_e32 v66, 0x80, v153
	v_mad_i64_i32 v[66:67], s[0:1], v66, s63, v[144:145]
	v_pk_mul_f32 v[60:61], v[60:61], v[64:65]
	v_exp_f32_e32 v64, v62
	v_exp_f32_e32 v65, v63
	v_pk_mul_f32 v[52:53], v[60:61], v[52:53]
	v_add_f32_e32 v60, 1.0, v64
	v_add_f32_e32 v61, 1.0, v65
	v_rcp_f32_e32 v60, v60
	v_rcp_f32_e32 v61, v61
	v_exp_f32_e32 v64, v56
	v_exp_f32_e32 v65, v57
	v_pk_mul_f32 v[60:61], v[62:63], v[60:61]
	v_add_f32_e32 v62, 1.0, v64
	v_add_f32_e32 v63, 1.0, v65
	v_exp_f32_e32 v64, v58
	v_exp_f32_e32 v65, v59
	v_rcp_f32_e32 v62, v62
	v_rcp_f32_e32 v63, v63
	v_add_f32_e32 v64, 1.0, v64
	v_add_f32_e32 v65, 1.0, v65
	v_rcp_f32_e32 v64, v64
	v_rcp_f32_e32 v65, v65
	v_pk_mul_f32 v[56:57], v[56:57], v[62:63]
	v_pk_mul_f32 v[54:55], v[60:61], v[54:55]
	v_pk_mul_f32 v[56:57], v[56:57], v[48:49]
	v_pk_mul_f32 v[48:49], v[58:59], v[64:65]
	v_lshl_add_u64 v[60:61], v[66:67], 0, v[112:113]
	v_pk_mul_f32 v[58:59], v[48:49], v[50:51]
	v_cvt_pk_bf16_f32 v48, v52, v53
	v_exp_f32_e32 v52, v44
	v_exp_f32_e32 v53, v45
	v_cvt_pk_bf16_f32 v49, v54, v55
	v_cvt_pk_bf16_f32 v50, v56, v57
	v_cvt_pk_bf16_f32 v51, v58, v59
	global_store_dwordx4 v[60:61], v[48:51], off
	s_nop 1
	v_add_f32_e32 v48, 1.0, v52
	v_add_f32_e32 v49, 1.0, v53
	v_rcp_f32_e32 v48, v48
	v_rcp_f32_e32 v49, v49
	v_add_u32_e32 v50, 0x90, v153
	v_mad_i64_i32 v[50:51], s[0:1], v50, s63, v[144:145]
	v_pk_mul_f32 v[44:45], v[44:45], v[48:49]
	v_exp_f32_e32 v48, v46
	v_exp_f32_e32 v49, v47
	v_pk_mul_f32 v[36:37], v[44:45], v[36:37]
	v_add_f32_e32 v44, 1.0, v48
	v_add_f32_e32 v45, 1.0, v49
	v_rcp_f32_e32 v44, v44
	v_rcp_f32_e32 v45, v45
	v_exp_f32_e32 v48, v40
	v_exp_f32_e32 v49, v41
	v_pk_mul_f32 v[44:45], v[46:47], v[44:45]
	v_add_f32_e32 v46, 1.0, v48
	v_add_f32_e32 v47, 1.0, v49
	v_exp_f32_e32 v48, v42
	v_exp_f32_e32 v49, v43
	v_rcp_f32_e32 v46, v46
	v_rcp_f32_e32 v47, v47
	v_add_f32_e32 v48, 1.0, v48
	v_add_f32_e32 v49, 1.0, v49
	v_rcp_f32_e32 v48, v48
	v_rcp_f32_e32 v49, v49
	v_pk_mul_f32 v[40:41], v[40:41], v[46:47]
	v_pk_mul_f32 v[38:39], v[44:45], v[38:39]
	v_pk_mul_f32 v[40:41], v[40:41], v[32:33]
	v_pk_mul_f32 v[32:33], v[42:43], v[48:49]
	v_lshl_add_u64 v[44:45], v[50:51], 0, v[112:113]
	v_pk_mul_f32 v[42:43], v[32:33], v[34:35]
	v_cvt_pk_bf16_f32 v32, v36, v37
	v_exp_f32_e32 v36, v28
	v_exp_f32_e32 v37, v29
	v_cvt_pk_bf16_f32 v33, v38, v39
	v_cvt_pk_bf16_f32 v34, v40, v41
	v_cvt_pk_bf16_f32 v35, v42, v43
	global_store_dwordx4 v[44:45], v[32:35], off
	s_nop 1
	v_add_f32_e32 v32, 1.0, v36
	v_add_f32_e32 v33, 1.0, v37
	v_rcp_f32_e32 v32, v32
	v_rcp_f32_e32 v33, v33
	v_add_u32_e32 v34, 0xa0, v153
	v_mad_i64_i32 v[34:35], s[0:1], v34, s63, v[144:145]
	v_pk_mul_f32 v[28:29], v[28:29], v[32:33]
	v_exp_f32_e32 v32, v30
	v_exp_f32_e32 v33, v31
	v_pk_mul_f32 v[20:21], v[28:29], v[20:21]
	v_add_f32_e32 v28, 1.0, v32
	v_add_f32_e32 v29, 1.0, v33
	v_rcp_f32_e32 v28, v28
	v_rcp_f32_e32 v29, v29
	v_exp_f32_e32 v32, v24
	v_exp_f32_e32 v33, v25
	v_pk_mul_f32 v[28:29], v[30:31], v[28:29]
	v_add_f32_e32 v30, 1.0, v32
	v_add_f32_e32 v31, 1.0, v33
	v_exp_f32_e32 v32, v26
	v_exp_f32_e32 v33, v27
	v_rcp_f32_e32 v30, v30
	v_rcp_f32_e32 v31, v31
	v_add_f32_e32 v32, 1.0, v32
	v_add_f32_e32 v33, 1.0, v33
	v_rcp_f32_e32 v32, v32
	v_rcp_f32_e32 v33, v33
	v_pk_mul_f32 v[24:25], v[24:25], v[30:31]
	v_pk_mul_f32 v[22:23], v[28:29], v[22:23]
	v_pk_mul_f32 v[24:25], v[24:25], v[16:17]
	v_pk_mul_f32 v[16:17], v[26:27], v[32:33]
	v_lshl_add_u64 v[28:29], v[34:35], 0, v[112:113]
	v_pk_mul_f32 v[26:27], v[16:17], v[18:19]
	v_cvt_pk_bf16_f32 v16, v20, v21
	v_exp_f32_e32 v20, v12
	v_exp_f32_e32 v21, v13
	v_cvt_pk_bf16_f32 v17, v22, v23
	v_cvt_pk_bf16_f32 v18, v24, v25
	v_cvt_pk_bf16_f32 v19, v26, v27
	global_store_dwordx4 v[28:29], v[16:19], off
	s_nop 1
	v_add_f32_e32 v16, 1.0, v20
	v_add_f32_e32 v17, 1.0, v21
	v_rcp_f32_e32 v16, v16
	v_rcp_f32_e32 v17, v17
	v_add_u32_e32 v18, 0xb0, v153
	v_mad_i64_i32 v[18:19], s[0:1], v18, s63, v[144:145]
	v_pk_mul_f32 v[12:13], v[12:13], v[16:17]
	v_exp_f32_e32 v16, v14
	v_exp_f32_e32 v17, v15
	v_pk_mul_f32 v[4:5], v[12:13], v[4:5]
	s_mov_b64 s[0:1], -1
	v_add_f32_e32 v12, 1.0, v16
	v_add_f32_e32 v13, 1.0, v17
	v_rcp_f32_e32 v12, v12
	v_rcp_f32_e32 v13, v13
	v_exp_f32_e32 v16, v8
	v_exp_f32_e32 v17, v9
	v_pk_mul_f32 v[12:13], v[14:15], v[12:13]
	v_add_f32_e32 v14, 1.0, v16
	v_add_f32_e32 v15, 1.0, v17
	v_exp_f32_e32 v16, v10
	v_exp_f32_e32 v17, v11
	v_rcp_f32_e32 v14, v14
	v_rcp_f32_e32 v15, v15
	v_add_f32_e32 v16, 1.0, v16
	v_add_f32_e32 v17, 1.0, v17
	v_rcp_f32_e32 v16, v16
	v_rcp_f32_e32 v17, v17
	v_pk_mul_f32 v[8:9], v[8:9], v[14:15]
	v_pk_mul_f32 v[6:7], v[12:13], v[6:7]
	v_pk_mul_f32 v[8:9], v[8:9], v[0:1]
	v_pk_mul_f32 v[0:1], v[10:11], v[16:17]
	v_lshl_add_u64 v[12:13], v[18:19], 0, v[112:113]
	v_pk_mul_f32 v[10:11], v[0:1], v[2:3]
	v_cvt_pk_bf16_f32 v0, v4, v5
	v_cvt_pk_bf16_f32 v1, v6, v7
	v_cvt_pk_bf16_f32 v2, v8, v9
	v_cvt_pk_bf16_f32 v3, v10, v11
	global_store_dwordx4 v[12:13], v[0:3], off
	s_cbranch_vccnz .LBB0_964
	s_andn2_b64 vcc, exec, s[4:5]
	s_cbranch_vccnz .LBB0_963
	s_barrier
	s_branch .LBB0_963

.LBB0_1210:
	v_lshl_add_u32 v148, s18, 8, v151
	v_lshl_or_b32 v144, s19, 8, v153
	v_ashrrev_i32_e32 v149, 31, v148
	v_ashrrev_i32_e32 v145, 31, v144
	v_lshlrev_b64 v[146:147], 10, v[148:149]
	v_lshl_add_u64 v[158:159], v[146:147], 0, v[144:145]
	v_lshlrev_b64 v[162:163], 1, v[158:159]
	v_lshl_add_u64 v[158:159], s[36:37], 0, v[162:163]
	global_load_dwordx4 v[158:161], v[158:159], off
	v_exp_f32_e32 v126, v126
	v_exp_f32_e32 v127, v127
	v_exp_f32_e32 v120, v120
	v_exp_f32_e32 v121, v121
	v_add_f32_e32 v126, 1.0, v126
	v_add_f32_e32 v127, 1.0, v127
	v_rcp_f32_e32 v126, v126
	v_rcp_f32_e32 v127, v127
	v_add_f32_e32 v120, 1.0, v120
	v_add_f32_e32 v121, 1.0, v121
	v_rcp_f32_e32 v120, v120
	v_rcp_f32_e32 v121, v121
	v_exp_f32_e32 v124, v124
	v_exp_f32_e32 v125, v125
	v_add_f32_e32 v124, 1.0, v124
	v_add_f32_e32 v125, 1.0, v125
	v_rcp_f32_e32 v124, v124
	v_rcp_f32_e32 v125, v125
	v_exp_f32_e32 v118, v118
	v_exp_f32_e32 v119, v119
	v_exp_f32_e32 v112, v112
	v_exp_f32_e32 v113, v113
	v_add_f32_e32 v118, 1.0, v118
	v_add_f32_e32 v119, 1.0, v119
	v_rcp_f32_e32 v118, v118
	v_rcp_f32_e32 v119, v119
	v_add_f32_e32 v112, 1.0, v112
	v_add_f32_e32 v113, 1.0, v113
	v_rcp_f32_e32 v112, v112
	v_rcp_f32_e32 v113, v113
	v_exp_f32_e32 v116, v116
	v_exp_f32_e32 v117, v117
	v_add_f32_e32 v116, 1.0, v116
	v_add_f32_e32 v117, 1.0, v117
	v_rcp_f32_e32 v116, v116
	v_rcp_f32_e32 v117, v117
	v_exp_f32_e32 v110, v110
	v_exp_f32_e32 v111, v111
	v_exp_f32_e32 v104, v104
	v_exp_f32_e32 v105, v105
	v_add_f32_e32 v110, 1.0, v110
	v_add_f32_e32 v111, 1.0, v111
	v_rcp_f32_e32 v110, v110
	v_rcp_f32_e32 v111, v111
	v_add_f32_e32 v104, 1.0, v104
	v_add_f32_e32 v105, 1.0, v105
	v_rcp_f32_e32 v104, v104
	v_rcp_f32_e32 v105, v105
	v_exp_f32_e32 v108, v108
	v_exp_f32_e32 v109, v109
	v_add_f32_e32 v108, 1.0, v108
	v_add_f32_e32 v109, 1.0, v109
	v_rcp_f32_e32 v108, v108
	v_rcp_f32_e32 v109, v109
	v_exp_f32_e32 v102, v102
	v_exp_f32_e32 v103, v103
	v_exp_f32_e32 v96, v96
	s_waitcnt vmcnt(0)
	v_lshlrev_b32_e32 v164, 16, v158
	v_and_b32_e32 v165, 0xffff0000, v158
	v_lshlrev_b32_e32 v158, 16, v159
	v_and_b32_e32 v159, 0xffff0000, v159
	v_pk_mul_f32 v[126:127], v[126:127], v[158:159]
	v_lshlrev_b32_e32 v158, 16, v160
	v_and_b32_e32 v159, 0xffff0000, v160
	v_pk_mul_f32 v[158:159], v[120:121], v[158:159]
	v_exp_f32_e32 v120, v122
	v_exp_f32_e32 v121, v123
	v_lshlrev_b32_e32 v122, 16, v161
	v_and_b32_e32 v123, 0xffff0000, v161
	v_add_f32_e32 v120, 1.0, v120
	v_add_f32_e32 v121, 1.0, v121
	v_rcp_f32_e32 v120, v120
	v_rcp_f32_e32 v121, v121
	v_pk_mul_f32 v[124:125], v[124:125], v[164:165]
	v_exp_f32_e32 v97, v97
	v_add_f32_e32 v102, 1.0, v102
	v_pk_mul_f32 v[160:161], v[120:121], v[122:123]
	v_cvt_pk_bf16_f32 v120, v124, v125
	v_cvt_pk_bf16_f32 v121, v126, v127
	v_cvt_pk_bf16_f32 v122, v158, v159
	v_cvt_pk_bf16_f32 v123, v160, v161
	v_lshl_add_u64 v[124:125], s[40:41], 0, v[162:163]
	global_store_dwordx4 v[124:125], v[120:123], off
	v_add_f32_e32 v103, 1.0, v103
	v_rcp_f32_e32 v102, v102
	v_or_b32_e32 v120, 0x80, v144
	v_mov_b32_e32 v121, v145
	v_lshl_add_u64 v[122:123], v[146:147], 0, v[120:121]
	v_lshlrev_b64 v[122:123], 1, v[122:123]
	v_lshl_add_u64 v[124:125], s[36:37], 0, v[122:123]
	global_load_dwordx4 v[124:127], v[124:125], off
	v_rcp_f32_e32 v103, v103
	v_add_f32_e32 v96, 1.0, v96
	v_add_f32_e32 v97, 1.0, v97
	v_rcp_f32_e32 v96, v96
	v_rcp_f32_e32 v97, v97
	v_exp_f32_e32 v100, v100
	v_exp_f32_e32 v101, v101
	v_add_f32_e32 v100, 1.0, v100
	v_add_f32_e32 v101, 1.0, v101
	v_rcp_f32_e32 v100, v100
	v_rcp_f32_e32 v101, v101
	v_exp_f32_e32 v94, v94
	v_exp_f32_e32 v95, v95
	v_exp_f32_e32 v88, v88
	v_exp_f32_e32 v89, v89
	v_add_f32_e32 v94, 1.0, v94
	v_add_f32_e32 v95, 1.0, v95
	v_rcp_f32_e32 v94, v94
	v_rcp_f32_e32 v95, v95
	v_add_f32_e32 v88, 1.0, v88
	v_add_f32_e32 v89, 1.0, v89
	v_rcp_f32_e32 v88, v88
	v_rcp_f32_e32 v89, v89
	v_exp_f32_e32 v92, v92
	v_exp_f32_e32 v93, v93
	v_add_f32_e32 v92, 1.0, v92
	v_add_f32_e32 v93, 1.0, v93
	v_rcp_f32_e32 v92, v92
	v_rcp_f32_e32 v93, v93
	v_exp_f32_e32 v86, v86
	v_exp_f32_e32 v87, v87
	v_exp_f32_e32 v80, v80
	v_exp_f32_e32 v81, v81
	v_add_f32_e32 v86, 1.0, v86
	v_add_f32_e32 v87, 1.0, v87
	v_rcp_f32_e32 v86, v86
	v_rcp_f32_e32 v87, v87
	v_add_f32_e32 v80, 1.0, v80
	v_add_f32_e32 v81, 1.0, v81
	v_rcp_f32_e32 v80, v80
	v_rcp_f32_e32 v81, v81
	v_exp_f32_e32 v84, v84
	v_exp_f32_e32 v85, v85
	v_add_f32_e32 v84, 1.0, v84
	v_add_f32_e32 v85, 1.0, v85
	v_rcp_f32_e32 v84, v84
	v_rcp_f32_e32 v85, v85
	v_exp_f32_e32 v78, v78
	v_exp_f32_e32 v79, v79
	v_exp_f32_e32 v72, v72
	v_exp_f32_e32 v73, v73
	v_add_f32_e32 v78, 1.0, v78
	v_add_f32_e32 v79, 1.0, v79
	v_rcp_f32_e32 v78, v78
	v_rcp_f32_e32 v79, v79
	v_add_f32_e32 v72, 1.0, v72
	v_add_f32_e32 v73, 1.0, v73
	v_rcp_f32_e32 v72, v72
	v_rcp_f32_e32 v73, v73
	s_waitcnt vmcnt(0)
	v_lshlrev_b32_e32 v158, 16, v124
	v_and_b32_e32 v159, 0xffff0000, v124
	v_lshlrev_b32_e32 v124, 16, v125
	v_and_b32_e32 v125, 0xffff0000, v125
	v_pk_mul_f32 v[118:119], v[118:119], v[124:125]
	v_lshlrev_b32_e32 v124, 16, v126
	v_and_b32_e32 v125, 0xffff0000, v126
	v_pk_mul_f32 v[124:125], v[112:113], v[124:125]
	v_exp_f32_e32 v112, v114
	v_exp_f32_e32 v113, v115
	v_lshlrev_b32_e32 v114, 16, v127
	v_and_b32_e32 v115, 0xffff0000, v127
	v_add_f32_e32 v112, 1.0, v112
	v_add_f32_e32 v113, 1.0, v113
	v_rcp_f32_e32 v112, v112
	v_rcp_f32_e32 v113, v113
	v_pk_mul_f32 v[116:117], v[116:117], v[158:159]
	v_exp_f32_e32 v76, v76
	v_exp_f32_e32 v77, v77
	v_pk_mul_f32 v[126:127], v[112:113], v[114:115]
	v_cvt_pk_bf16_f32 v112, v116, v117
	v_cvt_pk_bf16_f32 v113, v118, v119
	v_cvt_pk_bf16_f32 v114, v124, v125
	v_cvt_pk_bf16_f32 v115, v126, v127
	v_lshl_add_u64 v[116:117], s[40:41], 0, v[122:123]
	global_store_dwordx4 v[116:117], v[112:115], off
	v_add_f32_e32 v76, 1.0, v76
	v_add_f32_e32 v77, 1.0, v77
	v_or_b32_e32 v112, 16, v148
	v_ashrrev_i32_e32 v113, 31, v112
	v_lshlrev_b64 v[112:113], 10, v[112:113]
	v_lshl_add_u64 v[114:115], v[112:113], 0, v[144:145]
	v_lshlrev_b64 v[114:115], 1, v[114:115]
	v_lshl_add_u64 v[116:117], s[36:37], 0, v[114:115]
	global_load_dwordx4 v[116:119], v[116:117], off
	v_rcp_f32_e32 v76, v76
	v_rcp_f32_e32 v77, v77
	v_exp_f32_e32 v70, v70
	v_exp_f32_e32 v71, v71
	v_exp_f32_e32 v64, v64
	v_exp_f32_e32 v65, v65
	v_add_f32_e32 v70, 1.0, v70
	v_add_f32_e32 v71, 1.0, v71
	v_rcp_f32_e32 v70, v70
	v_rcp_f32_e32 v71, v71
	v_add_f32_e32 v64, 1.0, v64
	v_add_f32_e32 v65, 1.0, v65
	v_rcp_f32_e32 v64, v64
	v_rcp_f32_e32 v65, v65
	v_exp_f32_e32 v68, v68
	v_exp_f32_e32 v69, v69
	s_mov_b64 s[0:1], 0x20000
	v_add_f32_e32 v68, 1.0, v68
	v_add_f32_e32 v69, 1.0, v69
	v_rcp_f32_e32 v68, v68
	v_rcp_f32_e32 v69, v69
	v_exp_f32_e32 v62, v62
	v_exp_f32_e32 v63, v63
	v_exp_f32_e32 v56, v56
	v_exp_f32_e32 v57, v57
	v_add_f32_e32 v62, 1.0, v62
	v_add_f32_e32 v63, 1.0, v63
	v_rcp_f32_e32 v62, v62
	v_rcp_f32_e32 v63, v63
	v_add_f32_e32 v56, 1.0, v56
	v_add_f32_e32 v57, 1.0, v57
	v_rcp_f32_e32 v56, v56
	v_rcp_f32_e32 v57, v57
	v_exp_f32_e32 v60, v60
	v_exp_f32_e32 v61, v61
	v_add_f32_e32 v60, 1.0, v60
	v_add_f32_e32 v61, 1.0, v61
	v_rcp_f32_e32 v60, v60
	v_rcp_f32_e32 v61, v61
	v_exp_f32_e32 v54, v54
	v_exp_f32_e32 v55, v55
	v_exp_f32_e32 v48, v48
	v_exp_f32_e32 v49, v49
	v_add_f32_e32 v54, 1.0, v54
	v_add_f32_e32 v55, 1.0, v55
	v_rcp_f32_e32 v54, v54
	v_rcp_f32_e32 v55, v55
	v_add_f32_e32 v48, 1.0, v48
	v_add_f32_e32 v49, 1.0, v49
	v_rcp_f32_e32 v48, v48
	v_rcp_f32_e32 v49, v49
	v_exp_f32_e32 v52, v52
	v_exp_f32_e32 v53, v53
	v_add_f32_e32 v52, 1.0, v52
	v_add_f32_e32 v53, 1.0, v53
	v_rcp_f32_e32 v52, v52
	v_rcp_f32_e32 v53, v53
	v_exp_f32_e32 v46, v46
	v_exp_f32_e32 v47, v47
	s_waitcnt vmcnt(0)
	v_lshlrev_b32_e32 v122, 16, v116
	v_and_b32_e32 v123, 0xffff0000, v116
	v_lshlrev_b32_e32 v116, 16, v117
	v_and_b32_e32 v117, 0xffff0000, v117
	v_pk_mul_f32 v[110:111], v[110:111], v[116:117]
	v_lshlrev_b32_e32 v116, 16, v118
	v_and_b32_e32 v117, 0xffff0000, v118
	v_pk_mul_f32 v[116:117], v[104:105], v[116:117]
	v_exp_f32_e32 v104, v106
	v_exp_f32_e32 v105, v107
	v_lshlrev_b32_e32 v106, 16, v119
	v_and_b32_e32 v107, 0xffff0000, v119
	v_add_f32_e32 v104, 1.0, v104
	v_add_f32_e32 v105, 1.0, v105
	v_rcp_f32_e32 v104, v104
	v_rcp_f32_e32 v105, v105
	v_pk_mul_f32 v[108:109], v[108:109], v[122:123]
	v_pk_mul_f32 v[118:119], v[104:105], v[106:107]
	v_cvt_pk_bf16_f32 v104, v108, v109
	v_cvt_pk_bf16_f32 v105, v110, v111
	v_cvt_pk_bf16_f32 v106, v116, v117
	v_cvt_pk_bf16_f32 v107, v118, v119
	v_lshl_add_u64 v[108:109], s[40:41], 0, v[114:115]
	global_store_dwordx4 v[108:109], v[104:107], off
	v_exp_f32_e32 v40, v40
	v_exp_f32_e32 v41, v41
	v_lshl_add_u64 v[104:105], v[112:113], 0, v[120:121]
	v_lshlrev_b64 v[104:105], 1, v[104:105]
	v_lshl_add_u64 v[106:107], s[36:37], 0, v[104:105]
	global_load_dwordx4 v[106:109], v[106:107], off
	v_add_f32_e32 v46, 1.0, v46
	v_add_f32_e32 v47, 1.0, v47
	v_rcp_f32_e32 v46, v46
	v_rcp_f32_e32 v47, v47
	v_add_f32_e32 v40, 1.0, v40
	v_add_f32_e32 v41, 1.0, v41
	v_rcp_f32_e32 v40, v40
	v_rcp_f32_e32 v41, v41
	v_exp_f32_e32 v44, v44
	v_exp_f32_e32 v45, v45
	v_add_f32_e32 v44, 1.0, v44
	v_add_f32_e32 v45, 1.0, v45
	v_rcp_f32_e32 v44, v44
	v_rcp_f32_e32 v45, v45
	v_exp_f32_e32 v38, v38
	v_exp_f32_e32 v39, v39
	v_exp_f32_e32 v32, v32
	v_exp_f32_e32 v33, v33
	v_add_f32_e32 v38, 1.0, v38
	v_add_f32_e32 v39, 1.0, v39
	v_rcp_f32_e32 v38, v38
	v_rcp_f32_e32 v39, v39
	v_add_f32_e32 v32, 1.0, v32
	v_add_f32_e32 v33, 1.0, v33
	v_rcp_f32_e32 v32, v32
	v_rcp_f32_e32 v33, v33
	v_exp_f32_e32 v36, v36
	v_exp_f32_e32 v37, v37
	v_add_f32_e32 v36, 1.0, v36
	v_add_f32_e32 v37, 1.0, v37
	v_rcp_f32_e32 v36, v36
	v_rcp_f32_e32 v37, v37
	v_exp_f32_e32 v30, v30
	v_exp_f32_e32 v31, v31
	v_exp_f32_e32 v24, v24
	v_exp_f32_e32 v25, v25
	v_add_f32_e32 v30, 1.0, v30
	v_add_f32_e32 v31, 1.0, v31
	v_rcp_f32_e32 v30, v30
	v_rcp_f32_e32 v31, v31
	v_add_f32_e32 v24, 1.0, v24
	v_add_f32_e32 v25, 1.0, v25
	v_rcp_f32_e32 v24, v24
	v_rcp_f32_e32 v25, v25
	v_exp_f32_e32 v28, v28
	v_exp_f32_e32 v29, v29
	v_add_f32_e32 v28, 1.0, v28
	v_add_f32_e32 v29, 1.0, v29
	v_rcp_f32_e32 v28, v28
	v_rcp_f32_e32 v29, v29
	v_exp_f32_e32 v22, v22
	v_exp_f32_e32 v23, v23
	v_exp_f32_e32 v16, v16
	v_exp_f32_e32 v17, v17
	v_add_f32_e32 v22, 1.0, v22
	v_add_f32_e32 v23, 1.0, v23
	v_rcp_f32_e32 v22, v22
	v_rcp_f32_e32 v23, v23
	v_add_f32_e32 v16, 1.0, v16
	v_add_f32_e32 v17, 1.0, v17
	v_rcp_f32_e32 v16, v16
	s_waitcnt vmcnt(0)
	v_lshlrev_b32_e32 v110, 16, v106
	v_and_b32_e32 v111, 0xffff0000, v106
	v_lshlrev_b32_e32 v106, 16, v107
	v_and_b32_e32 v107, 0xffff0000, v107
	v_pk_mul_f32 v[102:103], v[102:103], v[106:107]
	v_lshlrev_b32_e32 v106, 16, v108
	v_and_b32_e32 v107, 0xffff0000, v108
	v_pk_mul_f32 v[106:107], v[96:97], v[106:107]
	v_exp_f32_e32 v96, v98
	v_exp_f32_e32 v97, v99
	v_lshlrev_b32_e32 v98, 16, v109
	v_and_b32_e32 v99, 0xffff0000, v109
	v_add_f32_e32 v96, 1.0, v96
	v_add_f32_e32 v97, 1.0, v97
	v_rcp_f32_e32 v96, v96
	v_rcp_f32_e32 v97, v97
	v_pk_mul_f32 v[100:101], v[100:101], v[110:111]
	v_rcp_f32_e32 v17, v17
	v_pk_mul_f32 v[108:109], v[96:97], v[98:99]
	v_cvt_pk_bf16_f32 v96, v100, v101
	v_cvt_pk_bf16_f32 v97, v102, v103
	v_cvt_pk_bf16_f32 v98, v106, v107
	v_cvt_pk_bf16_f32 v99, v108, v109
	v_lshl_add_u64 v[100:101], s[40:41], 0, v[104:105]
	global_store_dwordx4 v[100:101], v[96:99], off
	v_exp_f32_e32 v20, v20
	v_or_b32_e32 v96, 32, v148
	v_ashrrev_i32_e32 v97, 31, v96
	v_lshlrev_b64 v[96:97], 10, v[96:97]
	v_lshl_add_u64 v[98:99], v[96:97], 0, v[144:145]
	v_lshlrev_b64 v[98:99], 1, v[98:99]
	v_lshl_add_u64 v[100:101], s[36:37], 0, v[98:99]
	global_load_dwordx4 v[100:103], v[100:101], off
	v_exp_f32_e32 v21, v21
	v_add_f32_e32 v20, 1.0, v20
	v_rcp_f32_e32 v20, v20
	v_add_f32_e32 v21, 1.0, v21
	v_rcp_f32_e32 v21, v21
	v_exp_f32_e32 v14, v14
	v_exp_f32_e32 v15, v15
	v_exp_f32_e32 v8, v8
	v_exp_f32_e32 v9, v9
	v_add_f32_e32 v14, 1.0, v14
	v_add_f32_e32 v15, 1.0, v15
	v_rcp_f32_e32 v14, v14
	v_rcp_f32_e32 v15, v15
	v_add_f32_e32 v8, 1.0, v8
	v_add_f32_e32 v9, 1.0, v9
	v_rcp_f32_e32 v8, v8
	v_rcp_f32_e32 v9, v9
	v_exp_f32_e32 v12, v12
	v_exp_f32_e32 v13, v13
	v_add_f32_e32 v12, 1.0, v12
	v_add_f32_e32 v13, 1.0, v13
	v_rcp_f32_e32 v12, v12
	v_rcp_f32_e32 v13, v13
	v_exp_f32_e32 v6, v6
	v_exp_f32_e32 v7, v7
	v_exp_f32_e32 v0, v0
	v_exp_f32_e32 v1, v1
	v_add_f32_e32 v6, 1.0, v6
	v_add_f32_e32 v7, 1.0, v7
	v_rcp_f32_e32 v6, v6
	v_rcp_f32_e32 v7, v7
	v_add_f32_e32 v0, 1.0, v0
	v_add_f32_e32 v1, 1.0, v1
	v_rcp_f32_e32 v0, v0
	v_rcp_f32_e32 v1, v1
	v_exp_f32_e32 v4, v4
	v_exp_f32_e32 v5, v5
	s_mov_b64 s[18:19], -1
	s_andn2_b64 vcc, exec, s[2:3]
	v_add_f32_e32 v4, 1.0, v4
	v_add_f32_e32 v5, 1.0, v5
	v_rcp_f32_e32 v4, v4
	v_rcp_f32_e32 v5, v5
	s_waitcnt vmcnt(0)
	v_lshlrev_b32_e32 v104, 16, v100
	v_and_b32_e32 v105, 0xffff0000, v100
	v_lshlrev_b32_e32 v100, 16, v101
	v_and_b32_e32 v101, 0xffff0000, v101
	v_pk_mul_f32 v[94:95], v[94:95], v[100:101]
	v_lshlrev_b32_e32 v100, 16, v102
	v_and_b32_e32 v101, 0xffff0000, v102
	v_pk_mul_f32 v[100:101], v[88:89], v[100:101]
	v_exp_f32_e32 v88, v90
	v_exp_f32_e32 v89, v91
	v_lshlrev_b32_e32 v90, 16, v103
	v_and_b32_e32 v91, 0xffff0000, v103
	v_add_f32_e32 v88, 1.0, v88
	v_add_f32_e32 v89, 1.0, v89
	v_rcp_f32_e32 v88, v88
	v_rcp_f32_e32 v89, v89
	v_pk_mul_f32 v[92:93], v[92:93], v[104:105]
	v_pk_mul_f32 v[102:103], v[88:89], v[90:91]
	v_cvt_pk_bf16_f32 v88, v92, v93
	v_cvt_pk_bf16_f32 v89, v94, v95
	v_cvt_pk_bf16_f32 v90, v100, v101
	v_cvt_pk_bf16_f32 v91, v102, v103
	v_lshl_add_u64 v[92:93], s[40:41], 0, v[98:99]
	global_store_dwordx4 v[92:93], v[88:91], off
	s_nop 1
	v_lshl_add_u64 v[88:89], v[96:97], 0, v[120:121]
	v_lshlrev_b64 v[88:89], 1, v[88:89]
	v_lshl_add_u64 v[90:91], s[36:37], 0, v[88:89]
	global_load_dwordx4 v[90:93], v[90:91], off
	s_waitcnt vmcnt(0)
	v_lshlrev_b32_e32 v94, 16, v90
	v_and_b32_e32 v95, 0xffff0000, v90
	v_lshlrev_b32_e32 v90, 16, v91
	v_and_b32_e32 v91, 0xffff0000, v91
	v_pk_mul_f32 v[86:87], v[86:87], v[90:91]
	v_lshlrev_b32_e32 v90, 16, v92
	v_and_b32_e32 v91, 0xffff0000, v92
	v_pk_mul_f32 v[90:91], v[80:81], v[90:91]
	v_exp_f32_e32 v80, v82
	v_exp_f32_e32 v81, v83
	v_lshlrev_b32_e32 v82, 16, v93
	v_and_b32_e32 v83, 0xffff0000, v93
	v_add_f32_e32 v80, 1.0, v80
	v_add_f32_e32 v81, 1.0, v81
	v_rcp_f32_e32 v80, v80
	v_rcp_f32_e32 v81, v81
	v_pk_mul_f32 v[84:85], v[84:85], v[94:95]
	v_pk_mul_f32 v[92:93], v[80:81], v[82:83]
	v_cvt_pk_bf16_f32 v80, v84, v85
	v_cvt_pk_bf16_f32 v81, v86, v87
	v_cvt_pk_bf16_f32 v82, v90, v91
	v_cvt_pk_bf16_f32 v83, v92, v93
	v_lshl_add_u64 v[84:85], s[40:41], 0, v[88:89]
	global_store_dwordx4 v[84:85], v[80:83], off
	s_nop 1
	v_or_b32_e32 v80, 48, v148
	v_ashrrev_i32_e32 v81, 31, v80
	v_lshlrev_b64 v[80:81], 10, v[80:81]
	v_lshl_add_u64 v[82:83], v[80:81], 0, v[144:145]
	v_lshlrev_b64 v[82:83], 1, v[82:83]
	v_lshl_add_u64 v[84:85], s[36:37], 0, v[82:83]
	global_load_dwordx4 v[84:87], v[84:85], off
	s_waitcnt vmcnt(0)
	v_lshlrev_b32_e32 v88, 16, v84
	v_and_b32_e32 v89, 0xffff0000, v84
	v_lshlrev_b32_e32 v84, 16, v85
	v_and_b32_e32 v85, 0xffff0000, v85
	v_pk_mul_f32 v[78:79], v[78:79], v[84:85]
	v_lshlrev_b32_e32 v84, 16, v86
	v_and_b32_e32 v85, 0xffff0000, v86
	v_pk_mul_f32 v[84:85], v[72:73], v[84:85]
	v_exp_f32_e32 v72, v74
	v_exp_f32_e32 v73, v75
	v_lshlrev_b32_e32 v74, 16, v87
	v_and_b32_e32 v75, 0xffff0000, v87
	v_add_f32_e32 v72, 1.0, v72
	v_add_f32_e32 v73, 1.0, v73
	v_rcp_f32_e32 v72, v72
	v_rcp_f32_e32 v73, v73
	v_pk_mul_f32 v[76:77], v[76:77], v[88:89]
	v_pk_mul_f32 v[86:87], v[72:73], v[74:75]
	v_cvt_pk_bf16_f32 v72, v76, v77
	v_cvt_pk_bf16_f32 v73, v78, v79
	v_cvt_pk_bf16_f32 v74, v84, v85
	v_cvt_pk_bf16_f32 v75, v86, v87
	v_lshl_add_u64 v[76:77], s[40:41], 0, v[82:83]
	global_store_dwordx4 v[76:77], v[72:75], off
	s_nop 1
	v_lshl_add_u64 v[72:73], v[80:81], 0, v[120:121]
	v_lshlrev_b64 v[72:73], 1, v[72:73]
	v_lshl_add_u64 v[74:75], s[36:37], 0, v[72:73]
	global_load_dwordx4 v[74:77], v[74:75], off
	s_waitcnt vmcnt(0)
	v_lshlrev_b32_e32 v78, 16, v74
	v_and_b32_e32 v79, 0xffff0000, v74
	v_lshlrev_b32_e32 v74, 16, v75
	v_and_b32_e32 v75, 0xffff0000, v75
	v_pk_mul_f32 v[70:71], v[70:71], v[74:75]
	v_lshlrev_b32_e32 v74, 16, v76
	v_and_b32_e32 v75, 0xffff0000, v76
	v_pk_mul_f32 v[74:75], v[64:65], v[74:75]
	v_exp_f32_e32 v64, v66
	v_exp_f32_e32 v65, v67
	v_lshlrev_b32_e32 v66, 16, v77
	v_and_b32_e32 v67, 0xffff0000, v77
	v_add_f32_e32 v64, 1.0, v64
	v_add_f32_e32 v65, 1.0, v65
	v_rcp_f32_e32 v64, v64
	v_rcp_f32_e32 v65, v65
	v_pk_mul_f32 v[68:69], v[68:69], v[78:79]
	v_pk_mul_f32 v[76:77], v[64:65], v[66:67]
	v_cvt_pk_bf16_f32 v64, v68, v69
	v_cvt_pk_bf16_f32 v65, v70, v71
	v_cvt_pk_bf16_f32 v66, v74, v75
	v_cvt_pk_bf16_f32 v67, v76, v77
	v_lshl_add_u64 v[68:69], s[40:41], 0, v[72:73]
	global_store_dwordx4 v[68:69], v[64:67], off
	s_nop 1
	v_lshl_add_u64 v[64:65], v[146:147], 0, s[0:1]
	v_lshl_add_u64 v[66:67], v[64:65], 0, v[144:145]
	v_lshlrev_b64 v[66:67], 1, v[66:67]
	v_lshl_add_u64 v[68:69], s[36:37], 0, v[66:67]
	global_load_dwordx4 v[68:71], v[68:69], off
	s_mov_b64 s[0:1], 0x24000
	s_waitcnt vmcnt(0)
	v_lshlrev_b32_e32 v72, 16, v68
	v_and_b32_e32 v73, 0xffff0000, v68
	v_lshlrev_b32_e32 v68, 16, v69
	v_and_b32_e32 v69, 0xffff0000, v69
	v_pk_mul_f32 v[62:63], v[62:63], v[68:69]
	v_lshlrev_b32_e32 v68, 16, v70
	v_and_b32_e32 v69, 0xffff0000, v70
	v_pk_mul_f32 v[68:69], v[56:57], v[68:69]
	v_exp_f32_e32 v56, v58
	v_exp_f32_e32 v57, v59
	v_lshlrev_b32_e32 v58, 16, v71
	v_and_b32_e32 v59, 0xffff0000, v71
	v_add_f32_e32 v56, 1.0, v56
	v_add_f32_e32 v57, 1.0, v57
	v_rcp_f32_e32 v56, v56
	v_rcp_f32_e32 v57, v57
	v_pk_mul_f32 v[60:61], v[60:61], v[72:73]
	v_pk_mul_f32 v[70:71], v[56:57], v[58:59]
	v_cvt_pk_bf16_f32 v56, v60, v61
	v_cvt_pk_bf16_f32 v57, v62, v63
	v_cvt_pk_bf16_f32 v58, v68, v69
	v_cvt_pk_bf16_f32 v59, v70, v71
	v_lshl_add_u64 v[60:61], s[40:41], 0, v[66:67]
	global_store_dwordx4 v[60:61], v[56:59], off
	s_nop 1
	v_lshl_add_u64 v[56:57], v[64:65], 0, v[120:121]
	v_lshlrev_b64 v[56:57], 1, v[56:57]
	v_lshl_add_u64 v[58:59], s[36:37], 0, v[56:57]
	global_load_dwordx4 v[58:61], v[58:59], off
	s_waitcnt vmcnt(0)
	v_lshlrev_b32_e32 v62, 16, v58
	v_and_b32_e32 v63, 0xffff0000, v58
	v_lshlrev_b32_e32 v58, 16, v59
	v_and_b32_e32 v59, 0xffff0000, v59
	v_pk_mul_f32 v[54:55], v[54:55], v[58:59]
	v_lshlrev_b32_e32 v58, 16, v60
	v_and_b32_e32 v59, 0xffff0000, v60
	v_pk_mul_f32 v[58:59], v[48:49], v[58:59]
	v_exp_f32_e32 v48, v50
	v_exp_f32_e32 v49, v51
	v_lshlrev_b32_e32 v50, 16, v61
	v_and_b32_e32 v51, 0xffff0000, v61
	v_add_f32_e32 v48, 1.0, v48
	v_add_f32_e32 v49, 1.0, v49
	v_rcp_f32_e32 v48, v48
	v_rcp_f32_e32 v49, v49
	v_pk_mul_f32 v[52:53], v[52:53], v[62:63]
	v_pk_mul_f32 v[60:61], v[48:49], v[50:51]
	v_cvt_pk_bf16_f32 v48, v52, v53
	v_cvt_pk_bf16_f32 v49, v54, v55
	v_cvt_pk_bf16_f32 v50, v58, v59
	v_cvt_pk_bf16_f32 v51, v60, v61
	v_lshl_add_u64 v[52:53], s[40:41], 0, v[56:57]
	global_store_dwordx4 v[52:53], v[48:51], off
	s_nop 1
	v_lshl_add_u64 v[48:49], v[146:147], 0, s[0:1]
	v_lshl_add_u64 v[50:51], v[48:49], 0, v[144:145]
	v_lshlrev_b64 v[50:51], 1, v[50:51]
	v_lshl_add_u64 v[52:53], s[36:37], 0, v[50:51]
	global_load_dwordx4 v[52:55], v[52:53], off
	s_mov_b64 s[0:1], 0x28000
	s_waitcnt vmcnt(0)
	v_lshlrev_b32_e32 v56, 16, v52
	v_and_b32_e32 v57, 0xffff0000, v52
	v_lshlrev_b32_e32 v52, 16, v53
	v_and_b32_e32 v53, 0xffff0000, v53
	v_pk_mul_f32 v[46:47], v[46:47], v[52:53]
	v_lshlrev_b32_e32 v52, 16, v54
	v_and_b32_e32 v53, 0xffff0000, v54
	v_pk_mul_f32 v[52:53], v[40:41], v[52:53]
	v_exp_f32_e32 v40, v42
	v_exp_f32_e32 v41, v43
	v_lshlrev_b32_e32 v42, 16, v55
	v_and_b32_e32 v43, 0xffff0000, v55
	v_add_f32_e32 v40, 1.0, v40
	v_add_f32_e32 v41, 1.0, v41
	v_rcp_f32_e32 v40, v40
	v_rcp_f32_e32 v41, v41
	v_pk_mul_f32 v[44:45], v[44:45], v[56:57]
	v_pk_mul_f32 v[54:55], v[40:41], v[42:43]
	v_cvt_pk_bf16_f32 v40, v44, v45
	v_cvt_pk_bf16_f32 v41, v46, v47
	v_cvt_pk_bf16_f32 v42, v52, v53
	v_cvt_pk_bf16_f32 v43, v54, v55
	v_lshl_add_u64 v[44:45], s[40:41], 0, v[50:51]
	global_store_dwordx4 v[44:45], v[40:43], off
	s_nop 1
	v_lshl_add_u64 v[40:41], v[48:49], 0, v[120:121]
	v_lshlrev_b64 v[40:41], 1, v[40:41]
	v_lshl_add_u64 v[42:43], s[36:37], 0, v[40:41]
	global_load_dwordx4 v[42:45], v[42:43], off
	s_waitcnt vmcnt(0)
	v_lshlrev_b32_e32 v46, 16, v42
	v_and_b32_e32 v47, 0xffff0000, v42
	v_lshlrev_b32_e32 v42, 16, v43
	v_and_b32_e32 v43, 0xffff0000, v43
	v_pk_mul_f32 v[38:39], v[38:39], v[42:43]
	v_lshlrev_b32_e32 v42, 16, v44
	v_and_b32_e32 v43, 0xffff0000, v44
	v_pk_mul_f32 v[42:43], v[32:33], v[42:43]
	v_exp_f32_e32 v32, v34
	v_exp_f32_e32 v33, v35
	v_lshlrev_b32_e32 v34, 16, v45
	v_and_b32_e32 v35, 0xffff0000, v45
	v_add_f32_e32 v32, 1.0, v32
	v_add_f32_e32 v33, 1.0, v33
	v_rcp_f32_e32 v32, v32
	v_rcp_f32_e32 v33, v33
	v_pk_mul_f32 v[36:37], v[36:37], v[46:47]
	v_pk_mul_f32 v[44:45], v[32:33], v[34:35]
	v_cvt_pk_bf16_f32 v32, v36, v37
	v_cvt_pk_bf16_f32 v33, v38, v39
	v_cvt_pk_bf16_f32 v34, v42, v43
	v_cvt_pk_bf16_f32 v35, v44, v45
	v_lshl_add_u64 v[36:37], s[40:41], 0, v[40:41]
	global_store_dwordx4 v[36:37], v[32:35], off
	s_nop 1
	v_lshl_add_u64 v[32:33], v[146:147], 0, s[0:1]
	v_lshl_add_u64 v[34:35], v[32:33], 0, v[144:145]
	v_lshlrev_b64 v[34:35], 1, v[34:35]
	v_lshl_add_u64 v[36:37], s[36:37], 0, v[34:35]
	global_load_dwordx4 v[36:39], v[36:37], off
	s_mov_b64 s[0:1], 0x2c000
	s_waitcnt vmcnt(0)
	v_lshlrev_b32_e32 v40, 16, v36
	v_and_b32_e32 v41, 0xffff0000, v36
	v_lshlrev_b32_e32 v36, 16, v37
	v_and_b32_e32 v37, 0xffff0000, v37
	v_pk_mul_f32 v[30:31], v[30:31], v[36:37]
	v_lshlrev_b32_e32 v36, 16, v38
	v_and_b32_e32 v37, 0xffff0000, v38
	v_pk_mul_f32 v[36:37], v[24:25], v[36:37]
	v_exp_f32_e32 v24, v26
	v_exp_f32_e32 v25, v27
	v_lshlrev_b32_e32 v26, 16, v39
	v_and_b32_e32 v27, 0xffff0000, v39
	v_add_f32_e32 v24, 1.0, v24
	v_add_f32_e32 v25, 1.0, v25
	v_rcp_f32_e32 v24, v24
	v_rcp_f32_e32 v25, v25
	v_pk_mul_f32 v[28:29], v[28:29], v[40:41]
	v_pk_mul_f32 v[38:39], v[24:25], v[26:27]
	v_cvt_pk_bf16_f32 v24, v28, v29
	v_cvt_pk_bf16_f32 v25, v30, v31
	v_cvt_pk_bf16_f32 v26, v36, v37
	v_cvt_pk_bf16_f32 v27, v38, v39
	v_lshl_add_u64 v[28:29], s[40:41], 0, v[34:35]
	global_store_dwordx4 v[28:29], v[24:27], off
	s_nop 1
	v_lshl_add_u64 v[24:25], v[32:33], 0, v[120:121]
	v_lshlrev_b64 v[24:25], 1, v[24:25]
	v_lshl_add_u64 v[26:27], s[36:37], 0, v[24:25]
	global_load_dwordx4 v[26:29], v[26:27], off
	s_waitcnt vmcnt(0)
	v_lshlrev_b32_e32 v30, 16, v26
	v_and_b32_e32 v31, 0xffff0000, v26
	v_lshlrev_b32_e32 v26, 16, v27
	v_and_b32_e32 v27, 0xffff0000, v27
	v_pk_mul_f32 v[22:23], v[22:23], v[26:27]
	v_lshlrev_b32_e32 v26, 16, v28
	v_and_b32_e32 v27, 0xffff0000, v28
	v_pk_mul_f32 v[26:27], v[16:17], v[26:27]
	v_exp_f32_e32 v16, v18
	v_exp_f32_e32 v17, v19
	v_lshlrev_b32_e32 v18, 16, v29
	v_and_b32_e32 v19, 0xffff0000, v29
	v_add_f32_e32 v16, 1.0, v16
	v_add_f32_e32 v17, 1.0, v17
	v_rcp_f32_e32 v16, v16
	v_rcp_f32_e32 v17, v17
	v_pk_mul_f32 v[20:21], v[20:21], v[30:31]
	v_pk_mul_f32 v[28:29], v[16:17], v[18:19]
	v_cvt_pk_bf16_f32 v16, v20, v21
	v_cvt_pk_bf16_f32 v17, v22, v23
	v_cvt_pk_bf16_f32 v18, v26, v27
	v_cvt_pk_bf16_f32 v19, v28, v29
	v_lshl_add_u64 v[20:21], s[40:41], 0, v[24:25]
	global_store_dwordx4 v[20:21], v[16:19], off
	s_nop 1
	v_lshl_add_u64 v[16:17], v[146:147], 0, s[0:1]
	v_lshl_add_u64 v[18:19], v[16:17], 0, v[144:145]
	v_lshlrev_b64 v[18:19], 1, v[18:19]
	v_lshl_add_u64 v[20:21], s[36:37], 0, v[18:19]
	global_load_dwordx4 v[20:23], v[20:21], off
	s_waitcnt vmcnt(0)
	v_lshlrev_b32_e32 v24, 16, v20
	v_and_b32_e32 v25, 0xffff0000, v20
	v_lshlrev_b32_e32 v20, 16, v21
	v_and_b32_e32 v21, 0xffff0000, v21
	v_pk_mul_f32 v[14:15], v[14:15], v[20:21]
	v_lshlrev_b32_e32 v20, 16, v22
	v_and_b32_e32 v21, 0xffff0000, v22
	v_pk_mul_f32 v[20:21], v[8:9], v[20:21]
	v_exp_f32_e32 v8, v10
	v_exp_f32_e32 v9, v11
	v_lshlrev_b32_e32 v10, 16, v23
	v_and_b32_e32 v11, 0xffff0000, v23
	v_add_f32_e32 v8, 1.0, v8
	v_add_f32_e32 v9, 1.0, v9
	v_rcp_f32_e32 v8, v8
	v_rcp_f32_e32 v9, v9
	v_pk_mul_f32 v[12:13], v[12:13], v[24:25]
	v_pk_mul_f32 v[22:23], v[8:9], v[10:11]
	v_cvt_pk_bf16_f32 v8, v12, v13
	v_cvt_pk_bf16_f32 v9, v14, v15
	v_cvt_pk_bf16_f32 v10, v20, v21
	v_cvt_pk_bf16_f32 v11, v22, v23
	v_lshl_add_u64 v[12:13], s[40:41], 0, v[18:19]
	global_store_dwordx4 v[12:13], v[8:11], off
	s_nop 1
	v_lshl_add_u64 v[8:9], v[16:17], 0, v[120:121]
	v_lshlrev_b64 v[8:9], 1, v[8:9]
	v_lshl_add_u64 v[10:11], s[36:37], 0, v[8:9]
	global_load_dwordx4 v[10:13], v[10:11], off
	s_waitcnt vmcnt(0)
	v_lshlrev_b32_e32 v14, 16, v10
	v_and_b32_e32 v15, 0xffff0000, v10
	v_lshlrev_b32_e32 v10, 16, v11
	v_and_b32_e32 v11, 0xffff0000, v11
	v_pk_mul_f32 v[6:7], v[6:7], v[10:11]
	v_lshlrev_b32_e32 v10, 16, v12
	v_and_b32_e32 v11, 0xffff0000, v12
	v_pk_mul_f32 v[10:11], v[0:1], v[10:11]
	v_exp_f32_e32 v0, v2
	v_exp_f32_e32 v1, v3
	v_lshlrev_b32_e32 v2, 16, v13
	v_and_b32_e32 v3, 0xffff0000, v13
	v_add_f32_e32 v0, 1.0, v0
	v_add_f32_e32 v1, 1.0, v1
	v_rcp_f32_e32 v0, v0
	v_rcp_f32_e32 v1, v1
	v_pk_mul_f32 v[4:5], v[4:5], v[14:15]
	v_pk_mul_f32 v[12:13], v[0:1], v[2:3]
	v_cvt_pk_bf16_f32 v0, v4, v5
	v_cvt_pk_bf16_f32 v1, v6, v7
	v_cvt_pk_bf16_f32 v2, v10, v11
	v_cvt_pk_bf16_f32 v3, v12, v13
	v_lshl_add_u64 v[4:5], s[40:41], 0, v[8:9]
	global_store_dwordx4 v[4:5], v[0:3], off
	s_cbranch_vccnz .LBB0_1199
	s_andn2_b64 vcc, exec, s[4:5]
	s_cbranch_vccnz .LBB0_1198
	s_barrier
	s_branch .LBB0_1198

.LBB0_1288:
	s_lshl_b32 s9, s6, 1
	s_lshl_b32 s15, s7, 1
	v_or_b32_e32 v79, s15, v0
	s_add_i32 s16, s9, 4
	s_add_i32 s17, s15, 4
	s_add_i32 s19, s15, 8
	v_add_u32_e32 v2, s1, v79
	v_or_b32_e32 v80, s16, v1
	v_or_b32_e32 v81, s17, v0
	v_mov_b32_e32 v59, v3
	v_or_b32_e32 v78, s9, v1
	s_add_i32 s23, s15, 12
	v_or_b32_e32 v83, s19, v0
	v_lshlrev_b64 v[72:73], 12, v[2:3]
	v_add_u32_e32 v58, s4, v80
	v_add_u32_e32 v2, s1, v81
	v_mov_b32_e32 v57, v3
	s_add_i32 s18, s9, 8
	s_add_i32 s20, s9, 12
	s_add_i32 s38, s15, 16
	v_add_u32_e32 v56, s4, v78
	v_or_b32_e32 v85, s23, v0
	v_lshlrev_b64 v[58:59], 12, v[58:59]
	v_lshlrev_b64 v[74:75], 12, v[2:3]
	v_add_u32_e32 v2, s1, v83
	s_add_i32 s42, s15, 20
	v_or_b32_e32 v82, s18, v1
	v_or_b32_e32 v84, s20, v1
	v_or_b32_e32 v87, s38, v0
	v_lshlrev_b64 v[56:57], 12, v[56:57]
	v_lshl_add_u64 v[72:73], v[50:51], 0, v[72:73]
	v_lshl_add_u64 v[58:59], v[50:51], 0, v[58:59]
	v_lshlrev_b64 v[76:77], 12, v[2:3]
	v_add_u32_e32 v2, s1, v85
	v_mov_b32_e32 v61, v3
	v_mov_b32_e32 v63, v3
	s_add_i32 s35, s9, 16
	s_add_i32 s39, s9, 20
	s_add_i32 s44, s15, 24
	v_or_b32_e32 v91, s42, v0
	v_add_u32_e32 v60, s4, v82
	v_add_u32_e32 v62, s4, v84
	v_lshl_add_u64 v[56:57], v[50:51], 0, v[56:57]
	v_lshl_add_u64 v[74:75], v[50:51], 0, v[74:75]
	global_load_dword v96, v[72:73], off
	global_load_dword v97, v[56:57], off
	global_load_dword v98, v[74:75], off
	global_load_dword v99, v[58:59], off
	v_lshlrev_b64 v[58:59], 12, v[2:3]
	v_add_u32_e32 v2, s1, v87
	s_add_i32 s43, s9, 24
	s_add_i32 s9, s9, 28
	s_add_i32 s15, s15, 28
	v_or_b32_e32 v86, s35, v1
	v_or_b32_e32 v90, s39, v1
	v_or_b32_e32 v93, s44, v0
	v_lshlrev_b64 v[60:61], 12, v[60:61]
	v_lshlrev_b64 v[62:63], 12, v[62:63]
	v_lshl_add_u64 v[56:57], v[50:51], 0, v[76:77]
	v_lshl_add_u64 v[58:59], v[50:51], 0, v[58:59]
	v_lshlrev_b64 v[72:73], 12, v[2:3]
	v_add_u32_e32 v2, s1, v91
	v_mov_b32_e32 v65, v3
	v_mov_b32_e32 v67, v3
	v_or_b32_e32 v92, s43, v1
	v_or_b32_e32 v94, s9, v1
	v_or_b32_e32 v95, s15, v0
	v_add_u32_e32 v64, s4, v86
	v_add_u32_e32 v66, s4, v90
	v_lshl_add_u64 v[60:61], v[50:51], 0, v[60:61]
	v_lshl_add_u64 v[62:63], v[50:51], 0, v[62:63]
	global_load_dword v100, v[56:57], off
	global_load_dword v101, v[60:61], off
	global_load_dword v102, v[58:59], off
	global_load_dword v103, v[62:63], off
	v_lshlrev_b64 v[58:59], 12, v[2:3]
	v_add_u32_e32 v2, s1, v93
	v_mov_b32_e32 v69, v3
	v_mov_b32_e32 v71, v3
	v_add_u32_e32 v68, s4, v92
	v_add_u32_e32 v70, s4, v94
	v_lshlrev_b64 v[64:65], 12, v[64:65]
	v_lshlrev_b64 v[66:67], 12, v[66:67]
	v_lshl_add_u64 v[56:57], v[50:51], 0, v[72:73]
	v_lshl_add_u64 v[58:59], v[50:51], 0, v[58:59]
	v_lshlrev_b64 v[60:61], 12, v[2:3]
	v_add_u32_e32 v2, s1, v95
	v_lshlrev_b64 v[68:69], 12, v[68:69]
	v_lshlrev_b64 v[70:71], 12, v[70:71]
	v_lshl_add_u64 v[64:65], v[50:51], 0, v[64:65]
	v_lshl_add_u64 v[66:67], v[50:51], 0, v[66:67]
	global_load_dword v104, v[56:57], off
	global_load_dword v105, v[64:65], off
	global_load_dword v106, v[58:59], off
	global_load_dword v107, v[66:67], off
	v_lshl_add_u64 v[56:57], v[50:51], 0, v[60:61]
	v_lshlrev_b64 v[58:59], 12, v[2:3]
	v_lshl_add_u64 v[68:69], v[50:51], 0, v[68:69]
	v_lshl_add_u64 v[70:71], v[50:51], 0, v[70:71]
	v_lshl_add_u64 v[58:59], v[50:51], 0, v[58:59]
	global_load_dword v2, v[56:57], off
	global_load_dword v108, v[68:69], off
	global_load_dword v109, v[58:59], off
	global_load_dword v110, v[70:71], off
	s_add_i32 s7, s7, 16
	s_add_i32 s6, s6, 16
	s_add_i32 s8, s8, -16
	v_mad_u64_u32 v[56:57], s[16:17], v79, s3, v[6:7]
	s_cmp_lg_u32 s8, 0
	v_mad_u64_u32 v[58:59], s[16:17], v78, s3, v[6:7]
	v_mad_u64_u32 v[60:61], s[16:17], v81, s3, v[6:7]
	v_mad_u64_u32 v[62:63], s[16:17], v80, s3, v[6:7]
	v_mad_u64_u32 v[64:65], s[16:17], v83, s3, v[6:7]
	v_mad_u64_u32 v[66:67], s[16:17], v82, s3, v[6:7]
	v_mad_u64_u32 v[68:69], s[16:17], v85, s3, v[6:7]
	v_mad_u64_u32 v[70:71], s[16:17], v84, s3, v[6:7]
	v_mad_u64_u32 v[72:73], s[16:17], v87, s3, v[6:7]
	v_mad_u64_u32 v[74:75], s[16:17], v86, s3, v[6:7]
	v_mad_u64_u32 v[76:77], s[16:17], v91, s3, v[6:7]
	v_mad_u64_u32 v[78:79], s[16:17], v90, s3, v[6:7]
	v_mad_u64_u32 v[80:81], s[16:17], v93, s3, v[6:7]
	v_mad_u64_u32 v[82:83], s[16:17], v92, s3, v[6:7]
	v_mad_u64_u32 v[84:85], s[16:17], v95, s3, v[6:7]
	v_mad_u64_u32 v[86:87], s[16:17], v94, s3, v[6:7]
	s_waitcnt vmcnt(15)
	ds_write_b32 v56, v96
	s_waitcnt vmcnt(14)
	ds_write_b32 v58, v97
	s_waitcnt vmcnt(13)
	ds_write_b32 v60, v98
	s_waitcnt vmcnt(12)
	ds_write_b32 v62, v99
	s_waitcnt vmcnt(11)
	ds_write_b32 v64, v100
	s_waitcnt vmcnt(10)
	ds_write_b32 v66, v101
	s_waitcnt vmcnt(9)
	ds_write_b32 v68, v102
	s_waitcnt vmcnt(8)
	ds_write_b32 v70, v103
	s_waitcnt vmcnt(7)
	ds_write_b32 v72, v104
	s_waitcnt vmcnt(6)
	ds_write_b32 v74, v105
	s_waitcnt vmcnt(5)
	ds_write_b32 v76, v106
	s_waitcnt vmcnt(4)
	ds_write_b32 v78, v107
	s_waitcnt vmcnt(3)
	ds_write_b32 v80, v2
	s_waitcnt vmcnt(2)
	ds_write_b32 v82, v108
	s_waitcnt vmcnt(1)
	ds_write_b32 v84, v109
	s_waitcnt vmcnt(0)
	ds_write_b32 v86, v110
	s_cbranch_scc1 .LBB0_1288
	s_waitcnt lgkmcnt(0)
	ds_read2_b32 v[50:51], v52 offset0:33 offset1:41
	ds_read2_b32 v[60:61], v52 offset1:8
	ds_read2_b32 v[62:63], v52 offset0:66 offset1:74
	ds_read2_b32 v[64:65], v52 offset0:99 offset1:107
	ds_read2_b32 v[66:67], v52 offset0:132 offset1:140
	ds_read2_b32 v[68:69], v52 offset0:165 offset1:173
	ds_read2_b32 v[70:71], v52 offset0:198 offset1:206
	ds_read2_b32 v[72:73], v52 offset0:231 offset1:239
	s_lshl_b32 s4, s1, 1
	v_or_b32_e32 v2, s0, v7
	v_lshl_add_u64 v[74:75], v[8:9], 0, s[4:5]
	v_lshlrev_b32_e32 v2, 11, v2
	s_waitcnt lgkmcnt(6)
	v_mul_f32_e32 v60, 0xbfb8aa3b, v60
	v_mul_f32_e32 v50, 0xbfb8aa3b, v50
	v_cvt_pk_bf16_f32 v56, v60, v50
	s_waitcnt lgkmcnt(4)
	v_mul_f32_e32 v62, 0xbfb8aa3b, v62
	v_mul_f32_e32 v64, 0xbfb8aa3b, v64
	v_cvt_pk_bf16_f32 v57, v62, v64
	s_waitcnt lgkmcnt(2)
	v_mul_f32_e32 v66, 0xbfb8aa3b, v66
	v_mul_f32_e32 v68, 0xbfb8aa3b, v68
	v_cvt_pk_bf16_f32 v58, v66, v68
	s_waitcnt lgkmcnt(0)
	v_mul_f32_e32 v70, 0xbfb8aa3b, v70
	v_mul_f32_e32 v72, 0xbfb8aa3b, v72
	v_cvt_pk_bf16_f32 v59, v70, v72
	v_lshl_add_u64 v[76:77], v[74:75], 0, v[2:3]
	global_store_dwordx4 v[76:77], v[56:59], off
	v_or_b32_e32 v2, s0, v53
	v_lshlrev_b32_e32 v2, 11, v2
	v_mul_f32_e32 v61, 0xbfb8aa3b, v61
	v_mul_f32_e32 v51, 0xbfb8aa3b, v51
	v_cvt_pk_bf16_f32 v56, v61, v51
	v_mul_f32_e32 v63, 0xbfb8aa3b, v63
	v_mul_f32_e32 v65, 0xbfb8aa3b, v65
	v_cvt_pk_bf16_f32 v57, v63, v65
	v_mul_f32_e32 v67, 0xbfb8aa3b, v67
	v_mul_f32_e32 v69, 0xbfb8aa3b, v69
	v_cvt_pk_bf16_f32 v58, v67, v69
	v_mul_f32_e32 v71, 0xbfb8aa3b, v71
	v_mul_f32_e32 v73, 0xbfb8aa3b, v73
	v_cvt_pk_bf16_f32 v59, v71, v73
	ds_read2_b32 v[60:61], v52 offset0:49 offset1:57
	ds_read2_b32 v[62:63], v52 offset0:16 offset1:24
	ds_read2_b32 v[64:65], v52 offset0:82 offset1:90
	ds_read2_b32 v[66:67], v52 offset0:115 offset1:123
	ds_read2_b32 v[68:69], v52 offset0:148 offset1:156
	ds_read2_b32 v[70:71], v52 offset0:181 offset1:189
	ds_read2_b32 v[72:73], v52 offset0:214 offset1:222
	ds_read2_b32 v[76:77], v52 offset0:247 offset1:255
	v_lshl_add_u64 v[50:51], v[74:75], 0, v[2:3]
	v_or_b32_e32 v2, s0, v54
	v_lshlrev_b32_e32 v2, 11, v2
	global_store_dwordx4 v[50:51], v[56:59], off
	v_lshl_add_u64 v[50:51], v[74:75], 0, v[2:3]
	v_or_b32_e32 v2, s0, v55
	s_waitcnt lgkmcnt(6)
	v_mul_f32_e32 v62, 0xbfb8aa3b, v62
	v_mul_f32_e32 v60, 0xbfb8aa3b, v60
	v_cvt_pk_bf16_f32 v56, v62, v60
	s_waitcnt lgkmcnt(4)
	v_mul_f32_e32 v64, 0xbfb8aa3b, v64
	v_mul_f32_e32 v66, 0xbfb8aa3b, v66
	v_cvt_pk_bf16_f32 v57, v64, v66
	s_waitcnt lgkmcnt(2)
	v_mul_f32_e32 v68, 0xbfb8aa3b, v68
	v_mul_f32_e32 v70, 0xbfb8aa3b, v70
	v_cvt_pk_bf16_f32 v58, v68, v70
	s_waitcnt lgkmcnt(0)
	v_mul_f32_e32 v72, 0xbfb8aa3b, v72
	v_mul_f32_e32 v76, 0xbfb8aa3b, v76
	v_cvt_pk_bf16_f32 v59, v72, v76
	v_lshlrev_b32_e32 v2, 11, v2
	global_store_dwordx4 v[50:51], v[56:59], off
	v_lshl_add_u64 v[50:51], v[74:75], 0, v[2:3]
	s_mov_b64 s[0:1], 0
	v_mul_f32_e32 v63, 0xbfb8aa3b, v63
	v_mul_f32_e32 v61, 0xbfb8aa3b, v61
	v_cvt_pk_bf16_f32 v56, v63, v61
	v_mul_f32_e32 v65, 0xbfb8aa3b, v65
	v_mul_f32_e32 v67, 0xbfb8aa3b, v67
	v_cvt_pk_bf16_f32 v57, v65, v67
	v_mul_f32_e32 v69, 0xbfb8aa3b, v69
	v_mul_f32_e32 v71, 0xbfb8aa3b, v71
	v_cvt_pk_bf16_f32 v58, v69, v71
	v_mul_f32_e32 v73, 0xbfb8aa3b, v73
	v_mul_f32_e32 v77, 0xbfb8aa3b, v77
	v_cvt_pk_bf16_f32 v59, v73, v77
	global_store_dwordx4 v[50:51], v[56:59], off
	s_waitcnt lgkmcnt(0)

.LBB0_1327:
	s_lshl_b32 s15, s7, 1
	s_lshl_b32 s16, s8, 1
	v_or_b32_e32 v2, s15, v1
	v_or_b32_e32 v90, s16, v0
	s_add_i32 s17, s15, 4
	s_add_i32 s18, s16, 4
	s_add_i32 s19, s15, 8
	s_add_i32 s20, s16, 8
	s_add_i32 s23, s15, 12
	s_add_i32 s35, s16, 12
	s_add_i32 s38, s15, 16
	s_add_i32 s39, s16, 16
	s_add_i32 s42, s15, 20
	s_add_i32 s43, s16, 20
	s_add_i32 s44, s15, 24
	s_add_i32 s45, s16, 24
	s_add_i32 s15, s15, 28
	s_add_i32 s16, s16, 28
	v_add_u32_e32 v56, s0, v90
	v_or_b32_e32 v91, s17, v1
	v_or_b32_e32 v92, s18, v0
	v_or_b32_e32 v93, s19, v1
	v_or_b32_e32 v94, s20, v0
	v_or_b32_e32 v95, s23, v1
	v_or_b32_e32 v96, s35, v0
	v_or_b32_e32 v97, s38, v1
	v_or_b32_e32 v98, s39, v0
	v_or_b32_e32 v99, s42, v1
	v_or_b32_e32 v100, s43, v0
	v_or_b32_e32 v101, s44, v1
	v_or_b32_e32 v102, s45, v0
	v_or_b32_e32 v103, s15, v1
	v_or_b32_e32 v104, s16, v0
	v_add_u32_e32 v58, s4, v2
	v_mad_u64_u32 v[56:57], s[16:17], v56, s13, v[50:51]
	v_add_u32_e32 v62, s4, v91
	v_add_u32_e32 v60, s0, v92
	v_add_u32_e32 v66, s4, v93
	v_add_u32_e32 v64, s0, v94
	v_add_u32_e32 v70, s4, v95
	v_add_u32_e32 v68, s0, v96
	v_add_u32_e32 v74, s4, v97
	v_add_u32_e32 v72, s0, v98
	v_add_u32_e32 v78, s4, v99
	v_add_u32_e32 v76, s0, v100
	v_add_u32_e32 v82, s4, v101
	v_add_u32_e32 v80, s0, v102
	v_add_u32_e32 v86, s4, v103
	v_add_u32_e32 v84, s0, v104
	v_mad_u64_u32 v[58:59], s[16:17], v58, s13, v[50:51]
	v_mad_u64_u32 v[60:61], s[16:17], v60, s13, v[50:51]
	v_mad_u64_u32 v[62:63], s[16:17], v62, s13, v[50:51]
	v_mad_u64_u32 v[64:65], s[16:17], v64, s13, v[50:51]
	v_mad_u64_u32 v[66:67], s[16:17], v66, s13, v[50:51]
	v_mad_u64_u32 v[68:69], s[16:17], v68, s13, v[50:51]
	v_mad_u64_u32 v[70:71], s[16:17], v70, s13, v[50:51]
	v_mad_u64_u32 v[72:73], s[16:17], v72, s13, v[50:51]
	v_mad_u64_u32 v[74:75], s[16:17], v74, s13, v[50:51]
	v_mad_u64_u32 v[76:77], s[16:17], v76, s13, v[50:51]
	v_mad_u64_u32 v[78:79], s[16:17], v78, s13, v[50:51]
	v_mad_u64_u32 v[80:81], s[16:17], v80, s13, v[50:51]
	v_mad_u64_u32 v[82:83], s[16:17], v82, s13, v[50:51]
	v_mad_u64_u32 v[84:85], s[16:17], v84, s13, v[50:51]
	v_mad_u64_u32 v[86:87], s[16:17], v86, s13, v[50:51]
	global_load_dword v105, v[56:57], off
	global_load_dword v106, v[58:59], off
	global_load_dword v107, v[60:61], off
	global_load_dword v108, v[62:63], off
	global_load_dword v109, v[64:65], off
	global_load_dword v110, v[66:67], off
	global_load_dword v111, v[68:69], off
	global_load_dword v112, v[70:71], off
	global_load_dword v113, v[72:73], off
	global_load_dword v114, v[74:75], off
	global_load_dword v115, v[76:77], off
	global_load_dword v116, v[78:79], off
	global_load_dword v117, v[80:81], off
	global_load_dword v118, v[82:83], off
	global_load_dword v119, v[84:85], off
	global_load_dword v120, v[86:87], off
	s_add_i32 s8, s8, 16
	s_add_i32 s7, s7, 16
	s_add_i32 s9, s9, -16
	v_mad_u64_u32 v[56:57], s[16:17], v90, s3, v[6:7]
	s_cmp_lg_u32 s9, 0
	v_mad_u64_u32 v[58:59], s[16:17], v2, s3, v[6:7]
	v_mad_u64_u32 v[60:61], s[16:17], v92, s3, v[6:7]
	v_mad_u64_u32 v[62:63], s[16:17], v91, s3, v[6:7]
	v_mad_u64_u32 v[64:65], s[16:17], v94, s3, v[6:7]
	v_mad_u64_u32 v[66:67], s[16:17], v93, s3, v[6:7]
	v_mad_u64_u32 v[68:69], s[16:17], v96, s3, v[6:7]
	v_mad_u64_u32 v[70:71], s[16:17], v95, s3, v[6:7]
	v_mad_u64_u32 v[72:73], s[16:17], v98, s3, v[6:7]
	v_mad_u64_u32 v[74:75], s[16:17], v97, s3, v[6:7]
	v_mad_u64_u32 v[76:77], s[16:17], v100, s3, v[6:7]
	v_mad_u64_u32 v[78:79], s[16:17], v99, s3, v[6:7]
	v_mad_u64_u32 v[80:81], s[16:17], v102, s3, v[6:7]
	v_mad_u64_u32 v[82:83], s[16:17], v101, s3, v[6:7]
	v_mad_u64_u32 v[84:85], s[16:17], v104, s3, v[6:7]
	v_mad_u64_u32 v[86:87], s[16:17], v103, s3, v[6:7]
	s_waitcnt vmcnt(15)
	ds_write_b32 v56, v105
	s_waitcnt vmcnt(14)
	ds_write_b32 v58, v106
	s_waitcnt vmcnt(13)
	ds_write_b32 v60, v107
	s_waitcnt vmcnt(12)
	ds_write_b32 v62, v108
	s_waitcnt vmcnt(11)
	ds_write_b32 v64, v109
	s_waitcnt vmcnt(10)
	ds_write_b32 v66, v110
	s_waitcnt vmcnt(9)
	ds_write_b32 v68, v111
	s_waitcnt vmcnt(8)
	ds_write_b32 v70, v112
	s_waitcnt vmcnt(7)
	ds_write_b32 v72, v113
	s_waitcnt vmcnt(6)
	ds_write_b32 v74, v114
	s_waitcnt vmcnt(5)
	ds_write_b32 v76, v115
	s_waitcnt vmcnt(4)
	ds_write_b32 v78, v116
	s_waitcnt vmcnt(3)
	ds_write_b32 v80, v117
	s_waitcnt vmcnt(2)
	ds_write_b32 v82, v118
	s_waitcnt vmcnt(1)
	ds_write_b32 v84, v119
	s_waitcnt vmcnt(0)
	ds_write_b32 v86, v120
	s_cbranch_scc1 .LBB0_1327
	s_lshl_b32 s4, s6, 6
	s_waitcnt lgkmcnt(0)
	s_and_b32 s4, s4, 0x1f00
	s_and_b32 s1, s1, 0x60
	ds_read2_b32 v[50:51], v52 offset0:33 offset1:41
	ds_read2_b32 v[60:61], v52 offset1:8
	ds_read2_b32 v[62:63], v52 offset0:66 offset1:74
	ds_read2_b32 v[64:65], v52 offset0:99 offset1:107
	ds_read2_b32 v[66:67], v52 offset0:132 offset1:140
	ds_read2_b32 v[68:69], v52 offset0:165 offset1:173
	ds_read2_b32 v[70:71], v52 offset0:198 offset1:206
	ds_read2_b32 v[72:73], v52 offset0:231 offset1:239
	s_or_b32 s1, s1, s4
	s_bitset1_b32 s1, 7
	s_and_b32 s0, 0xffff, s0
	s_lshl_b32 s4, s0, 1
	v_or_b32_e32 v2, s1, v7
	v_lshl_add_u64 v[74:75], v[42:43], 0, s[4:5]
	v_lshlrev_b32_e32 v2, 11, v2
	s_waitcnt lgkmcnt(6)
	v_mul_f32_e32 v60, 0xbf317218, v60
	v_mul_f32_e32 v50, 0xbf317218, v50
	v_cvt_pk_bf16_f32 v56, v60, v50
	s_waitcnt lgkmcnt(4)
	v_mul_f32_e32 v62, 0xbf317218, v62
	v_mul_f32_e32 v64, 0xbf317218, v64
	v_cvt_pk_bf16_f32 v57, v62, v64
	s_waitcnt lgkmcnt(2)
	v_mul_f32_e32 v66, 0xbf317218, v66
	v_mul_f32_e32 v68, 0xbf317218, v68
	v_cvt_pk_bf16_f32 v58, v66, v68
	s_waitcnt lgkmcnt(0)
	v_mul_f32_e32 v70, 0xbf317218, v70
	v_mul_f32_e32 v72, 0xbf317218, v72
	v_cvt_pk_bf16_f32 v59, v70, v72
	v_lshl_add_u64 v[76:77], v[74:75], 0, v[2:3]
	global_store_dwordx4 v[76:77], v[56:59], off
	v_or_b32_e32 v2, s1, v53
	v_lshlrev_b32_e32 v2, 11, v2
	v_mul_f32_e32 v61, 0xbf317218, v61
	v_mul_f32_e32 v51, 0xbf317218, v51
	v_cvt_pk_bf16_f32 v56, v61, v51
	v_mul_f32_e32 v63, 0xbf317218, v63
	v_mul_f32_e32 v65, 0xbf317218, v65
	v_cvt_pk_bf16_f32 v57, v63, v65
	v_mul_f32_e32 v67, 0xbf317218, v67
	v_mul_f32_e32 v69, 0xbf317218, v69
	v_cvt_pk_bf16_f32 v58, v67, v69
	v_mul_f32_e32 v71, 0xbf317218, v71
	v_mul_f32_e32 v73, 0xbf317218, v73
	v_cvt_pk_bf16_f32 v59, v71, v73
	ds_read2_b32 v[60:61], v52 offset0:49 offset1:57
	ds_read2_b32 v[62:63], v52 offset0:16 offset1:24
	ds_read2_b32 v[64:65], v52 offset0:82 offset1:90
	ds_read2_b32 v[66:67], v52 offset0:115 offset1:123
	ds_read2_b32 v[68:69], v52 offset0:148 offset1:156
	ds_read2_b32 v[70:71], v52 offset0:181 offset1:189
	ds_read2_b32 v[72:73], v52 offset0:214 offset1:222
	ds_read2_b32 v[76:77], v52 offset0:247 offset1:255
	v_lshl_add_u64 v[50:51], v[74:75], 0, v[2:3]
	v_or_b32_e32 v2, s1, v54
	v_lshlrev_b32_e32 v2, 11, v2
	global_store_dwordx4 v[50:51], v[56:59], off
	v_lshl_add_u64 v[50:51], v[74:75], 0, v[2:3]
	v_or_b32_e32 v2, s1, v55
	s_waitcnt lgkmcnt(6)
	v_mul_f32_e32 v62, 0xbf317218, v62
	v_mul_f32_e32 v60, 0xbf317218, v60
	v_cvt_pk_bf16_f32 v56, v62, v60
	s_waitcnt lgkmcnt(4)
	v_mul_f32_e32 v64, 0xbf317218, v64
	v_mul_f32_e32 v66, 0xbf317218, v66
	v_cvt_pk_bf16_f32 v57, v64, v66
	s_waitcnt lgkmcnt(2)
	v_mul_f32_e32 v68, 0xbf317218, v68
	v_mul_f32_e32 v70, 0xbf317218, v70
	v_cvt_pk_bf16_f32 v58, v68, v70
	s_waitcnt lgkmcnt(0)
	v_mul_f32_e32 v72, 0xbf317218, v72
	v_mul_f32_e32 v76, 0xbf317218, v76
	v_cvt_pk_bf16_f32 v59, v72, v76
	v_lshlrev_b32_e32 v2, 11, v2
	global_store_dwordx4 v[50:51], v[56:59], off
	v_lshl_add_u64 v[50:51], v[74:75], 0, v[2:3]
	s_nop 0
	v_mul_f32_e32 v63, 0xbf317218, v63
	v_mul_f32_e32 v61, 0xbf317218, v61
	v_cvt_pk_bf16_f32 v56, v63, v61
	v_mul_f32_e32 v65, 0xbf317218, v65
	v_mul_f32_e32 v67, 0xbf317218, v67
	v_cvt_pk_bf16_f32 v57, v65, v67
	v_mul_f32_e32 v69, 0xbf317218, v69
	v_mul_f32_e32 v71, 0xbf317218, v71
	v_cvt_pk_bf16_f32 v58, v69, v71
	v_mul_f32_e32 v73, 0xbf317218, v73
	v_mul_f32_e32 v77, 0xbf317218, v77
	v_cvt_pk_bf16_f32 v59, v73, v77
	global_store_dwordx4 v[50:51], v[56:59], off
	s_waitcnt lgkmcnt(0)

.LBB0_1332:
	s_lshl_b32 s15, s7, 1
	s_lshl_b32 s16, s8, 1
	v_or_b32_e32 v2, s15, v1
	v_or_b32_e32 v90, s16, v0
	s_add_i32 s17, s15, 4
	s_add_i32 s18, s16, 4
	s_add_i32 s19, s15, 8
	s_add_i32 s20, s16, 8
	s_add_i32 s23, s15, 12
	s_add_i32 s35, s16, 12
	s_add_i32 s38, s15, 16
	s_add_i32 s39, s16, 16
	s_add_i32 s42, s15, 20
	s_add_i32 s43, s16, 20
	s_add_i32 s44, s15, 24
	s_add_i32 s45, s16, 24
	s_add_i32 s15, s15, 28
	s_add_i32 s16, s16, 28
	v_add_u32_e32 v56, s0, v90
	v_or_b32_e32 v91, s17, v1
	v_or_b32_e32 v92, s18, v0
	v_or_b32_e32 v93, s19, v1
	v_or_b32_e32 v94, s20, v0
	v_or_b32_e32 v95, s23, v1
	v_or_b32_e32 v96, s35, v0
	v_or_b32_e32 v97, s38, v1
	v_or_b32_e32 v98, s39, v0
	v_or_b32_e32 v99, s42, v1
	v_or_b32_e32 v100, s43, v0
	v_or_b32_e32 v101, s44, v1
	v_or_b32_e32 v102, s45, v0
	v_or_b32_e32 v103, s15, v1
	v_or_b32_e32 v104, s16, v0
	v_add_u32_e32 v58, s4, v2
	v_mad_u64_u32 v[56:57], s[16:17], v56, s13, v[50:51]
	v_add_u32_e32 v62, s4, v91
	v_add_u32_e32 v60, s0, v92
	v_add_u32_e32 v66, s4, v93
	v_add_u32_e32 v64, s0, v94
	v_add_u32_e32 v70, s4, v95
	v_add_u32_e32 v68, s0, v96
	v_add_u32_e32 v74, s4, v97
	v_add_u32_e32 v72, s0, v98
	v_add_u32_e32 v78, s4, v99
	v_add_u32_e32 v76, s0, v100
	v_add_u32_e32 v82, s4, v101
	v_add_u32_e32 v80, s0, v102
	v_add_u32_e32 v86, s4, v103
	v_add_u32_e32 v84, s0, v104
	v_mad_u64_u32 v[58:59], s[16:17], v58, s13, v[50:51]
	v_mad_u64_u32 v[60:61], s[16:17], v60, s13, v[50:51]
	v_mad_u64_u32 v[62:63], s[16:17], v62, s13, v[50:51]
	v_mad_u64_u32 v[64:65], s[16:17], v64, s13, v[50:51]
	v_mad_u64_u32 v[66:67], s[16:17], v66, s13, v[50:51]
	v_mad_u64_u32 v[68:69], s[16:17], v68, s13, v[50:51]
	v_mad_u64_u32 v[70:71], s[16:17], v70, s13, v[50:51]
	v_mad_u64_u32 v[72:73], s[16:17], v72, s13, v[50:51]
	v_mad_u64_u32 v[74:75], s[16:17], v74, s13, v[50:51]
	v_mad_u64_u32 v[76:77], s[16:17], v76, s13, v[50:51]
	v_mad_u64_u32 v[78:79], s[16:17], v78, s13, v[50:51]
	v_mad_u64_u32 v[80:81], s[16:17], v80, s13, v[50:51]
	v_mad_u64_u32 v[82:83], s[16:17], v82, s13, v[50:51]
	v_mad_u64_u32 v[84:85], s[16:17], v84, s13, v[50:51]
	v_mad_u64_u32 v[86:87], s[16:17], v86, s13, v[50:51]
	global_load_dword v105, v[56:57], off
	global_load_dword v106, v[58:59], off
	global_load_dword v107, v[60:61], off
	global_load_dword v108, v[62:63], off
	global_load_dword v109, v[64:65], off
	global_load_dword v110, v[66:67], off
	global_load_dword v111, v[68:69], off
	global_load_dword v112, v[70:71], off
	global_load_dword v113, v[72:73], off
	global_load_dword v114, v[74:75], off
	global_load_dword v115, v[76:77], off
	global_load_dword v116, v[78:79], off
	global_load_dword v117, v[80:81], off
	global_load_dword v118, v[82:83], off
	global_load_dword v119, v[84:85], off
	global_load_dword v120, v[86:87], off
	s_add_i32 s8, s8, 16
	s_add_i32 s7, s7, 16
	s_add_i32 s9, s9, -16
	v_mad_u64_u32 v[56:57], s[16:17], v90, s3, v[6:7]
	s_cmp_lg_u32 s9, 0
	v_mad_u64_u32 v[58:59], s[16:17], v2, s3, v[6:7]
	v_mad_u64_u32 v[60:61], s[16:17], v92, s3, v[6:7]
	v_mad_u64_u32 v[62:63], s[16:17], v91, s3, v[6:7]
	v_mad_u64_u32 v[64:65], s[16:17], v94, s3, v[6:7]
	v_mad_u64_u32 v[66:67], s[16:17], v93, s3, v[6:7]
	v_mad_u64_u32 v[68:69], s[16:17], v96, s3, v[6:7]
	v_mad_u64_u32 v[70:71], s[16:17], v95, s3, v[6:7]
	v_mad_u64_u32 v[72:73], s[16:17], v98, s3, v[6:7]
	v_mad_u64_u32 v[74:75], s[16:17], v97, s3, v[6:7]
	v_mad_u64_u32 v[76:77], s[16:17], v100, s3, v[6:7]
	v_mad_u64_u32 v[78:79], s[16:17], v99, s3, v[6:7]
	v_mad_u64_u32 v[80:81], s[16:17], v102, s3, v[6:7]
	v_mad_u64_u32 v[82:83], s[16:17], v101, s3, v[6:7]
	v_mad_u64_u32 v[84:85], s[16:17], v104, s3, v[6:7]
	v_mad_u64_u32 v[86:87], s[16:17], v103, s3, v[6:7]
	s_waitcnt vmcnt(15)
	ds_write_b32 v56, v105
	s_waitcnt vmcnt(14)
	ds_write_b32 v58, v106
	s_waitcnt vmcnt(13)
	ds_write_b32 v60, v107
	s_waitcnt vmcnt(12)
	ds_write_b32 v62, v108
	s_waitcnt vmcnt(11)
	ds_write_b32 v64, v109
	s_waitcnt vmcnt(10)
	ds_write_b32 v66, v110
	s_waitcnt vmcnt(9)
	ds_write_b32 v68, v111
	s_waitcnt vmcnt(8)
	ds_write_b32 v70, v112
	s_waitcnt vmcnt(7)
	ds_write_b32 v72, v113
	s_waitcnt vmcnt(6)
	ds_write_b32 v74, v114
	s_waitcnt vmcnt(5)
	ds_write_b32 v76, v115
	s_waitcnt vmcnt(4)
	ds_write_b32 v78, v116
	s_waitcnt vmcnt(3)
	ds_write_b32 v80, v117
	s_waitcnt vmcnt(2)
	ds_write_b32 v82, v118
	s_waitcnt vmcnt(1)
	ds_write_b32 v84, v119
	s_waitcnt vmcnt(0)
	ds_write_b32 v86, v120
	s_cbranch_scc1 .LBB0_1332
	s_waitcnt lgkmcnt(0)
	s_lshl_b32 s4, s6, 6
	ds_read2_b32 v[50:51], v52 offset0:33 offset1:41
	ds_read2_b32 v[60:61], v52 offset1:8
	ds_read2_b32 v[62:63], v52 offset0:66 offset1:74
	ds_read2_b32 v[64:65], v52 offset0:99 offset1:107
	ds_read2_b32 v[66:67], v52 offset0:132 offset1:140
	ds_read2_b32 v[68:69], v52 offset0:165 offset1:173
	ds_read2_b32 v[70:71], v52 offset0:198 offset1:206
	ds_read2_b32 v[72:73], v52 offset0:231 offset1:239
	s_and_b32 s4, s4, 0x1f00
	s_and_b32 s1, s1, 0x60
	s_or_b32 s1, s1, s4
	s_and_b32 s0, 0xffff, s0
	s_lshl_b32 s4, s0, 1
	v_or_b32_e32 v2, s1, v7
	v_lshl_add_u64 v[74:75], v[42:43], 0, s[4:5]
	v_lshlrev_b32_e32 v2, 11, v2
	s_waitcnt lgkmcnt(6)
	v_mul_f32_e32 v60, 0xbfb8aa3b, v60
	v_mul_f32_e32 v50, 0xbfb8aa3b, v50
	v_cvt_pk_bf16_f32 v56, v60, v50
	s_waitcnt lgkmcnt(4)
	v_mul_f32_e32 v62, 0xbfb8aa3b, v62
	v_mul_f32_e32 v64, 0xbfb8aa3b, v64
	v_cvt_pk_bf16_f32 v57, v62, v64
	s_waitcnt lgkmcnt(2)
	v_mul_f32_e32 v66, 0xbfb8aa3b, v66
	v_mul_f32_e32 v68, 0xbfb8aa3b, v68
	v_cvt_pk_bf16_f32 v58, v66, v68
	s_waitcnt lgkmcnt(0)
	v_mul_f32_e32 v70, 0xbfb8aa3b, v70
	v_mul_f32_e32 v72, 0xbfb8aa3b, v72
	v_cvt_pk_bf16_f32 v59, v70, v72
	v_lshl_add_u64 v[76:77], v[74:75], 0, v[2:3]
	global_store_dwordx4 v[76:77], v[56:59], off
	v_or_b32_e32 v2, s1, v53
	v_lshlrev_b32_e32 v2, 11, v2
	v_mul_f32_e32 v61, 0xbfb8aa3b, v61
	v_mul_f32_e32 v51, 0xbfb8aa3b, v51
	v_cvt_pk_bf16_f32 v56, v61, v51
	v_mul_f32_e32 v63, 0xbfb8aa3b, v63
	v_mul_f32_e32 v65, 0xbfb8aa3b, v65
	v_cvt_pk_bf16_f32 v57, v63, v65
	v_mul_f32_e32 v67, 0xbfb8aa3b, v67
	v_mul_f32_e32 v69, 0xbfb8aa3b, v69
	v_cvt_pk_bf16_f32 v58, v67, v69
	v_mul_f32_e32 v71, 0xbfb8aa3b, v71
	v_mul_f32_e32 v73, 0xbfb8aa3b, v73
	v_cvt_pk_bf16_f32 v59, v71, v73
	ds_read2_b32 v[60:61], v52 offset0:49 offset1:57
	ds_read2_b32 v[62:63], v52 offset0:16 offset1:24
	ds_read2_b32 v[64:65], v52 offset0:82 offset1:90
	ds_read2_b32 v[66:67], v52 offset0:115 offset1:123
	ds_read2_b32 v[68:69], v52 offset0:148 offset1:156
	ds_read2_b32 v[70:71], v52 offset0:181 offset1:189
	ds_read2_b32 v[72:73], v52 offset0:214 offset1:222
	ds_read2_b32 v[76:77], v52 offset0:247 offset1:255
	v_lshl_add_u64 v[50:51], v[74:75], 0, v[2:3]
	v_or_b32_e32 v2, s1, v54
	v_lshlrev_b32_e32 v2, 11, v2
	global_store_dwordx4 v[50:51], v[56:59], off
	v_lshl_add_u64 v[50:51], v[74:75], 0, v[2:3]
	v_or_b32_e32 v2, s1, v55
	s_waitcnt lgkmcnt(6)
	v_mul_f32_e32 v62, 0xbfb8aa3b, v62
	v_mul_f32_e32 v60, 0xbfb8aa3b, v60
	v_cvt_pk_bf16_f32 v56, v62, v60
	s_waitcnt lgkmcnt(4)
	v_mul_f32_e32 v64, 0xbfb8aa3b, v64
	v_mul_f32_e32 v66, 0xbfb8aa3b, v66
	v_cvt_pk_bf16_f32 v57, v64, v66
	s_waitcnt lgkmcnt(2)
	v_mul_f32_e32 v68, 0xbfb8aa3b, v68
	v_mul_f32_e32 v70, 0xbfb8aa3b, v70
	v_cvt_pk_bf16_f32 v58, v68, v70
	s_waitcnt lgkmcnt(0)
	v_mul_f32_e32 v72, 0xbfb8aa3b, v72
	v_mul_f32_e32 v76, 0xbfb8aa3b, v76
	v_cvt_pk_bf16_f32 v59, v72, v76
	v_lshlrev_b32_e32 v2, 11, v2
	global_store_dwordx4 v[50:51], v[56:59], off
	v_lshl_add_u64 v[50:51], v[74:75], 0, v[2:3]
	s_nop 0
	v_mul_f32_e32 v63, 0xbfb8aa3b, v63
	v_mul_f32_e32 v61, 0xbfb8aa3b, v61
	v_cvt_pk_bf16_f32 v56, v63, v61
	v_mul_f32_e32 v65, 0xbfb8aa3b, v65
	v_mul_f32_e32 v67, 0xbfb8aa3b, v67
	v_cvt_pk_bf16_f32 v57, v65, v67
	v_mul_f32_e32 v69, 0xbfb8aa3b, v69
	v_mul_f32_e32 v71, 0xbfb8aa3b, v71
	v_cvt_pk_bf16_f32 v58, v69, v71
	v_mul_f32_e32 v73, 0xbfb8aa3b, v73
	v_mul_f32_e32 v77, 0xbfb8aa3b, v77
	v_cvt_pk_bf16_f32 v59, v73, v77
	global_store_dwordx4 v[50:51], v[56:59], off
	s_waitcnt lgkmcnt(0)

.LBB0_1337:
	s_lshl_b32 s15, s7, 1
	s_lshl_b32 s16, s8, 1
	v_or_b32_e32 v2, s15, v1
	v_or_b32_e32 v90, s16, v0
	s_add_i32 s17, s15, 4
	s_add_i32 s18, s16, 4
	s_add_i32 s19, s15, 8
	s_add_i32 s20, s16, 8
	s_add_i32 s23, s15, 12
	s_add_i32 s35, s16, 12
	s_add_i32 s38, s15, 16
	s_add_i32 s39, s16, 16
	s_add_i32 s42, s15, 20
	s_add_i32 s43, s16, 20
	s_add_i32 s44, s15, 24
	s_add_i32 s45, s16, 24
	s_add_i32 s15, s15, 28
	s_add_i32 s16, s16, 28
	v_add_u32_e32 v56, s0, v90
	v_or_b32_e32 v91, s17, v1
	v_or_b32_e32 v92, s18, v0
	v_or_b32_e32 v93, s19, v1
	v_or_b32_e32 v94, s20, v0
	v_or_b32_e32 v95, s23, v1
	v_or_b32_e32 v96, s35, v0
	v_or_b32_e32 v97, s38, v1
	v_or_b32_e32 v98, s39, v0
	v_or_b32_e32 v99, s42, v1
	v_or_b32_e32 v100, s43, v0
	v_or_b32_e32 v101, s44, v1
	v_or_b32_e32 v102, s45, v0
	v_or_b32_e32 v103, s15, v1
	v_or_b32_e32 v104, s16, v0
	v_add_u32_e32 v58, s4, v2
	v_mad_u64_u32 v[56:57], s[16:17], v56, s13, v[50:51]
	v_add_u32_e32 v62, s4, v91
	v_add_u32_e32 v60, s0, v92
	v_add_u32_e32 v66, s4, v93
	v_add_u32_e32 v64, s0, v94
	v_add_u32_e32 v70, s4, v95
	v_add_u32_e32 v68, s0, v96
	v_add_u32_e32 v74, s4, v97
	v_add_u32_e32 v72, s0, v98
	v_add_u32_e32 v78, s4, v99
	v_add_u32_e32 v76, s0, v100
	v_add_u32_e32 v82, s4, v101
	v_add_u32_e32 v80, s0, v102
	v_add_u32_e32 v86, s4, v103
	v_add_u32_e32 v84, s0, v104
	v_mad_u64_u32 v[58:59], s[16:17], v58, s13, v[50:51]
	v_mad_u64_u32 v[60:61], s[16:17], v60, s13, v[50:51]
	v_mad_u64_u32 v[62:63], s[16:17], v62, s13, v[50:51]
	v_mad_u64_u32 v[64:65], s[16:17], v64, s13, v[50:51]
	v_mad_u64_u32 v[66:67], s[16:17], v66, s13, v[50:51]
	v_mad_u64_u32 v[68:69], s[16:17], v68, s13, v[50:51]
	v_mad_u64_u32 v[70:71], s[16:17], v70, s13, v[50:51]
	v_mad_u64_u32 v[72:73], s[16:17], v72, s13, v[50:51]
	v_mad_u64_u32 v[74:75], s[16:17], v74, s13, v[50:51]
	v_mad_u64_u32 v[76:77], s[16:17], v76, s13, v[50:51]
	v_mad_u64_u32 v[78:79], s[16:17], v78, s13, v[50:51]
	v_mad_u64_u32 v[80:81], s[16:17], v80, s13, v[50:51]
	v_mad_u64_u32 v[82:83], s[16:17], v82, s13, v[50:51]
	v_mad_u64_u32 v[84:85], s[16:17], v84, s13, v[50:51]
	v_mad_u64_u32 v[86:87], s[16:17], v86, s13, v[50:51]
	global_load_dword v105, v[56:57], off
	global_load_dword v106, v[58:59], off
	global_load_dword v107, v[60:61], off
	global_load_dword v108, v[62:63], off
	global_load_dword v109, v[64:65], off
	global_load_dword v110, v[66:67], off
	global_load_dword v111, v[68:69], off
	global_load_dword v112, v[70:71], off
	global_load_dword v113, v[72:73], off
	global_load_dword v114, v[74:75], off
	global_load_dword v115, v[76:77], off
	global_load_dword v116, v[78:79], off
	global_load_dword v117, v[80:81], off
	global_load_dword v118, v[82:83], off
	global_load_dword v119, v[84:85], off
	global_load_dword v120, v[86:87], off
	s_add_i32 s8, s8, 16
	s_add_i32 s7, s7, 16
	s_add_i32 s9, s9, -16
	v_mad_u64_u32 v[56:57], s[16:17], v90, s3, v[6:7]
	s_cmp_lg_u32 s9, 0
	v_mad_u64_u32 v[58:59], s[16:17], v2, s3, v[6:7]
	v_mad_u64_u32 v[60:61], s[16:17], v92, s3, v[6:7]
	v_mad_u64_u32 v[62:63], s[16:17], v91, s3, v[6:7]
	v_mad_u64_u32 v[64:65], s[16:17], v94, s3, v[6:7]
	v_mad_u64_u32 v[66:67], s[16:17], v93, s3, v[6:7]
	v_mad_u64_u32 v[68:69], s[16:17], v96, s3, v[6:7]
	v_mad_u64_u32 v[70:71], s[16:17], v95, s3, v[6:7]
	v_mad_u64_u32 v[72:73], s[16:17], v98, s3, v[6:7]
	v_mad_u64_u32 v[74:75], s[16:17], v97, s3, v[6:7]
	v_mad_u64_u32 v[76:77], s[16:17], v100, s3, v[6:7]
	v_mad_u64_u32 v[78:79], s[16:17], v99, s3, v[6:7]
	v_mad_u64_u32 v[80:81], s[16:17], v102, s3, v[6:7]
	v_mad_u64_u32 v[82:83], s[16:17], v101, s3, v[6:7]
	v_mad_u64_u32 v[84:85], s[16:17], v104, s3, v[6:7]
	v_mad_u64_u32 v[86:87], s[16:17], v103, s3, v[6:7]
	s_waitcnt vmcnt(15)
	ds_write_b32 v56, v105
	s_waitcnt vmcnt(14)
	ds_write_b32 v58, v106
	s_waitcnt vmcnt(13)
	ds_write_b32 v60, v107
	s_waitcnt vmcnt(12)
	ds_write_b32 v62, v108
	s_waitcnt vmcnt(11)
	ds_write_b32 v64, v109
	s_waitcnt vmcnt(10)
	ds_write_b32 v66, v110
	s_waitcnt vmcnt(9)
	ds_write_b32 v68, v111
	s_waitcnt vmcnt(8)
	ds_write_b32 v70, v112
	s_waitcnt vmcnt(7)
	ds_write_b32 v72, v113
	s_waitcnt vmcnt(6)
	ds_write_b32 v74, v114
	s_waitcnt vmcnt(5)
	ds_write_b32 v76, v115
	s_waitcnt vmcnt(4)
	ds_write_b32 v78, v116
	s_waitcnt vmcnt(3)
	ds_write_b32 v80, v117
	s_waitcnt vmcnt(2)
	ds_write_b32 v82, v118
	s_waitcnt vmcnt(1)
	ds_write_b32 v84, v119
	s_waitcnt vmcnt(0)
	ds_write_b32 v86, v120
	s_cbranch_scc1 .LBB0_1337
	s_lshl_b32 s4, s6, 6
	s_waitcnt lgkmcnt(0)
	s_and_b32 s4, s4, 0x1f00
	s_and_b32 s1, s1, 0x60
	ds_read2_b32 v[50:51], v52 offset0:33 offset1:41
	ds_read2_b32 v[60:61], v52 offset1:8
	ds_read2_b32 v[62:63], v52 offset0:66 offset1:74
	ds_read2_b32 v[64:65], v52 offset0:99 offset1:107
	ds_read2_b32 v[66:67], v52 offset0:132 offset1:140
	ds_read2_b32 v[68:69], v52 offset0:165 offset1:173
	ds_read2_b32 v[70:71], v52 offset0:198 offset1:206
	ds_read2_b32 v[72:73], v52 offset0:231 offset1:239
	s_or_b32 s1, s1, s4
	s_bitset1_b32 s1, 7
	s_and_b32 s0, 0xffff, s0
	s_lshl_b32 s4, s0, 1
	v_or_b32_e32 v2, s1, v7
	v_lshl_add_u64 v[74:75], v[20:21], 0, s[4:5]
	v_lshlrev_b32_e32 v2, 11, v2
	s_waitcnt lgkmcnt(6)
	v_mul_f32_e32 v60, 0xbf317218, v60
	v_mul_f32_e32 v50, 0xbf317218, v50
	v_cvt_pk_bf16_f32 v56, v60, v50
	s_waitcnt lgkmcnt(4)
	v_mul_f32_e32 v62, 0xbf317218, v62
	v_mul_f32_e32 v64, 0xbf317218, v64
	v_cvt_pk_bf16_f32 v57, v62, v64
	s_waitcnt lgkmcnt(2)
	v_mul_f32_e32 v66, 0xbf317218, v66
	v_mul_f32_e32 v68, 0xbf317218, v68
	v_cvt_pk_bf16_f32 v58, v66, v68
	s_waitcnt lgkmcnt(0)
	v_mul_f32_e32 v70, 0xbf317218, v70
	v_mul_f32_e32 v72, 0xbf317218, v72
	v_cvt_pk_bf16_f32 v59, v70, v72
	v_lshl_add_u64 v[76:77], v[74:75], 0, v[2:3]
	global_store_dwordx4 v[76:77], v[56:59], off
	v_or_b32_e32 v2, s1, v53
	v_lshlrev_b32_e32 v2, 11, v2
	v_mul_f32_e32 v61, 0xbf317218, v61
	v_mul_f32_e32 v51, 0xbf317218, v51
	v_cvt_pk_bf16_f32 v56, v61, v51
	v_mul_f32_e32 v63, 0xbf317218, v63
	v_mul_f32_e32 v65, 0xbf317218, v65
	v_cvt_pk_bf16_f32 v57, v63, v65
	v_mul_f32_e32 v67, 0xbf317218, v67
	v_mul_f32_e32 v69, 0xbf317218, v69
	v_cvt_pk_bf16_f32 v58, v67, v69
	v_mul_f32_e32 v71, 0xbf317218, v71
	v_mul_f32_e32 v73, 0xbf317218, v73
	v_cvt_pk_bf16_f32 v59, v71, v73
	ds_read2_b32 v[60:61], v52 offset0:49 offset1:57
	ds_read2_b32 v[62:63], v52 offset0:16 offset1:24
	ds_read2_b32 v[64:65], v52 offset0:82 offset1:90
	ds_read2_b32 v[66:67], v52 offset0:115 offset1:123
	ds_read2_b32 v[68:69], v52 offset0:148 offset1:156
	ds_read2_b32 v[70:71], v52 offset0:181 offset1:189
	ds_read2_b32 v[72:73], v52 offset0:214 offset1:222
	ds_read2_b32 v[76:77], v52 offset0:247 offset1:255
	v_lshl_add_u64 v[50:51], v[74:75], 0, v[2:3]
	v_or_b32_e32 v2, s1, v54
	v_lshlrev_b32_e32 v2, 11, v2
	global_store_dwordx4 v[50:51], v[56:59], off
	v_lshl_add_u64 v[50:51], v[74:75], 0, v[2:3]
	v_or_b32_e32 v2, s1, v55
	s_waitcnt lgkmcnt(6)
	v_mul_f32_e32 v62, 0xbf317218, v62
	v_mul_f32_e32 v60, 0xbf317218, v60
	v_cvt_pk_bf16_f32 v56, v62, v60
	s_waitcnt lgkmcnt(4)
	v_mul_f32_e32 v64, 0xbf317218, v64
	v_mul_f32_e32 v66, 0xbf317218, v66
	v_cvt_pk_bf16_f32 v57, v64, v66
	s_waitcnt lgkmcnt(2)
	v_mul_f32_e32 v68, 0xbf317218, v68
	v_mul_f32_e32 v70, 0xbf317218, v70
	v_cvt_pk_bf16_f32 v58, v68, v70
	s_waitcnt lgkmcnt(0)
	v_mul_f32_e32 v72, 0xbf317218, v72
	v_mul_f32_e32 v76, 0xbf317218, v76
	v_cvt_pk_bf16_f32 v59, v72, v76
	v_lshlrev_b32_e32 v2, 11, v2
	global_store_dwordx4 v[50:51], v[56:59], off
	v_lshl_add_u64 v[50:51], v[74:75], 0, v[2:3]
	s_nop 0
	v_mul_f32_e32 v63, 0xbf317218, v63
	v_mul_f32_e32 v61, 0xbf317218, v61
	v_cvt_pk_bf16_f32 v56, v63, v61
	v_mul_f32_e32 v65, 0xbf317218, v65
	v_mul_f32_e32 v67, 0xbf317218, v67
	v_cvt_pk_bf16_f32 v57, v65, v67
	v_mul_f32_e32 v69, 0xbf317218, v69
	v_mul_f32_e32 v71, 0xbf317218, v71
	v_cvt_pk_bf16_f32 v58, v69, v71
	v_mul_f32_e32 v73, 0xbf317218, v73
	v_mul_f32_e32 v77, 0xbf317218, v77
	v_cvt_pk_bf16_f32 v59, v73, v77
	global_store_dwordx4 v[50:51], v[56:59], off
	s_waitcnt lgkmcnt(0)

.LBB0_1342:
	s_lshl_b32 s15, s4, 1
	s_lshl_b32 s16, s7, 1
	v_or_b32_e32 v2, s15, v1
	v_or_b32_e32 v90, s16, v0
	s_add_i32 s17, s15, 4
	s_add_i32 s18, s16, 4
	s_add_i32 s19, s15, 8
	s_add_i32 s20, s16, 8
	s_add_i32 s23, s15, 12
	s_add_i32 s35, s16, 12
	s_add_i32 s38, s15, 16
	s_add_i32 s39, s16, 16
	s_add_i32 s42, s15, 20
	s_add_i32 s43, s16, 20
	s_add_i32 s44, s15, 24
	s_add_i32 s45, s16, 24
	s_add_i32 s15, s15, 28
	s_add_i32 s16, s16, 28
	v_add_u32_e32 v56, s6, v90
	v_or_b32_e32 v91, s17, v1
	v_or_b32_e32 v92, s18, v0
	v_or_b32_e32 v93, s19, v1
	v_or_b32_e32 v94, s20, v0
	v_or_b32_e32 v95, s23, v1
	v_or_b32_e32 v96, s35, v0
	v_or_b32_e32 v97, s38, v1
	v_or_b32_e32 v98, s39, v0
	v_or_b32_e32 v99, s42, v1
	v_or_b32_e32 v100, s43, v0
	v_or_b32_e32 v101, s44, v1
	v_or_b32_e32 v102, s45, v0
	v_or_b32_e32 v103, s15, v1
	v_or_b32_e32 v104, s16, v0
	v_add_u32_e32 v58, s1, v2
	v_mad_i64_i32 v[56:57], s[16:17], v56, s13, v[50:51]
	v_add_u32_e32 v62, s1, v91
	v_add_u32_e32 v60, s6, v92
	v_add_u32_e32 v66, s1, v93
	v_add_u32_e32 v64, s6, v94
	v_add_u32_e32 v70, s1, v95
	v_add_u32_e32 v68, s6, v96
	v_add_u32_e32 v74, s1, v97
	v_add_u32_e32 v72, s6, v98
	v_add_u32_e32 v78, s1, v99
	v_add_u32_e32 v76, s6, v100
	v_add_u32_e32 v82, s1, v101
	v_add_u32_e32 v80, s6, v102
	v_add_u32_e32 v86, s1, v103
	v_add_u32_e32 v84, s6, v104
	v_mad_i64_i32 v[58:59], s[16:17], v58, s13, v[50:51]
	v_mad_i64_i32 v[60:61], s[16:17], v60, s13, v[50:51]
	v_mad_i64_i32 v[62:63], s[16:17], v62, s13, v[50:51]
	v_mad_i64_i32 v[64:65], s[16:17], v64, s13, v[50:51]
	v_mad_i64_i32 v[66:67], s[16:17], v66, s13, v[50:51]
	v_mad_i64_i32 v[68:69], s[16:17], v68, s13, v[50:51]
	v_mad_i64_i32 v[70:71], s[16:17], v70, s13, v[50:51]
	v_mad_i64_i32 v[72:73], s[16:17], v72, s13, v[50:51]
	v_mad_i64_i32 v[74:75], s[16:17], v74, s13, v[50:51]
	v_mad_i64_i32 v[76:77], s[16:17], v76, s13, v[50:51]
	v_mad_i64_i32 v[78:79], s[16:17], v78, s13, v[50:51]
	v_mad_i64_i32 v[80:81], s[16:17], v80, s13, v[50:51]
	v_mad_i64_i32 v[82:83], s[16:17], v82, s13, v[50:51]
	v_mad_i64_i32 v[84:85], s[16:17], v84, s13, v[50:51]
	v_mad_i64_i32 v[86:87], s[16:17], v86, s13, v[50:51]
	global_load_dword v105, v[56:57], off
	global_load_dword v106, v[58:59], off
	global_load_dword v107, v[60:61], off
	global_load_dword v108, v[62:63], off
	global_load_dword v109, v[64:65], off
	global_load_dword v110, v[66:67], off
	global_load_dword v111, v[68:69], off
	global_load_dword v112, v[70:71], off
	global_load_dword v113, v[72:73], off
	global_load_dword v114, v[74:75], off
	global_load_dword v115, v[76:77], off
	global_load_dword v116, v[78:79], off
	global_load_dword v117, v[80:81], off
	global_load_dword v118, v[82:83], off
	global_load_dword v119, v[84:85], off
	global_load_dword v120, v[86:87], off
	s_add_i32 s7, s7, 16
	s_add_i32 s4, s4, 16
	s_add_i32 s9, s9, -16
	v_mad_u64_u32 v[56:57], s[16:17], v90, s3, v[6:7]
	s_cmp_lg_u32 s9, 0
	v_mad_u64_u32 v[58:59], s[16:17], v2, s3, v[6:7]
	v_mad_u64_u32 v[60:61], s[16:17], v92, s3, v[6:7]
	v_mad_u64_u32 v[62:63], s[16:17], v91, s3, v[6:7]
	v_mad_u64_u32 v[64:65], s[16:17], v94, s3, v[6:7]
	v_mad_u64_u32 v[66:67], s[16:17], v93, s3, v[6:7]
	v_mad_u64_u32 v[68:69], s[16:17], v96, s3, v[6:7]
	v_mad_u64_u32 v[70:71], s[16:17], v95, s3, v[6:7]
	v_mad_u64_u32 v[72:73], s[16:17], v98, s3, v[6:7]
	v_mad_u64_u32 v[74:75], s[16:17], v97, s3, v[6:7]
	v_mad_u64_u32 v[76:77], s[16:17], v100, s3, v[6:7]
	v_mad_u64_u32 v[78:79], s[16:17], v99, s3, v[6:7]
	v_mad_u64_u32 v[80:81], s[16:17], v102, s3, v[6:7]
	v_mad_u64_u32 v[82:83], s[16:17], v101, s3, v[6:7]
	v_mad_u64_u32 v[84:85], s[16:17], v104, s3, v[6:7]
	v_mad_u64_u32 v[86:87], s[16:17], v103, s3, v[6:7]
	s_waitcnt vmcnt(15)
	ds_write_b32 v56, v105
	s_waitcnt vmcnt(14)
	ds_write_b32 v58, v106
	s_waitcnt vmcnt(13)
	ds_write_b32 v60, v107
	s_waitcnt vmcnt(12)
	ds_write_b32 v62, v108
	s_waitcnt vmcnt(11)
	ds_write_b32 v64, v109
	s_waitcnt vmcnt(10)
	ds_write_b32 v66, v110
	s_waitcnt vmcnt(9)
	ds_write_b32 v68, v111
	s_waitcnt vmcnt(8)
	ds_write_b32 v70, v112
	s_waitcnt vmcnt(7)
	ds_write_b32 v72, v113
	s_waitcnt vmcnt(6)
	ds_write_b32 v74, v114
	s_waitcnt vmcnt(5)
	ds_write_b32 v76, v115
	s_waitcnt vmcnt(4)
	ds_write_b32 v78, v116
	s_waitcnt vmcnt(3)
	ds_write_b32 v80, v117
	s_waitcnt vmcnt(2)
	ds_write_b32 v82, v118
	s_waitcnt vmcnt(1)
	ds_write_b32 v84, v119
	s_waitcnt vmcnt(0)
	ds_write_b32 v86, v120
	s_cbranch_scc1 .LBB0_1342
	s_lshl_b32 s0, s0, 6
	s_waitcnt lgkmcnt(0)
	s_and_b32 s0, s0, 0xffffff00
	s_and_b32 s1, s8, 0x60
	ds_read2_b32 v[50:51], v52 offset0:33 offset1:41
	ds_read2_b32 v[60:61], v52 offset1:8
	ds_read2_b32 v[62:63], v52 offset0:66 offset1:74
	ds_read2_b32 v[64:65], v52 offset0:99 offset1:107
	ds_read2_b32 v[66:67], v52 offset0:132 offset1:140
	ds_read2_b32 v[68:69], v52 offset0:165 offset1:173
	ds_read2_b32 v[70:71], v52 offset0:198 offset1:206
	ds_read2_b32 v[72:73], v52 offset0:231 offset1:239
	s_or_b32 s0, s1, s0
	v_or_b32_e32 v76, s0, v7
	s_ashr_i32 s7, s6, 31
	v_ashrrev_i32_e32 v77, 31, v76
	v_lshl_add_u64 v[74:75], s[6:7], 1, v[20:21]
	v_lshlrev_b64 v[76:77], 11, v[76:77]
	s_waitcnt lgkmcnt(6)
	v_mul_f32_e32 v60, 0xbfb8aa3b, v60
	v_mul_f32_e32 v50, 0xbfb8aa3b, v50
	v_cvt_pk_bf16_f32 v56, v60, v50
	s_waitcnt lgkmcnt(4)
	v_mul_f32_e32 v62, 0xbfb8aa3b, v62
	v_mul_f32_e32 v64, 0xbfb8aa3b, v64
	v_cvt_pk_bf16_f32 v57, v62, v64
	s_waitcnt lgkmcnt(2)
	v_mul_f32_e32 v66, 0xbfb8aa3b, v66
	v_mul_f32_e32 v68, 0xbfb8aa3b, v68
	v_cvt_pk_bf16_f32 v58, v66, v68
	s_waitcnt lgkmcnt(0)
	v_mul_f32_e32 v70, 0xbfb8aa3b, v70
	v_mul_f32_e32 v72, 0xbfb8aa3b, v72
	v_cvt_pk_bf16_f32 v59, v70, v72
	v_lshl_add_u64 v[76:77], v[74:75], 0, v[76:77]
	v_or_b32_e32 v50, s0, v53
	global_store_dwordx4 v[76:77], v[56:59], off
	s_nop 1
	v_mul_f32_e32 v61, 0xbfb8aa3b, v61
	v_mul_f32_e32 v51, 0xbfb8aa3b, v51
	v_cvt_pk_bf16_f32 v56, v61, v51
	v_ashrrev_i32_e32 v51, 31, v50
	v_mul_f32_e32 v63, 0xbfb8aa3b, v63
	v_mul_f32_e32 v65, 0xbfb8aa3b, v65
	v_cvt_pk_bf16_f32 v57, v63, v65
	v_mul_f32_e32 v67, 0xbfb8aa3b, v67
	v_mul_f32_e32 v69, 0xbfb8aa3b, v69
	v_cvt_pk_bf16_f32 v58, v67, v69
	v_mul_f32_e32 v71, 0xbfb8aa3b, v71
	v_mul_f32_e32 v73, 0xbfb8aa3b, v73
	v_cvt_pk_bf16_f32 v59, v71, v73
	v_lshlrev_b64 v[50:51], 11, v[50:51]
	ds_read2_b32 v[60:61], v52 offset0:49 offset1:57
	ds_read2_b32 v[62:63], v52 offset0:16 offset1:24
	ds_read2_b32 v[64:65], v52 offset0:82 offset1:90
	ds_read2_b32 v[66:67], v52 offset0:115 offset1:123
	ds_read2_b32 v[68:69], v52 offset0:148 offset1:156
	ds_read2_b32 v[70:71], v52 offset0:181 offset1:189
	ds_read2_b32 v[72:73], v52 offset0:214 offset1:222
	ds_read2_b32 v[76:77], v52 offset0:247 offset1:255
	v_lshl_add_u64 v[50:51], v[74:75], 0, v[50:51]
	global_store_dwordx4 v[50:51], v[56:59], off
	v_or_b32_e32 v50, s0, v54
	v_ashrrev_i32_e32 v51, 31, v50
	v_lshlrev_b64 v[50:51], 11, v[50:51]
	s_waitcnt lgkmcnt(6)
	v_mul_f32_e32 v62, 0xbfb8aa3b, v62
	v_mul_f32_e32 v60, 0xbfb8aa3b, v60
	v_cvt_pk_bf16_f32 v56, v62, v60
	s_waitcnt lgkmcnt(4)
	v_mul_f32_e32 v64, 0xbfb8aa3b, v64
	v_mul_f32_e32 v66, 0xbfb8aa3b, v66
	v_cvt_pk_bf16_f32 v57, v64, v66
	s_waitcnt lgkmcnt(2)
	v_mul_f32_e32 v68, 0xbfb8aa3b, v68
	v_mul_f32_e32 v70, 0xbfb8aa3b, v70
	v_cvt_pk_bf16_f32 v58, v68, v70
	s_waitcnt lgkmcnt(0)
	v_mul_f32_e32 v72, 0xbfb8aa3b, v72
	v_mul_f32_e32 v76, 0xbfb8aa3b, v76
	v_cvt_pk_bf16_f32 v59, v72, v76
	v_lshl_add_u64 v[50:51], v[74:75], 0, v[50:51]
	global_store_dwordx4 v[50:51], v[56:59], off
	v_or_b32_e32 v50, s0, v55
	v_ashrrev_i32_e32 v51, 31, v50
	v_lshlrev_b64 v[50:51], 11, v[50:51]
	v_mul_f32_e32 v63, 0xbfb8aa3b, v63
	v_mul_f32_e32 v61, 0xbfb8aa3b, v61
	v_cvt_pk_bf16_f32 v56, v63, v61
	v_mul_f32_e32 v65, 0xbfb8aa3b, v65
	v_mul_f32_e32 v67, 0xbfb8aa3b, v67
	v_cvt_pk_bf16_f32 v57, v65, v67
	v_mul_f32_e32 v69, 0xbfb8aa3b, v69
	v_mul_f32_e32 v71, 0xbfb8aa3b, v71
	v_cvt_pk_bf16_f32 v58, v69, v71
	v_mul_f32_e32 v73, 0xbfb8aa3b, v73
	v_mul_f32_e32 v77, 0xbfb8aa3b, v77
	v_cvt_pk_bf16_f32 v59, v73, v77
	v_lshl_add_u64 v[50:51], v[74:75], 0, v[50:51]
	global_store_dwordx4 v[50:51], v[56:59], off
	s_waitcnt lgkmcnt(0)
	s_branch .LBB0_1275

.LBB0_2262:
	v_exp_f32_e32 v144, v124
	v_exp_f32_e32 v145, v125
	v_lshl_or_b32 v154, s58, 7, v149
	v_add_f32_e32 v144, 1.0, v144
	v_rcp_f32_e32 v156, v144
	v_add_f32_e32 v144, 1.0, v145
	v_rcp_f32_e32 v157, v144
	v_lshl_add_u32 v153, s18, 8, v147
	v_ashrrev_i32_e32 v155, 31, v154
	v_mov_b64_e32 v[144:145], s[36:37]
	v_pk_mul_f32 v[124:125], v[124:125], v[156:157]
	v_exp_f32_e32 v156, v126
	v_exp_f32_e32 v157, v127
	v_pk_mul_f32 v[116:117], v[124:125], v[116:117]
	v_mad_i64_i32 v[158:159], s[0:1], v153, s57, v[144:145]
	v_add_f32_e32 v124, 1.0, v156
	v_add_f32_e32 v125, 1.0, v157
	v_rcp_f32_e32 v124, v124
	v_rcp_f32_e32 v125, v125
	v_exp_f32_e32 v156, v120
	v_exp_f32_e32 v157, v121
	s_andn2_b64 vcc, exec, s[2:3]
	v_pk_mul_f32 v[124:125], v[126:127], v[124:125]
	v_add_f32_e32 v126, 1.0, v156
	v_add_f32_e32 v127, 1.0, v157
	v_exp_f32_e32 v156, v122
	v_exp_f32_e32 v157, v123
	v_rcp_f32_e32 v126, v126
	v_rcp_f32_e32 v127, v127
	v_add_f32_e32 v156, 1.0, v156
	v_add_f32_e32 v157, 1.0, v157
	v_rcp_f32_e32 v156, v156
	v_rcp_f32_e32 v157, v157
	v_pk_mul_f32 v[120:121], v[120:121], v[126:127]
	v_pk_mul_f32 v[118:119], v[124:125], v[118:119]
	v_pk_mul_f32 v[120:121], v[120:121], v[112:113]
	v_pk_mul_f32 v[112:113], v[122:123], v[156:157]
	s_nop 0
	v_pk_mul_f32 v[122:123], v[112:113], v[114:115]
	v_cvt_pk_bf16_f32 v115, v118, v119
	v_exp_f32_e32 v118, v108
	v_exp_f32_e32 v119, v109
	v_lshlrev_b64 v[112:113], 1, v[154:155]
	v_lshl_add_u64 v[124:125], v[158:159], 0, v[112:113]
	v_cvt_pk_bf16_f32 v114, v116, v117
	v_cvt_pk_bf16_f32 v116, v120, v121
	v_cvt_pk_bf16_f32 v117, v122, v123
	global_store_dwordx4 v[124:125], v[114:117], off
	s_nop 1
	v_add_f32_e32 v114, 1.0, v118
	v_add_f32_e32 v115, 1.0, v119
	v_rcp_f32_e32 v114, v114
	v_rcp_f32_e32 v115, v115
	v_or_b32_e32 v116, 16, v153
	v_mad_i64_i32 v[116:117], s[0:1], v116, s57, v[144:145]
	v_pk_mul_f32 v[108:109], v[108:109], v[114:115]
	v_exp_f32_e32 v114, v110
	v_exp_f32_e32 v115, v111
	v_pk_mul_f32 v[100:101], v[108:109], v[100:101]
	v_add_f32_e32 v108, 1.0, v114
	v_add_f32_e32 v109, 1.0, v115
	v_rcp_f32_e32 v108, v108
	v_rcp_f32_e32 v109, v109
	v_exp_f32_e32 v114, v104
	v_exp_f32_e32 v115, v105
	v_pk_mul_f32 v[108:109], v[110:111], v[108:109]
	v_add_f32_e32 v110, 1.0, v114
	v_add_f32_e32 v111, 1.0, v115
	v_exp_f32_e32 v114, v106
	v_exp_f32_e32 v115, v107
	v_rcp_f32_e32 v110, v110
	v_rcp_f32_e32 v111, v111
	v_add_f32_e32 v114, 1.0, v114
	v_add_f32_e32 v115, 1.0, v115
	v_rcp_f32_e32 v114, v114
	v_rcp_f32_e32 v115, v115
	v_pk_mul_f32 v[104:105], v[104:105], v[110:111]
	v_pk_mul_f32 v[102:103], v[108:109], v[102:103]
	v_pk_mul_f32 v[104:105], v[104:105], v[96:97]
	v_pk_mul_f32 v[96:97], v[106:107], v[114:115]
	v_lshl_add_u64 v[108:109], v[116:117], 0, v[112:113]
	v_pk_mul_f32 v[106:107], v[96:97], v[98:99]
	v_cvt_pk_bf16_f32 v96, v100, v101
	v_exp_f32_e32 v100, v92
	v_exp_f32_e32 v101, v93
	v_cvt_pk_bf16_f32 v97, v102, v103
	v_cvt_pk_bf16_f32 v98, v104, v105
	v_cvt_pk_bf16_f32 v99, v106, v107
	global_store_dwordx4 v[108:109], v[96:99], off
	s_nop 1
	v_add_f32_e32 v96, 1.0, v100
	v_add_f32_e32 v97, 1.0, v101
	v_rcp_f32_e32 v96, v96
	v_rcp_f32_e32 v97, v97
	v_or_b32_e32 v98, 32, v153
	v_mad_i64_i32 v[98:99], s[0:1], v98, s57, v[144:145]
	v_pk_mul_f32 v[92:93], v[92:93], v[96:97]
	v_exp_f32_e32 v96, v94
	v_exp_f32_e32 v97, v95
	v_pk_mul_f32 v[84:85], v[92:93], v[84:85]
	v_add_f32_e32 v92, 1.0, v96
	v_add_f32_e32 v93, 1.0, v97
	v_rcp_f32_e32 v92, v92
	v_rcp_f32_e32 v93, v93
	v_exp_f32_e32 v96, v88
	v_exp_f32_e32 v97, v89
	v_pk_mul_f32 v[92:93], v[94:95], v[92:93]
	v_add_f32_e32 v94, 1.0, v96
	v_add_f32_e32 v95, 1.0, v97
	v_exp_f32_e32 v96, v90
	v_exp_f32_e32 v97, v91
	v_rcp_f32_e32 v94, v94
	v_rcp_f32_e32 v95, v95
	v_add_f32_e32 v96, 1.0, v96
	v_add_f32_e32 v97, 1.0, v97
	v_rcp_f32_e32 v96, v96
	v_rcp_f32_e32 v97, v97
	v_pk_mul_f32 v[88:89], v[88:89], v[94:95]
	v_pk_mul_f32 v[86:87], v[92:93], v[86:87]
	v_pk_mul_f32 v[88:89], v[88:89], v[80:81]
	v_pk_mul_f32 v[80:81], v[90:91], v[96:97]
	v_lshl_add_u64 v[92:93], v[98:99], 0, v[112:113]
	v_pk_mul_f32 v[90:91], v[80:81], v[82:83]
	v_cvt_pk_bf16_f32 v80, v84, v85
	v_exp_f32_e32 v84, v76
	v_exp_f32_e32 v85, v77
	v_cvt_pk_bf16_f32 v81, v86, v87
	v_cvt_pk_bf16_f32 v82, v88, v89
	v_cvt_pk_bf16_f32 v83, v90, v91
	global_store_dwordx4 v[92:93], v[80:83], off
	s_nop 1
	v_add_f32_e32 v80, 1.0, v84
	v_add_f32_e32 v81, 1.0, v85
	v_rcp_f32_e32 v80, v80
	v_rcp_f32_e32 v81, v81
	v_or_b32_e32 v82, 48, v153
	v_mad_i64_i32 v[82:83], s[0:1], v82, s57, v[144:145]
	v_pk_mul_f32 v[76:77], v[76:77], v[80:81]
	v_exp_f32_e32 v80, v78
	v_exp_f32_e32 v81, v79
	v_pk_mul_f32 v[68:69], v[76:77], v[68:69]
	v_add_f32_e32 v76, 1.0, v80
	v_add_f32_e32 v77, 1.0, v81
	v_rcp_f32_e32 v76, v76
	v_rcp_f32_e32 v77, v77
	v_exp_f32_e32 v80, v72
	v_exp_f32_e32 v81, v73
	v_pk_mul_f32 v[76:77], v[78:79], v[76:77]
	v_add_f32_e32 v78, 1.0, v80
	v_add_f32_e32 v79, 1.0, v81
	v_exp_f32_e32 v80, v74
	v_exp_f32_e32 v81, v75
	v_rcp_f32_e32 v78, v78
	v_rcp_f32_e32 v79, v79
	v_add_f32_e32 v80, 1.0, v80
	v_add_f32_e32 v81, 1.0, v81
	v_rcp_f32_e32 v80, v80
	v_rcp_f32_e32 v81, v81
	v_pk_mul_f32 v[72:73], v[72:73], v[78:79]
	v_pk_mul_f32 v[70:71], v[76:77], v[70:71]
	v_pk_mul_f32 v[72:73], v[72:73], v[64:65]
	v_pk_mul_f32 v[64:65], v[74:75], v[80:81]
	v_lshl_add_u64 v[76:77], v[82:83], 0, v[112:113]
	v_pk_mul_f32 v[74:75], v[64:65], v[66:67]
	v_cvt_pk_bf16_f32 v64, v68, v69
	v_exp_f32_e32 v68, v60
	v_exp_f32_e32 v69, v61
	v_cvt_pk_bf16_f32 v65, v70, v71
	v_cvt_pk_bf16_f32 v66, v72, v73
	v_cvt_pk_bf16_f32 v67, v74, v75
	global_store_dwordx4 v[76:77], v[64:67], off
	s_nop 1
	v_add_f32_e32 v64, 1.0, v68
	v_add_f32_e32 v65, 1.0, v69
	v_rcp_f32_e32 v64, v64
	v_rcp_f32_e32 v65, v65
	v_add_u32_e32 v66, 0x80, v153
	v_mad_i64_i32 v[66:67], s[0:1], v66, s57, v[144:145]
	v_pk_mul_f32 v[60:61], v[60:61], v[64:65]
	v_exp_f32_e32 v64, v62
	v_exp_f32_e32 v65, v63
	v_pk_mul_f32 v[52:53], v[60:61], v[52:53]
	v_add_f32_e32 v60, 1.0, v64
	v_add_f32_e32 v61, 1.0, v65
	v_rcp_f32_e32 v60, v60
	v_rcp_f32_e32 v61, v61
	v_exp_f32_e32 v64, v56
	v_exp_f32_e32 v65, v57
	v_pk_mul_f32 v[60:61], v[62:63], v[60:61]
	v_add_f32_e32 v62, 1.0, v64
	v_add_f32_e32 v63, 1.0, v65
	v_exp_f32_e32 v64, v58
	v_exp_f32_e32 v65, v59
	v_rcp_f32_e32 v62, v62
	v_rcp_f32_e32 v63, v63
	v_add_f32_e32 v64, 1.0, v64
	v_add_f32_e32 v65, 1.0, v65
	v_rcp_f32_e32 v64, v64
	v_rcp_f32_e32 v65, v65
	v_pk_mul_f32 v[56:57], v[56:57], v[62:63]
	v_pk_mul_f32 v[54:55], v[60:61], v[54:55]
	v_pk_mul_f32 v[56:57], v[56:57], v[48:49]
	v_pk_mul_f32 v[48:49], v[58:59], v[64:65]
	v_lshl_add_u64 v[60:61], v[66:67], 0, v[112:113]
	v_pk_mul_f32 v[58:59], v[48:49], v[50:51]
	v_cvt_pk_bf16_f32 v48, v52, v53
	v_exp_f32_e32 v52, v44
	v_exp_f32_e32 v53, v45
	v_cvt_pk_bf16_f32 v49, v54, v55
	v_cvt_pk_bf16_f32 v50, v56, v57
	v_cvt_pk_bf16_f32 v51, v58, v59
	global_store_dwordx4 v[60:61], v[48:51], off
	s_nop 1
	v_add_f32_e32 v48, 1.0, v52
	v_add_f32_e32 v49, 1.0, v53
	v_rcp_f32_e32 v48, v48
	v_rcp_f32_e32 v49, v49
	v_add_u32_e32 v50, 0x90, v153
	v_mad_i64_i32 v[50:51], s[0:1], v50, s57, v[144:145]
	v_pk_mul_f32 v[44:45], v[44:45], v[48:49]
	v_exp_f32_e32 v48, v46
	v_exp_f32_e32 v49, v47
	v_pk_mul_f32 v[36:37], v[44:45], v[36:37]
	v_add_f32_e32 v44, 1.0, v48
	v_add_f32_e32 v45, 1.0, v49
	v_rcp_f32_e32 v44, v44
	v_rcp_f32_e32 v45, v45
	v_exp_f32_e32 v48, v40
	v_exp_f32_e32 v49, v41
	v_pk_mul_f32 v[44:45], v[46:47], v[44:45]
	v_add_f32_e32 v46, 1.0, v48
	v_add_f32_e32 v47, 1.0, v49
	v_exp_f32_e32 v48, v42
	v_exp_f32_e32 v49, v43
	v_rcp_f32_e32 v46, v46
	v_rcp_f32_e32 v47, v47
	v_add_f32_e32 v48, 1.0, v48
	v_add_f32_e32 v49, 1.0, v49
	v_rcp_f32_e32 v48, v48
	v_rcp_f32_e32 v49, v49
	v_pk_mul_f32 v[40:41], v[40:41], v[46:47]
	v_pk_mul_f32 v[38:39], v[44:45], v[38:39]
	v_pk_mul_f32 v[40:41], v[40:41], v[32:33]
	v_pk_mul_f32 v[32:33], v[42:43], v[48:49]
	v_lshl_add_u64 v[44:45], v[50:51], 0, v[112:113]
	v_pk_mul_f32 v[42:43], v[32:33], v[34:35]
	v_cvt_pk_bf16_f32 v32, v36, v37
	v_exp_f32_e32 v36, v28
	v_exp_f32_e32 v37, v29
	v_cvt_pk_bf16_f32 v33, v38, v39
	v_cvt_pk_bf16_f32 v34, v40, v41
	v_cvt_pk_bf16_f32 v35, v42, v43
	global_store_dwordx4 v[44:45], v[32:35], off
	s_nop 1
	v_add_f32_e32 v32, 1.0, v36
	v_add_f32_e32 v33, 1.0, v37
	v_rcp_f32_e32 v32, v32
	v_rcp_f32_e32 v33, v33
	v_add_u32_e32 v34, 0xa0, v153
	v_mad_i64_i32 v[34:35], s[0:1], v34, s57, v[144:145]
	v_pk_mul_f32 v[28:29], v[28:29], v[32:33]
	v_exp_f32_e32 v32, v30
	v_exp_f32_e32 v33, v31
	v_pk_mul_f32 v[20:21], v[28:29], v[20:21]
	v_add_f32_e32 v28, 1.0, v32
	v_add_f32_e32 v29, 1.0, v33
	v_rcp_f32_e32 v28, v28
	v_rcp_f32_e32 v29, v29
	v_exp_f32_e32 v32, v24
	v_exp_f32_e32 v33, v25
	v_pk_mul_f32 v[28:29], v[30:31], v[28:29]
	v_add_f32_e32 v30, 1.0, v32
	v_add_f32_e32 v31, 1.0, v33
	v_exp_f32_e32 v32, v26
	v_exp_f32_e32 v33, v27
	v_rcp_f32_e32 v30, v30
	v_rcp_f32_e32 v31, v31
	v_add_f32_e32 v32, 1.0, v32
	v_add_f32_e32 v33, 1.0, v33
	v_rcp_f32_e32 v32, v32
	v_rcp_f32_e32 v33, v33
	v_pk_mul_f32 v[24:25], v[24:25], v[30:31]
	v_pk_mul_f32 v[22:23], v[28:29], v[22:23]
	v_pk_mul_f32 v[24:25], v[24:25], v[16:17]
	v_pk_mul_f32 v[16:17], v[26:27], v[32:33]
	v_lshl_add_u64 v[28:29], v[34:35], 0, v[112:113]
	v_pk_mul_f32 v[26:27], v[16:17], v[18:19]
	v_cvt_pk_bf16_f32 v16, v20, v21
	v_exp_f32_e32 v20, v12
	v_exp_f32_e32 v21, v13
	v_cvt_pk_bf16_f32 v17, v22, v23
	v_cvt_pk_bf16_f32 v18, v24, v25
	v_cvt_pk_bf16_f32 v19, v26, v27
	global_store_dwordx4 v[28:29], v[16:19], off
	s_nop 1
	v_add_f32_e32 v16, 1.0, v20
	v_add_f32_e32 v17, 1.0, v21
	v_rcp_f32_e32 v16, v16
	v_rcp_f32_e32 v17, v17
	v_add_u32_e32 v18, 0xb0, v153
	v_mad_i64_i32 v[18:19], s[0:1], v18, s57, v[144:145]
	v_pk_mul_f32 v[12:13], v[12:13], v[16:17]
	v_exp_f32_e32 v16, v14
	v_exp_f32_e32 v17, v15
	v_pk_mul_f32 v[4:5], v[12:13], v[4:5]
	s_mov_b64 s[0:1], -1
	v_add_f32_e32 v12, 1.0, v16
	v_add_f32_e32 v13, 1.0, v17
	v_rcp_f32_e32 v12, v12
	v_rcp_f32_e32 v13, v13
	v_exp_f32_e32 v16, v8
	v_exp_f32_e32 v17, v9
	v_pk_mul_f32 v[12:13], v[14:15], v[12:13]
	v_add_f32_e32 v14, 1.0, v16
	v_add_f32_e32 v15, 1.0, v17
	v_exp_f32_e32 v16, v10
	v_exp_f32_e32 v17, v11
	v_rcp_f32_e32 v14, v14
	v_rcp_f32_e32 v15, v15
	v_add_f32_e32 v16, 1.0, v16
	v_add_f32_e32 v17, 1.0, v17
	v_rcp_f32_e32 v16, v16
	v_rcp_f32_e32 v17, v17
	v_pk_mul_f32 v[8:9], v[8:9], v[14:15]
	v_pk_mul_f32 v[6:7], v[12:13], v[6:7]
	v_pk_mul_f32 v[8:9], v[8:9], v[0:1]
	v_pk_mul_f32 v[0:1], v[10:11], v[16:17]
	v_lshl_add_u64 v[12:13], v[18:19], 0, v[112:113]
	v_pk_mul_f32 v[10:11], v[0:1], v[2:3]
	v_cvt_pk_bf16_f32 v0, v4, v5
	v_cvt_pk_bf16_f32 v1, v6, v7
	v_cvt_pk_bf16_f32 v2, v8, v9
	v_cvt_pk_bf16_f32 v3, v10, v11
	global_store_dwordx4 v[12:13], v[0:3], off
	s_cbranch_vccnz .LBB0_2255
	s_andn2_b64 vcc, exec, s[4:5]
	s_cbranch_vccnz .LBB0_2254
	s_barrier
	s_branch .LBB0_2254

.LBB0_2501:
	v_lshl_add_u32 v148, s48, 8, v151
	v_lshl_or_b32 v144, s62, 8, v153
	v_ashrrev_i32_e32 v149, 31, v148
	v_ashrrev_i32_e32 v145, 31, v144
	v_lshlrev_b64 v[146:147], 10, v[148:149]
	v_lshl_add_u64 v[158:159], v[146:147], 0, v[144:145]
	v_lshlrev_b64 v[162:163], 1, v[158:159]
	v_lshl_add_u64 v[158:159], s[36:37], 0, v[162:163]
	global_load_dwordx4 v[158:161], v[158:159], off
	v_exp_f32_e32 v124, v124
	v_exp_f32_e32 v125, v125
	v_exp_f32_e32 v149, v126
	v_exp_f32_e32 v157, v127
	v_exp_f32_e32 v164, v120
	v_exp_f32_e32 v165, v121
	v_exp_f32_e32 v166, v122
	v_exp_f32_e32 v167, v123
	v_or_b32_e32 v120, 0x80, v144
	v_mov_b32_e32 v121, v145
	v_lshl_add_u64 v[122:123], v[146:147], 0, v[120:121]
	v_lshlrev_b64 v[126:127], 1, v[122:123]
	v_add_f32_e32 v122, 1.0, v124
	v_add_f32_e32 v123, 1.0, v125
	v_add_f32_e32 v124, 1.0, v149
	v_add_f32_e32 v125, 1.0, v157
	v_add_f32_e32 v149, 1.0, v164
	v_add_f32_e32 v157, 1.0, v165
	v_add_f32_e32 v168, 1.0, v166
	v_add_f32_e32 v169, 1.0, v167
	v_rcp_f32_e32 v122, v122
	v_rcp_f32_e32 v123, v123
	v_rcp_f32_e32 v124, v124
	v_rcp_f32_e32 v125, v125
	v_rcp_f32_e32 v166, v149
	v_rcp_f32_e32 v167, v157
	v_rcp_f32_e32 v168, v168
	v_rcp_f32_e32 v169, v169
	v_lshl_add_u64 v[162:163], s[40:41], 0, v[162:163]
	v_lshl_add_u64 v[164:165], s[36:37], 0, v[126:127]
	v_exp_f32_e32 v149, v116
	v_exp_f32_e32 v157, v117
	v_exp_f32_e32 v118, v118
	v_exp_f32_e32 v119, v119
	v_exp_f32_e32 v114, v114
	v_exp_f32_e32 v115, v115
	v_add_f32_e32 v149, 1.0, v149
	v_add_f32_e32 v157, 1.0, v157
	v_exp_f32_e32 v108, v108
	v_exp_f32_e32 v109, v109
	v_exp_f32_e32 v110, v110
	v_exp_f32_e32 v111, v111
	v_exp_f32_e32 v106, v106
	v_exp_f32_e32 v107, v107
	v_add_f32_e32 v110, 1.0, v110
	v_add_f32_e32 v111, 1.0, v111
	v_exp_f32_e32 v102, v102
	s_waitcnt vmcnt(0)
	v_lshlrev_b32_e32 v170, 16, v158
	v_and_b32_e32 v171, 0xffff0000, v158
	v_lshlrev_b32_e32 v158, 16, v159
	v_and_b32_e32 v159, 0xffff0000, v159
	v_lshlrev_b32_e32 v172, 16, v160
	v_and_b32_e32 v173, 0xffff0000, v160
	v_lshlrev_b32_e32 v160, 16, v161
	v_and_b32_e32 v161, 0xffff0000, v161
	v_pk_mul_f32 v[122:123], v[122:123], v[170:171]
	v_pk_mul_f32 v[124:125], v[124:125], v[158:159]
	v_pk_mul_f32 v[158:159], v[166:167], v[172:173]
	v_pk_mul_f32 v[160:161], v[168:169], v[160:161]
	v_cvt_pk_bf16_f32 v122, v122, v123
	v_cvt_pk_bf16_f32 v123, v124, v125
	v_cvt_pk_bf16_f32 v124, v158, v159
	v_cvt_pk_bf16_f32 v125, v160, v161
	global_store_dwordx4 v[162:163], v[122:125], off
	global_load_dwordx4 v[122:125], v[164:165], off
	v_exp_f32_e32 v158, v112
	v_exp_f32_e32 v159, v113
	v_or_b32_e32 v112, 16, v148
	v_ashrrev_i32_e32 v113, 31, v112
	v_lshlrev_b64 v[116:117], 10, v[112:113]
	v_lshl_add_u64 v[112:113], v[116:117], 0, v[144:145]
	v_add_f32_e32 v160, 1.0, v118
	v_add_f32_e32 v161, 1.0, v119
	v_add_f32_e32 v158, 1.0, v158
	v_add_f32_e32 v159, 1.0, v159
	v_add_f32_e32 v162, 1.0, v114
	v_add_f32_e32 v163, 1.0, v115
	v_lshl_add_u64 v[118:119], s[40:41], 0, v[126:127]
	v_lshlrev_b64 v[126:127], 1, v[112:113]
	v_rcp_f32_e32 v112, v149
	v_rcp_f32_e32 v113, v157
	v_rcp_f32_e32 v114, v160
	v_rcp_f32_e32 v115, v161
	v_rcp_f32_e32 v158, v158
	v_rcp_f32_e32 v159, v159
	v_rcp_f32_e32 v160, v162
	v_rcp_f32_e32 v161, v163
	v_lshl_add_u64 v[162:163], s[36:37], 0, v[126:127]
	v_exp_f32_e32 v103, v103
	v_exp_f32_e32 v98, v98
	v_exp_f32_e32 v99, v99
	v_exp_f32_e32 v92, v92
	v_exp_f32_e32 v93, v93
	v_exp_f32_e32 v94, v94
	v_exp_f32_e32 v95, v95
	v_exp_f32_e32 v90, v90
	v_exp_f32_e32 v91, v91
	v_add_f32_e32 v94, 1.0, v94
	v_add_f32_e32 v95, 1.0, v95
	v_exp_f32_e32 v86, v86
	v_exp_f32_e32 v87, v87
	v_exp_f32_e32 v82, v82
	v_exp_f32_e32 v83, v83
	v_exp_f32_e32 v76, v76
	v_exp_f32_e32 v77, v77
	v_exp_f32_e32 v78, v78
	v_exp_f32_e32 v79, v79
	v_exp_f32_e32 v74, v74
	v_exp_f32_e32 v75, v75
	v_add_f32_e32 v78, 1.0, v78
	v_add_f32_e32 v79, 1.0, v79
	v_exp_f32_e32 v70, v70
	s_waitcnt vmcnt(0)
	v_lshlrev_b32_e32 v164, 16, v122
	v_and_b32_e32 v165, 0xffff0000, v122
	v_lshlrev_b32_e32 v122, 16, v123
	v_and_b32_e32 v123, 0xffff0000, v123
	v_lshlrev_b32_e32 v166, 16, v124
	v_and_b32_e32 v167, 0xffff0000, v124
	v_lshlrev_b32_e32 v124, 16, v125
	v_and_b32_e32 v125, 0xffff0000, v125
	v_pk_mul_f32 v[112:113], v[112:113], v[164:165]
	v_pk_mul_f32 v[114:115], v[114:115], v[122:123]
	v_pk_mul_f32 v[122:123], v[158:159], v[166:167]
	v_pk_mul_f32 v[124:125], v[160:161], v[124:125]
	v_cvt_pk_bf16_f32 v112, v112, v113
	v_cvt_pk_bf16_f32 v113, v114, v115
	v_cvt_pk_bf16_f32 v114, v122, v123
	v_cvt_pk_bf16_f32 v115, v124, v125
	global_store_dwordx4 v[118:119], v[112:115], off
	global_load_dwordx4 v[112:115], v[162:163], off
	v_exp_f32_e32 v118, v104
	v_exp_f32_e32 v119, v105
	v_lshl_add_u64 v[104:105], v[116:117], 0, v[120:121]
	v_add_f32_e32 v116, 1.0, v108
	v_add_f32_e32 v117, 1.0, v109
	v_add_f32_e32 v118, 1.0, v118
	v_add_f32_e32 v119, 1.0, v119
	v_add_f32_e32 v122, 1.0, v106
	v_add_f32_e32 v123, 1.0, v107
	v_lshlrev_b64 v[108:109], 1, v[104:105]
	v_rcp_f32_e32 v104, v116
	v_rcp_f32_e32 v105, v117
	v_rcp_f32_e32 v106, v110
	v_rcp_f32_e32 v107, v111
	v_rcp_f32_e32 v110, v118
	v_rcp_f32_e32 v111, v119
	v_rcp_f32_e32 v116, v122
	v_rcp_f32_e32 v117, v123
	v_lshl_add_u64 v[118:119], s[40:41], 0, v[126:127]
	v_lshl_add_u64 v[122:123], s[36:37], 0, v[108:109]
	v_lshl_add_u64 v[108:109], s[40:41], 0, v[108:109]
	v_exp_f32_e32 v71, v71
	v_exp_f32_e32 v66, v66
	v_exp_f32_e32 v67, v67
	v_exp_f32_e32 v60, v60
	v_exp_f32_e32 v61, v61
	v_exp_f32_e32 v62, v62
	v_exp_f32_e32 v63, v63
	v_exp_f32_e32 v58, v58
	v_exp_f32_e32 v59, v59
	v_add_f32_e32 v62, 1.0, v62
	v_add_f32_e32 v63, 1.0, v63
	v_exp_f32_e32 v54, v54
	v_exp_f32_e32 v55, v55
	v_exp_f32_e32 v50, v50
	v_exp_f32_e32 v51, v51
	v_exp_f32_e32 v44, v44
	v_exp_f32_e32 v45, v45
	v_exp_f32_e32 v46, v46
	v_exp_f32_e32 v47, v47
	v_exp_f32_e32 v42, v42
	v_exp_f32_e32 v43, v43
	v_add_f32_e32 v46, 1.0, v46
	v_add_f32_e32 v47, 1.0, v47
	v_exp_f32_e32 v38, v38
	v_exp_f32_e32 v39, v39
	v_exp_f32_e32 v34, v34
	s_waitcnt vmcnt(0)
	v_lshlrev_b32_e32 v124, 16, v112
	v_and_b32_e32 v125, 0xffff0000, v112
	v_lshlrev_b32_e32 v112, 16, v113
	v_and_b32_e32 v113, 0xffff0000, v113
	v_lshlrev_b32_e32 v126, 16, v114
	v_and_b32_e32 v127, 0xffff0000, v114
	v_lshlrev_b32_e32 v114, 16, v115
	v_and_b32_e32 v115, 0xffff0000, v115
	v_pk_mul_f32 v[104:105], v[104:105], v[124:125]
	v_pk_mul_f32 v[106:107], v[106:107], v[112:113]
	v_pk_mul_f32 v[110:111], v[110:111], v[126:127]
	v_pk_mul_f32 v[112:113], v[116:117], v[114:115]
	v_cvt_pk_bf16_f32 v104, v104, v105
	v_cvt_pk_bf16_f32 v105, v106, v107
	v_cvt_pk_bf16_f32 v106, v110, v111
	v_cvt_pk_bf16_f32 v107, v112, v113
	global_store_dwordx4 v[118:119], v[104:107], off
	global_load_dwordx4 v[104:107], v[122:123], off
	v_exp_f32_e32 v110, v100
	v_exp_f32_e32 v111, v101
	v_exp_f32_e32 v112, v96
	v_exp_f32_e32 v113, v97
	v_or_b32_e32 v96, 32, v148
	v_ashrrev_i32_e32 v97, 31, v96
	v_lshlrev_b64 v[100:101], 10, v[96:97]
	v_lshl_add_u64 v[96:97], v[100:101], 0, v[144:145]
	v_add_f32_e32 v110, 1.0, v110
	v_add_f32_e32 v111, 1.0, v111
	v_add_f32_e32 v114, 1.0, v102
	v_add_f32_e32 v115, 1.0, v103
	v_add_f32_e32 v112, 1.0, v112
	v_add_f32_e32 v113, 1.0, v113
	v_add_f32_e32 v116, 1.0, v98
	v_add_f32_e32 v117, 1.0, v99
	v_lshlrev_b64 v[102:103], 1, v[96:97]
	v_rcp_f32_e32 v96, v110
	v_rcp_f32_e32 v97, v111
	v_rcp_f32_e32 v98, v114
	v_rcp_f32_e32 v99, v115
	v_rcp_f32_e32 v110, v112
	v_rcp_f32_e32 v111, v113
	v_rcp_f32_e32 v112, v116
	v_rcp_f32_e32 v113, v117
	v_lshl_add_u64 v[114:115], s[36:37], 0, v[102:103]
	v_lshl_add_u64 v[102:103], s[40:41], 0, v[102:103]
	v_exp_f32_e32 v35, v35
	v_exp_f32_e32 v28, v28
	v_exp_f32_e32 v29, v29
	v_exp_f32_e32 v30, v30
	v_exp_f32_e32 v31, v31
	v_exp_f32_e32 v26, v26
	v_exp_f32_e32 v27, v27
	v_add_f32_e32 v30, 1.0, v30
	v_add_f32_e32 v31, 1.0, v31
	v_exp_f32_e32 v22, v22
	v_exp_f32_e32 v23, v23
	v_exp_f32_e32 v18, v18
	v_exp_f32_e32 v19, v19
	v_exp_f32_e32 v12, v12
	v_exp_f32_e32 v13, v13
	v_exp_f32_e32 v14, v14
	v_exp_f32_e32 v15, v15
	v_exp_f32_e32 v10, v10
	v_exp_f32_e32 v11, v11
	v_add_f32_e32 v14, 1.0, v14
	v_add_f32_e32 v15, 1.0, v15
	s_waitcnt vmcnt(0)
	v_lshlrev_b32_e32 v116, 16, v104
	v_and_b32_e32 v117, 0xffff0000, v104
	v_lshlrev_b32_e32 v104, 16, v105
	v_and_b32_e32 v105, 0xffff0000, v105
	v_lshlrev_b32_e32 v118, 16, v106
	v_and_b32_e32 v119, 0xffff0000, v106
	v_lshlrev_b32_e32 v106, 16, v107
	v_and_b32_e32 v107, 0xffff0000, v107
	v_pk_mul_f32 v[96:97], v[96:97], v[116:117]
	v_pk_mul_f32 v[98:99], v[98:99], v[104:105]
	v_pk_mul_f32 v[104:105], v[110:111], v[118:119]
	v_pk_mul_f32 v[106:107], v[112:113], v[106:107]
	v_cvt_pk_bf16_f32 v96, v96, v97
	v_cvt_pk_bf16_f32 v97, v98, v99
	v_cvt_pk_bf16_f32 v98, v104, v105
	v_cvt_pk_bf16_f32 v99, v106, v107
	global_store_dwordx4 v[108:109], v[96:99], off
	global_load_dwordx4 v[96:99], v[114:115], off
	v_exp_f32_e32 v104, v88
	v_exp_f32_e32 v105, v89
	v_lshl_add_u64 v[88:89], v[100:101], 0, v[120:121]
	v_add_f32_e32 v100, 1.0, v92
	v_add_f32_e32 v101, 1.0, v93
	v_add_f32_e32 v104, 1.0, v104
	v_add_f32_e32 v105, 1.0, v105
	v_add_f32_e32 v106, 1.0, v90
	v_add_f32_e32 v107, 1.0, v91
	v_lshlrev_b64 v[92:93], 1, v[88:89]
	v_rcp_f32_e32 v88, v100
	v_rcp_f32_e32 v89, v101
	v_rcp_f32_e32 v90, v94
	v_rcp_f32_e32 v91, v95
	v_rcp_f32_e32 v94, v104
	v_rcp_f32_e32 v95, v105
	v_rcp_f32_e32 v100, v106
	v_rcp_f32_e32 v101, v107
	v_lshl_add_u64 v[104:105], s[36:37], 0, v[92:93]
	v_lshl_add_u64 v[92:93], s[40:41], 0, v[92:93]
	v_exp_f32_e32 v4, v4
	v_exp_f32_e32 v5, v5
	v_exp_f32_e32 v6, v6
	v_exp_f32_e32 v7, v7
	v_exp_f32_e32 v0, v0
	v_exp_f32_e32 v1, v1
	v_exp_f32_e32 v2, v2
	v_exp_f32_e32 v3, v3
	v_add_f32_e32 v4, 1.0, v4
	v_add_f32_e32 v5, 1.0, v5
	v_add_f32_e32 v6, 1.0, v6
	v_add_f32_e32 v7, 1.0, v7
	s_andn2_b64 vcc, exec, s[2:3]
	s_mov_b64 s[0:1], -1
	s_waitcnt vmcnt(0)
	v_lshlrev_b32_e32 v106, 16, v96
	v_and_b32_e32 v107, 0xffff0000, v96
	v_lshlrev_b32_e32 v96, 16, v97
	v_and_b32_e32 v97, 0xffff0000, v97
	v_lshlrev_b32_e32 v108, 16, v98
	v_and_b32_e32 v109, 0xffff0000, v98
	v_lshlrev_b32_e32 v98, 16, v99
	v_and_b32_e32 v99, 0xffff0000, v99
	v_pk_mul_f32 v[88:89], v[88:89], v[106:107]
	v_pk_mul_f32 v[90:91], v[90:91], v[96:97]
	v_pk_mul_f32 v[94:95], v[94:95], v[108:109]
	v_pk_mul_f32 v[96:97], v[100:101], v[98:99]
	v_cvt_pk_bf16_f32 v88, v88, v89
	v_cvt_pk_bf16_f32 v89, v90, v91
	v_cvt_pk_bf16_f32 v90, v94, v95
	v_cvt_pk_bf16_f32 v91, v96, v97
	global_store_dwordx4 v[102:103], v[88:91], off
	global_load_dwordx4 v[88:91], v[104:105], off
	v_exp_f32_e32 v94, v84
	v_exp_f32_e32 v95, v85
	v_exp_f32_e32 v96, v80
	v_exp_f32_e32 v97, v81
	v_or_b32_e32 v80, 48, v148
	v_ashrrev_i32_e32 v81, 31, v80
	v_lshlrev_b64 v[84:85], 10, v[80:81]
	v_lshl_add_u64 v[80:81], v[84:85], 0, v[144:145]
	v_add_f32_e32 v94, 1.0, v94
	v_add_f32_e32 v95, 1.0, v95
	v_add_f32_e32 v98, 1.0, v86
	v_add_f32_e32 v99, 1.0, v87
	v_add_f32_e32 v96, 1.0, v96
	v_add_f32_e32 v97, 1.0, v97
	v_add_f32_e32 v100, 1.0, v82
	v_add_f32_e32 v101, 1.0, v83
	v_lshlrev_b64 v[86:87], 1, v[80:81]
	v_rcp_f32_e32 v80, v94
	v_rcp_f32_e32 v81, v95
	v_rcp_f32_e32 v82, v98
	v_rcp_f32_e32 v83, v99
	v_rcp_f32_e32 v94, v96
	v_rcp_f32_e32 v95, v97
	v_rcp_f32_e32 v96, v100
	v_rcp_f32_e32 v97, v101
	v_lshl_add_u64 v[98:99], s[36:37], 0, v[86:87]
	v_lshl_add_u64 v[86:87], s[40:41], 0, v[86:87]
	s_waitcnt vmcnt(0)
	v_lshlrev_b32_e32 v100, 16, v88
	v_and_b32_e32 v101, 0xffff0000, v88
	v_lshlrev_b32_e32 v88, 16, v89
	v_and_b32_e32 v89, 0xffff0000, v89
	v_lshlrev_b32_e32 v102, 16, v90
	v_and_b32_e32 v103, 0xffff0000, v90
	v_lshlrev_b32_e32 v90, 16, v91
	v_and_b32_e32 v91, 0xffff0000, v91
	v_pk_mul_f32 v[80:81], v[80:81], v[100:101]
	v_pk_mul_f32 v[82:83], v[82:83], v[88:89]
	v_pk_mul_f32 v[88:89], v[94:95], v[102:103]
	v_pk_mul_f32 v[90:91], v[96:97], v[90:91]
	v_cvt_pk_bf16_f32 v80, v80, v81
	v_cvt_pk_bf16_f32 v81, v82, v83
	v_cvt_pk_bf16_f32 v82, v88, v89
	v_cvt_pk_bf16_f32 v83, v90, v91
	global_store_dwordx4 v[92:93], v[80:83], off
	global_load_dwordx4 v[80:83], v[98:99], off
	v_exp_f32_e32 v88, v72
	v_exp_f32_e32 v89, v73
	v_lshl_add_u64 v[72:73], v[84:85], 0, v[120:121]
	v_add_f32_e32 v84, 1.0, v76
	v_add_f32_e32 v85, 1.0, v77
	v_add_f32_e32 v88, 1.0, v88
	v_add_f32_e32 v89, 1.0, v89
	v_add_f32_e32 v90, 1.0, v74
	v_add_f32_e32 v91, 1.0, v75
	v_lshlrev_b64 v[76:77], 1, v[72:73]
	v_rcp_f32_e32 v72, v84
	v_rcp_f32_e32 v73, v85
	v_rcp_f32_e32 v74, v78
	v_rcp_f32_e32 v75, v79
	v_rcp_f32_e32 v78, v88
	v_rcp_f32_e32 v79, v89
	v_rcp_f32_e32 v84, v90
	v_rcp_f32_e32 v85, v91
	v_lshl_add_u64 v[88:89], s[36:37], 0, v[76:77]
	v_lshl_add_u64 v[76:77], s[40:41], 0, v[76:77]
	s_waitcnt vmcnt(0)
	v_lshlrev_b32_e32 v90, 16, v80
	v_and_b32_e32 v91, 0xffff0000, v80
	v_lshlrev_b32_e32 v80, 16, v81
	v_and_b32_e32 v81, 0xffff0000, v81
	v_lshlrev_b32_e32 v92, 16, v82
	v_and_b32_e32 v93, 0xffff0000, v82
	v_lshlrev_b32_e32 v82, 16, v83
	v_and_b32_e32 v83, 0xffff0000, v83
	v_pk_mul_f32 v[72:73], v[72:73], v[90:91]
	v_pk_mul_f32 v[74:75], v[74:75], v[80:81]
	v_pk_mul_f32 v[78:79], v[78:79], v[92:93]
	v_pk_mul_f32 v[80:81], v[84:85], v[82:83]
	v_cvt_pk_bf16_f32 v72, v72, v73
	v_cvt_pk_bf16_f32 v73, v74, v75
	v_cvt_pk_bf16_f32 v74, v78, v79
	v_cvt_pk_bf16_f32 v75, v80, v81
	global_store_dwordx4 v[86:87], v[72:75], off
	global_load_dwordx4 v[72:75], v[88:89], off
	v_exp_f32_e32 v78, v68
	v_exp_f32_e32 v79, v69
	v_exp_f32_e32 v80, v64
	v_exp_f32_e32 v81, v65
	v_lshl_add_u64 v[68:69], v[146:147], 0, s[10:11]
	v_lshl_add_u64 v[64:65], v[68:69], 0, v[144:145]
	v_add_f32_e32 v78, 1.0, v78
	v_add_f32_e32 v79, 1.0, v79
	v_add_f32_e32 v82, 1.0, v70
	v_add_f32_e32 v83, 1.0, v71
	v_add_f32_e32 v80, 1.0, v80
	v_add_f32_e32 v81, 1.0, v81
	v_add_f32_e32 v84, 1.0, v66
	v_add_f32_e32 v85, 1.0, v67
	v_lshlrev_b64 v[70:71], 1, v[64:65]
	v_rcp_f32_e32 v64, v78
	v_rcp_f32_e32 v65, v79
	v_rcp_f32_e32 v66, v82
	v_rcp_f32_e32 v67, v83
	v_rcp_f32_e32 v78, v80
	v_rcp_f32_e32 v79, v81
	v_rcp_f32_e32 v80, v84
	v_rcp_f32_e32 v81, v85
	v_lshl_add_u64 v[82:83], s[36:37], 0, v[70:71]
	v_lshl_add_u64 v[70:71], s[40:41], 0, v[70:71]
	s_waitcnt vmcnt(0)
	v_lshlrev_b32_e32 v84, 16, v72
	v_and_b32_e32 v85, 0xffff0000, v72
	v_lshlrev_b32_e32 v72, 16, v73
	v_and_b32_e32 v73, 0xffff0000, v73
	v_lshlrev_b32_e32 v86, 16, v74
	v_and_b32_e32 v87, 0xffff0000, v74
	v_lshlrev_b32_e32 v74, 16, v75
	v_and_b32_e32 v75, 0xffff0000, v75
	v_pk_mul_f32 v[64:65], v[64:65], v[84:85]
	v_pk_mul_f32 v[66:67], v[66:67], v[72:73]
	v_pk_mul_f32 v[72:73], v[78:79], v[86:87]
	v_pk_mul_f32 v[74:75], v[80:81], v[74:75]
	v_cvt_pk_bf16_f32 v64, v64, v65
	v_cvt_pk_bf16_f32 v65, v66, v67
	v_cvt_pk_bf16_f32 v66, v72, v73
	v_cvt_pk_bf16_f32 v67, v74, v75
	global_store_dwordx4 v[76:77], v[64:67], off
	global_load_dwordx4 v[64:67], v[82:83], off
	v_exp_f32_e32 v72, v56
	v_exp_f32_e32 v73, v57
	v_lshl_add_u64 v[56:57], v[68:69], 0, v[120:121]
	v_add_f32_e32 v68, 1.0, v60
	v_add_f32_e32 v69, 1.0, v61
	v_add_f32_e32 v72, 1.0, v72
	v_add_f32_e32 v73, 1.0, v73
	v_add_f32_e32 v74, 1.0, v58
	v_add_f32_e32 v75, 1.0, v59
	v_lshlrev_b64 v[60:61], 1, v[56:57]
	v_rcp_f32_e32 v56, v68
	v_rcp_f32_e32 v57, v69
	v_rcp_f32_e32 v58, v62
	v_rcp_f32_e32 v59, v63
	v_rcp_f32_e32 v62, v72
	v_rcp_f32_e32 v63, v73
	v_rcp_f32_e32 v68, v74
	v_rcp_f32_e32 v69, v75
	v_lshl_add_u64 v[72:73], s[36:37], 0, v[60:61]
	v_lshl_add_u64 v[60:61], s[40:41], 0, v[60:61]
	s_waitcnt vmcnt(0)
	v_lshlrev_b32_e32 v74, 16, v64
	v_and_b32_e32 v75, 0xffff0000, v64
	v_lshlrev_b32_e32 v64, 16, v65
	v_and_b32_e32 v65, 0xffff0000, v65
	v_lshlrev_b32_e32 v76, 16, v66
	v_and_b32_e32 v77, 0xffff0000, v66
	v_lshlrev_b32_e32 v66, 16, v67
	v_and_b32_e32 v67, 0xffff0000, v67
	v_pk_mul_f32 v[56:57], v[56:57], v[74:75]
	v_pk_mul_f32 v[58:59], v[58:59], v[64:65]
	v_pk_mul_f32 v[62:63], v[62:63], v[76:77]
	v_pk_mul_f32 v[64:65], v[68:69], v[66:67]
	v_cvt_pk_bf16_f32 v56, v56, v57
	v_cvt_pk_bf16_f32 v57, v58, v59
	v_cvt_pk_bf16_f32 v58, v62, v63
	v_cvt_pk_bf16_f32 v59, v64, v65
	global_store_dwordx4 v[70:71], v[56:59], off
	global_load_dwordx4 v[56:59], v[72:73], off
	v_exp_f32_e32 v62, v52
	v_exp_f32_e32 v63, v53
	v_exp_f32_e32 v64, v48
	v_exp_f32_e32 v65, v49
	v_lshl_add_u64 v[52:53], v[146:147], 0, s[12:13]
	v_lshl_add_u64 v[48:49], v[52:53], 0, v[144:145]
	v_add_f32_e32 v62, 1.0, v62
	v_add_f32_e32 v63, 1.0, v63
	v_add_f32_e32 v66, 1.0, v54
	v_add_f32_e32 v67, 1.0, v55
	v_add_f32_e32 v64, 1.0, v64
	v_add_f32_e32 v65, 1.0, v65
	v_add_f32_e32 v68, 1.0, v50
	v_add_f32_e32 v69, 1.0, v51
	v_lshlrev_b64 v[54:55], 1, v[48:49]
	v_rcp_f32_e32 v48, v62
	v_rcp_f32_e32 v49, v63
	v_rcp_f32_e32 v50, v66
	v_rcp_f32_e32 v51, v67
	v_rcp_f32_e32 v62, v64
	v_rcp_f32_e32 v63, v65
	v_rcp_f32_e32 v64, v68
	v_rcp_f32_e32 v65, v69
	v_lshl_add_u64 v[66:67], s[36:37], 0, v[54:55]
	v_lshl_add_u64 v[54:55], s[40:41], 0, v[54:55]
	s_waitcnt vmcnt(0)
	v_lshlrev_b32_e32 v68, 16, v56
	v_and_b32_e32 v69, 0xffff0000, v56
	v_lshlrev_b32_e32 v56, 16, v57
	v_and_b32_e32 v57, 0xffff0000, v57
	v_lshlrev_b32_e32 v70, 16, v58
	v_and_b32_e32 v71, 0xffff0000, v58
	v_lshlrev_b32_e32 v58, 16, v59
	v_and_b32_e32 v59, 0xffff0000, v59
	v_pk_mul_f32 v[48:49], v[48:49], v[68:69]
	v_pk_mul_f32 v[50:51], v[50:51], v[56:57]
	v_pk_mul_f32 v[56:57], v[62:63], v[70:71]
	v_pk_mul_f32 v[58:59], v[64:65], v[58:59]
	v_cvt_pk_bf16_f32 v48, v48, v49
	v_cvt_pk_bf16_f32 v49, v50, v51
	v_cvt_pk_bf16_f32 v50, v56, v57
	v_cvt_pk_bf16_f32 v51, v58, v59
	global_store_dwordx4 v[60:61], v[48:51], off
	global_load_dwordx4 v[48:51], v[66:67], off
	v_exp_f32_e32 v56, v40
	v_exp_f32_e32 v57, v41
	v_lshl_add_u64 v[40:41], v[52:53], 0, v[120:121]
	v_add_f32_e32 v52, 1.0, v44
	v_add_f32_e32 v53, 1.0, v45
	v_add_f32_e32 v56, 1.0, v56
	v_add_f32_e32 v57, 1.0, v57
	v_add_f32_e32 v58, 1.0, v42
	v_add_f32_e32 v59, 1.0, v43
	v_lshlrev_b64 v[44:45], 1, v[40:41]
	v_rcp_f32_e32 v40, v52
	v_rcp_f32_e32 v41, v53
	v_rcp_f32_e32 v42, v46
	v_rcp_f32_e32 v43, v47
	v_rcp_f32_e32 v46, v56
	v_rcp_f32_e32 v47, v57
	v_rcp_f32_e32 v52, v58
	v_rcp_f32_e32 v53, v59
	v_lshl_add_u64 v[56:57], s[36:37], 0, v[44:45]
	v_lshl_add_u64 v[44:45], s[40:41], 0, v[44:45]
	s_waitcnt vmcnt(0)
	v_lshlrev_b32_e32 v58, 16, v48
	v_and_b32_e32 v59, 0xffff0000, v48
	v_lshlrev_b32_e32 v48, 16, v49
	v_and_b32_e32 v49, 0xffff0000, v49
	v_lshlrev_b32_e32 v60, 16, v50
	v_and_b32_e32 v61, 0xffff0000, v50
	v_lshlrev_b32_e32 v50, 16, v51
	v_and_b32_e32 v51, 0xffff0000, v51
	v_pk_mul_f32 v[40:41], v[40:41], v[58:59]
	v_pk_mul_f32 v[42:43], v[42:43], v[48:49]
	v_pk_mul_f32 v[46:47], v[46:47], v[60:61]
	v_pk_mul_f32 v[48:49], v[52:53], v[50:51]
	v_cvt_pk_bf16_f32 v40, v40, v41
	v_cvt_pk_bf16_f32 v41, v42, v43
	v_cvt_pk_bf16_f32 v42, v46, v47
	v_cvt_pk_bf16_f32 v43, v48, v49
	global_store_dwordx4 v[54:55], v[40:43], off
	global_load_dwordx4 v[40:43], v[56:57], off
	v_exp_f32_e32 v46, v36
	v_exp_f32_e32 v47, v37
	v_exp_f32_e32 v48, v32
	v_exp_f32_e32 v49, v33
	v_lshl_add_u64 v[36:37], v[146:147], 0, s[14:15]
	v_lshl_add_u64 v[32:33], v[36:37], 0, v[144:145]
	v_add_f32_e32 v46, 1.0, v46
	v_add_f32_e32 v47, 1.0, v47
	v_add_f32_e32 v50, 1.0, v38
	v_add_f32_e32 v51, 1.0, v39
	v_add_f32_e32 v48, 1.0, v48
	v_add_f32_e32 v49, 1.0, v49
	v_add_f32_e32 v52, 1.0, v34
	v_add_f32_e32 v53, 1.0, v35
	v_lshlrev_b64 v[38:39], 1, v[32:33]
	v_rcp_f32_e32 v32, v46
	v_rcp_f32_e32 v33, v47
	v_rcp_f32_e32 v34, v50
	v_rcp_f32_e32 v35, v51
	v_rcp_f32_e32 v46, v48
	v_rcp_f32_e32 v47, v49
	v_rcp_f32_e32 v48, v52
	v_rcp_f32_e32 v49, v53
	v_lshl_add_u64 v[50:51], s[36:37], 0, v[38:39]
	v_lshl_add_u64 v[38:39], s[40:41], 0, v[38:39]
	s_waitcnt vmcnt(0)
	v_lshlrev_b32_e32 v52, 16, v40
	v_and_b32_e32 v53, 0xffff0000, v40
	v_lshlrev_b32_e32 v40, 16, v41
	v_and_b32_e32 v41, 0xffff0000, v41
	v_lshlrev_b32_e32 v54, 16, v42
	v_and_b32_e32 v55, 0xffff0000, v42
	v_lshlrev_b32_e32 v42, 16, v43
	v_and_b32_e32 v43, 0xffff0000, v43
	v_pk_mul_f32 v[32:33], v[32:33], v[52:53]
	v_pk_mul_f32 v[34:35], v[34:35], v[40:41]
	v_pk_mul_f32 v[40:41], v[46:47], v[54:55]
	v_pk_mul_f32 v[42:43], v[48:49], v[42:43]
	v_cvt_pk_bf16_f32 v32, v32, v33
	v_cvt_pk_bf16_f32 v33, v34, v35
	v_cvt_pk_bf16_f32 v34, v40, v41
	v_cvt_pk_bf16_f32 v35, v42, v43
	global_store_dwordx4 v[44:45], v[32:35], off
	global_load_dwordx4 v[32:35], v[50:51], off
	v_exp_f32_e32 v40, v24
	v_exp_f32_e32 v41, v25
	v_lshl_add_u64 v[24:25], v[36:37], 0, v[120:121]
	v_add_f32_e32 v36, 1.0, v28
	v_add_f32_e32 v37, 1.0, v29
	v_add_f32_e32 v40, 1.0, v40
	v_add_f32_e32 v41, 1.0, v41
	v_add_f32_e32 v42, 1.0, v26
	v_add_f32_e32 v43, 1.0, v27
	v_lshlrev_b64 v[28:29], 1, v[24:25]
	v_rcp_f32_e32 v24, v36
	v_rcp_f32_e32 v25, v37
	v_rcp_f32_e32 v26, v30
	v_rcp_f32_e32 v27, v31
	v_rcp_f32_e32 v30, v40
	v_rcp_f32_e32 v31, v41
	v_rcp_f32_e32 v36, v42
	v_rcp_f32_e32 v37, v43
	v_lshl_add_u64 v[40:41], s[36:37], 0, v[28:29]
	v_lshl_add_u64 v[28:29], s[40:41], 0, v[28:29]
	s_waitcnt vmcnt(0)
	v_lshlrev_b32_e32 v42, 16, v32
	v_and_b32_e32 v43, 0xffff0000, v32
	v_lshlrev_b32_e32 v32, 16, v33
	v_and_b32_e32 v33, 0xffff0000, v33
	v_lshlrev_b32_e32 v44, 16, v34
	v_and_b32_e32 v45, 0xffff0000, v34
	v_lshlrev_b32_e32 v34, 16, v35
	v_and_b32_e32 v35, 0xffff0000, v35
	v_pk_mul_f32 v[24:25], v[24:25], v[42:43]
	v_pk_mul_f32 v[26:27], v[26:27], v[32:33]
	v_pk_mul_f32 v[30:31], v[30:31], v[44:45]
	v_pk_mul_f32 v[32:33], v[36:37], v[34:35]
	v_cvt_pk_bf16_f32 v24, v24, v25
	v_cvt_pk_bf16_f32 v25, v26, v27
	v_cvt_pk_bf16_f32 v26, v30, v31
	v_cvt_pk_bf16_f32 v27, v32, v33
	global_store_dwordx4 v[38:39], v[24:27], off
	global_load_dwordx4 v[24:27], v[40:41], off
	v_exp_f32_e32 v30, v20
	v_exp_f32_e32 v31, v21
	v_exp_f32_e32 v32, v16
	v_exp_f32_e32 v33, v17
	v_lshl_add_u64 v[20:21], v[146:147], 0, s[16:17]
	v_lshl_add_u64 v[16:17], v[20:21], 0, v[144:145]
	v_add_f32_e32 v30, 1.0, v30
	v_add_f32_e32 v31, 1.0, v31
	v_add_f32_e32 v34, 1.0, v22
	v_add_f32_e32 v35, 1.0, v23
	v_add_f32_e32 v32, 1.0, v32
	v_add_f32_e32 v33, 1.0, v33
	v_add_f32_e32 v36, 1.0, v18
	v_add_f32_e32 v37, 1.0, v19
	v_lshlrev_b64 v[22:23], 1, v[16:17]
	v_rcp_f32_e32 v16, v30
	v_rcp_f32_e32 v17, v31
	v_rcp_f32_e32 v18, v34
	v_rcp_f32_e32 v19, v35
	v_rcp_f32_e32 v30, v32
	v_rcp_f32_e32 v31, v33
	v_rcp_f32_e32 v32, v36
	v_rcp_f32_e32 v33, v37
	v_lshl_add_u64 v[34:35], s[36:37], 0, v[22:23]
	v_lshl_add_u64 v[22:23], s[40:41], 0, v[22:23]
	s_waitcnt vmcnt(0)
	v_lshlrev_b32_e32 v36, 16, v24
	v_and_b32_e32 v37, 0xffff0000, v24
	v_lshlrev_b32_e32 v24, 16, v25
	v_and_b32_e32 v25, 0xffff0000, v25
	v_lshlrev_b32_e32 v38, 16, v26
	v_and_b32_e32 v39, 0xffff0000, v26
	v_lshlrev_b32_e32 v26, 16, v27
	v_and_b32_e32 v27, 0xffff0000, v27
	v_pk_mul_f32 v[16:17], v[16:17], v[36:37]
	v_pk_mul_f32 v[18:19], v[18:19], v[24:25]
	v_pk_mul_f32 v[24:25], v[30:31], v[38:39]
	v_pk_mul_f32 v[26:27], v[32:33], v[26:27]
	v_cvt_pk_bf16_f32 v16, v16, v17
	v_cvt_pk_bf16_f32 v17, v18, v19
	v_cvt_pk_bf16_f32 v18, v24, v25
	v_cvt_pk_bf16_f32 v19, v26, v27
	global_store_dwordx4 v[28:29], v[16:19], off
	global_load_dwordx4 v[16:19], v[34:35], off
	v_exp_f32_e32 v24, v8
	v_exp_f32_e32 v25, v9
	v_lshl_add_u64 v[8:9], v[20:21], 0, v[120:121]
	v_add_f32_e32 v20, 1.0, v12
	v_add_f32_e32 v21, 1.0, v13
	v_add_f32_e32 v24, 1.0, v24
	v_add_f32_e32 v25, 1.0, v25
	v_add_f32_e32 v26, 1.0, v10
	v_add_f32_e32 v27, 1.0, v11
	v_lshlrev_b64 v[12:13], 1, v[8:9]
	v_rcp_f32_e32 v8, v20
	v_rcp_f32_e32 v9, v21
	v_rcp_f32_e32 v10, v14
	v_rcp_f32_e32 v11, v15
	v_rcp_f32_e32 v14, v24
	v_rcp_f32_e32 v15, v25
	v_rcp_f32_e32 v20, v26
	v_rcp_f32_e32 v21, v27
	v_lshl_add_u64 v[24:25], s[36:37], 0, v[12:13]
	v_lshl_add_u64 v[12:13], s[40:41], 0, v[12:13]
	s_waitcnt vmcnt(0)
	v_lshlrev_b32_e32 v26, 16, v16
	v_and_b32_e32 v27, 0xffff0000, v16
	v_lshlrev_b32_e32 v16, 16, v17
	v_and_b32_e32 v17, 0xffff0000, v17
	v_lshlrev_b32_e32 v28, 16, v18
	v_and_b32_e32 v29, 0xffff0000, v18
	v_lshlrev_b32_e32 v18, 16, v19
	v_and_b32_e32 v19, 0xffff0000, v19
	v_pk_mul_f32 v[8:9], v[8:9], v[26:27]
	v_pk_mul_f32 v[10:11], v[10:11], v[16:17]
	v_pk_mul_f32 v[14:15], v[14:15], v[28:29]
	v_pk_mul_f32 v[16:17], v[20:21], v[18:19]
	v_cvt_pk_bf16_f32 v8, v8, v9
	v_cvt_pk_bf16_f32 v9, v10, v11
	v_cvt_pk_bf16_f32 v10, v14, v15
	v_cvt_pk_bf16_f32 v11, v16, v17
	global_store_dwordx4 v[22:23], v[8:11], off
	global_load_dwordx4 v[8:11], v[24:25], off
	v_add_f32_e32 v14, 1.0, v0
	v_add_f32_e32 v15, 1.0, v1
	v_add_f32_e32 v16, 1.0, v2
	v_add_f32_e32 v17, 1.0, v3
	v_rcp_f32_e32 v0, v4
	v_rcp_f32_e32 v1, v5
	v_rcp_f32_e32 v2, v6
	v_rcp_f32_e32 v3, v7
	v_rcp_f32_e32 v4, v14
	v_rcp_f32_e32 v5, v15
	v_rcp_f32_e32 v6, v16
	v_rcp_f32_e32 v7, v17
	s_waitcnt vmcnt(0)
	v_lshlrev_b32_e32 v14, 16, v8
	v_and_b32_e32 v15, 0xffff0000, v8
	v_lshlrev_b32_e32 v8, 16, v9
	v_and_b32_e32 v9, 0xffff0000, v9
	v_lshlrev_b32_e32 v16, 16, v10
	v_and_b32_e32 v17, 0xffff0000, v10
	v_lshlrev_b32_e32 v10, 16, v11
	v_and_b32_e32 v11, 0xffff0000, v11
	v_pk_mul_f32 v[0:1], v[0:1], v[14:15]
	v_pk_mul_f32 v[2:3], v[2:3], v[8:9]
	v_pk_mul_f32 v[4:5], v[4:5], v[16:17]
	v_pk_mul_f32 v[6:7], v[6:7], v[10:11]
	v_cvt_pk_bf16_f32 v0, v0, v1
	v_cvt_pk_bf16_f32 v1, v2, v3
	v_cvt_pk_bf16_f32 v2, v4, v5
	v_cvt_pk_bf16_f32 v3, v6, v7
	global_store_dwordx4 v[12:13], v[0:3], off
	s_cbranch_vccnz .LBB0_2490
	s_andn2_b64 vcc, exec, s[4:5]
	s_cbranch_vccnz .LBB0_2489
	s_barrier
	s_branch .LBB0_2489
